# instruction selection: 191 six-instruction f32->bf16 round-to-nearest-even packs (bfe/add3/lshr/and_or) replaced by v_cvt_pk_bf16_f32 in the thin phases; on top of norm-loop consolidation
# speedup vs baseline: 1.0044x; 1.0044x over previous
; #define LAS __attribute__((address_space(3)))
; template <bool F8>
; __device__ __forceinline__ void transpose_item(const float* W, int ldw, int k0, int srccol0, bf16* WT, int ldt, int dstrow0, LAS float* scr, int lane) {
;     float wv[32];
; #pragma unroll
;     for (int i = 0; i < 32; ++i) wv[i] = W[(size_t)(k0 + 2 * i + (lane >> 5)) * ldw + srccol0 + (lane & 31)];
; #pragma unroll
;     for (int i = 0; i < 32; ++i) scr[(2 * i + (lane >> 5)) * 33 + (lane & 31)] = wv[i];
.LBB0_58:
	s_lshl_b32 s26, s29, 6
	v_or_b32_e32 v5, s26, v1
	s_ashr_i32 s29, s28, 31
	s_ashr_i32 s27, s26, 31
	v_lshl_add_u64 v[10:11], s[28:29], 2, v[6:7]
	s_mul_i32 s28, s24, s27
	v_mul_lo_u32 v25, s25, v5
	v_mad_u64_u32 v[26:27], s[40:41], s24, v5, 0
	v_add3_u32 v27, v27, s28, v25
	v_or_b32_e32 v25, 2, v5
	v_mul_lo_u32 v30, s25, v25
	v_mad_u64_u32 v[28:29], s[40:41], s24, v25, 0
	v_or_b32_e32 v25, 4, v5
	v_add3_u32 v29, v29, s28, v30
	v_mul_lo_u32 v32, s25, v25
	v_mad_u64_u32 v[30:31], s[40:41], s24, v25, 0
	v_or_b32_e32 v25, 6, v5
	v_add3_u32 v31, v31, s28, v32
	v_mul_lo_u32 v34, s25, v25
	v_mad_u64_u32 v[32:33], s[40:41], s24, v25, 0
	v_or_b32_e32 v25, 8, v5
	v_add3_u32 v33, v33, s28, v34
	v_mul_lo_u32 v36, s25, v25
	v_mad_u64_u32 v[34:35], s[40:41], s24, v25, 0
	v_or_b32_e32 v25, 10, v5
	v_add3_u32 v35, v35, s28, v36
	v_mul_lo_u32 v39, s25, v25
	v_mad_u64_u32 v[36:37], s[40:41], s24, v25, 0
	v_or_b32_e32 v25, 12, v5
	v_add3_u32 v37, v37, s28, v39
	v_mul_lo_u32 v39, s25, v25
	v_mad_u64_u32 v[40:41], s[40:41], s24, v25, 0
	v_or_b32_e32 v25, 14, v5
	v_add3_u32 v41, v41, s28, v39
	v_mul_lo_u32 v39, s25, v25
	v_mad_u64_u32 v[42:43], s[40:41], s24, v25, 0
	v_lshl_add_u64 v[26:27], v[26:27], 2, v[10:11]
	v_add3_u32 v43, v43, s28, v39
	v_lshl_add_u64 v[28:29], v[28:29], 2, v[10:11]
	v_lshl_add_u64 v[30:31], v[30:31], 2, v[10:11]
	v_lshl_add_u64 v[32:33], v[32:33], 2, v[10:11]
	v_lshl_add_u64 v[34:35], v[34:35], 2, v[10:11]
	v_lshl_add_u64 v[36:37], v[36:37], 2, v[10:11]
	v_lshl_add_u64 v[40:41], v[40:41], 2, v[10:11]
	v_lshl_add_u64 v[42:43], v[42:43], 2, v[10:11]
	global_load_dword v25, v[26:27], off
	global_load_dword v39, v[28:29], off
	global_load_dword v44, v[30:31], off
	global_load_dword v45, v[32:33], off
	global_load_dword v46, v[34:35], off
	global_load_dword v47, v[36:37], off
	global_load_dword v48, v[40:41], off
	global_load_dword v49, v[42:43], off
	v_or_b32_e32 v26, 16, v5
	v_mul_lo_u32 v28, s25, v26
	v_mad_u64_u32 v[26:27], s[40:41], s24, v26, 0
	v_add3_u32 v27, v27, s28, v28
	v_or_b32_e32 v28, 18, v5
	v_mul_lo_u32 v30, s25, v28
	v_mad_u64_u32 v[28:29], s[40:41], s24, v28, 0
	v_add3_u32 v29, v29, s28, v30
	v_or_b32_e32 v30, 20, v5
	v_mul_lo_u32 v32, s25, v30
	v_mad_u64_u32 v[30:31], s[40:41], s24, v30, 0
	v_add3_u32 v31, v31, s28, v32
	v_or_b32_e32 v32, 22, v5
	v_mul_lo_u32 v34, s25, v32
	v_mad_u64_u32 v[32:33], s[40:41], s24, v32, 0
	v_add3_u32 v33, v33, s28, v34
	v_or_b32_e32 v34, 24, v5
	v_mul_lo_u32 v36, s25, v34
	v_mad_u64_u32 v[34:35], s[40:41], s24, v34, 0
	v_add3_u32 v35, v35, s28, v36
	v_or_b32_e32 v36, 26, v5
	v_mul_lo_u32 v40, s25, v36
	v_mad_u64_u32 v[36:37], s[40:41], s24, v36, 0
	v_add3_u32 v37, v37, s28, v40
	v_or_b32_e32 v40, 28, v5
	v_mul_lo_u32 v42, s25, v40
	v_mad_u64_u32 v[40:41], s[40:41], s24, v40, 0
	v_add3_u32 v41, v41, s28, v42
	v_or_b32_e32 v42, 30, v5
	v_mul_lo_u32 v50, s25, v42
	v_mad_u64_u32 v[42:43], s[40:41], s24, v42, 0
	v_lshl_add_u64 v[26:27], v[26:27], 2, v[10:11]
	v_add3_u32 v43, v43, s28, v50
	v_lshl_add_u64 v[28:29], v[28:29], 2, v[10:11]
	v_lshl_add_u64 v[30:31], v[30:31], 2, v[10:11]
	v_lshl_add_u64 v[32:33], v[32:33], 2, v[10:11]
	v_lshl_add_u64 v[34:35], v[34:35], 2, v[10:11]
	v_lshl_add_u64 v[36:37], v[36:37], 2, v[10:11]
	v_lshl_add_u64 v[40:41], v[40:41], 2, v[10:11]
	v_lshl_add_u64 v[42:43], v[42:43], 2, v[10:11]
	global_load_dword v50, v[26:27], off
	global_load_dword v51, v[28:29], off
	global_load_dword v52, v[30:31], off
	global_load_dword v53, v[32:33], off
	global_load_dword v54, v[34:35], off
	global_load_dword v55, v[36:37], off
	global_load_dword v56, v[40:41], off
	global_load_dword v57, v[42:43], off
	v_or_b32_e32 v26, 32, v5
	v_mul_lo_u32 v28, s25, v26
	v_mad_u64_u32 v[26:27], s[40:41], s24, v26, 0
	v_add3_u32 v27, v27, s28, v28
	v_or_b32_e32 v28, 34, v5
	v_mul_lo_u32 v30, s25, v28
	v_mad_u64_u32 v[28:29], s[40:41], s24, v28, 0
	v_add3_u32 v29, v29, s28, v30
	v_or_b32_e32 v30, 36, v5
	v_mul_lo_u32 v32, s25, v30
	v_mad_u64_u32 v[30:31], s[40:41], s24, v30, 0
	v_add3_u32 v31, v31, s28, v32
	v_or_b32_e32 v32, 38, v5
	v_mul_lo_u32 v34, s25, v32
	v_mad_u64_u32 v[32:33], s[40:41], s24, v32, 0
	v_add3_u32 v33, v33, s28, v34
	v_or_b32_e32 v34, 40, v5
	v_mul_lo_u32 v36, s25, v34
	v_mad_u64_u32 v[34:35], s[40:41], s24, v34, 0
	v_add3_u32 v35, v35, s28, v36
	v_or_b32_e32 v36, 42, v5
	v_mul_lo_u32 v40, s25, v36
	v_mad_u64_u32 v[36:37], s[40:41], s24, v36, 0
	v_add3_u32 v37, v37, s28, v40
	v_or_b32_e32 v40, 44, v5
	v_mul_lo_u32 v42, s25, v40
	v_mad_u64_u32 v[40:41], s[40:41], s24, v40, 0
	v_add3_u32 v41, v41, s28, v42
	v_or_b32_e32 v42, 46, v5
	v_mul_lo_u32 v58, s25, v42
	v_mad_u64_u32 v[42:43], s[40:41], s24, v42, 0
	v_lshl_add_u64 v[26:27], v[26:27], 2, v[10:11]
	v_add3_u32 v43, v43, s28, v58
	v_lshl_add_u64 v[28:29], v[28:29], 2, v[10:11]
	v_lshl_add_u64 v[30:31], v[30:31], 2, v[10:11]
	v_lshl_add_u64 v[32:33], v[32:33], 2, v[10:11]
	v_lshl_add_u64 v[34:35], v[34:35], 2, v[10:11]
	v_lshl_add_u64 v[36:37], v[36:37], 2, v[10:11]
	v_lshl_add_u64 v[40:41], v[40:41], 2, v[10:11]
	v_lshl_add_u64 v[42:43], v[42:43], 2, v[10:11]
	global_load_dword v58, v[26:27], off
	global_load_dword v59, v[28:29], off
	global_load_dword v60, v[30:31], off
	global_load_dword v61, v[32:33], off
	global_load_dword v62, v[34:35], off
	global_load_dword v63, v[36:37], off
	global_load_dword v64, v[40:41], off
	global_load_dword v65, v[42:43], off
	v_or_b32_e32 v26, 48, v5
	v_mul_lo_u32 v28, s25, v26
	v_mad_u64_u32 v[26:27], s[40:41], s24, v26, 0
	v_add3_u32 v27, v27, s28, v28
	v_or_b32_e32 v28, 50, v5
	v_mul_lo_u32 v30, s25, v28
	v_mad_u64_u32 v[28:29], s[40:41], s24, v28, 0
	v_add3_u32 v29, v29, s28, v30
; #define LAS __attribute__((address_space(3)))
; #define LDS_WAIT() asm volatile("s_waitcnt lgkmcnt(0)" ::: "memory")
; __device__ __forceinline__ unsigned pk2(float lo, float hi) { return f2bf(lo) | (f2bf(hi) << 16); }
; template <bool F8>
; __device__ __forceinline__ void transpose_item(const float* W, int ldw, int k0, int srccol0, bf16* WT, int ldt, int dstrow0, LAS float* scr, int lane) {
;     ...
;     for (int i = 0; i < 32; ++i) wv[i] = W[(size_t)(k0 + 2 * i + (lane >> 5)) * ldw + srccol0 + (lane & 31)];
; #pragma unroll
;     for (int i = 0; i < 32; ++i) scr[(2 * i + (lane >> 5)) * 33 + (lane & 31)] = wv[i];
;     LDS_WAIT(); asm volatile("" ::: "memory");
;     const int c = lane & 7;
; #pragma unroll
;     for (int j = 0; j < 4; ++j) { const int n = (lane >> 3) + 8 * j; const LAS float* s = scr + (8 * c) * 33 + n;
;         if constexpr (F8) { *(v2u*)((unsigned char*)WT + (size_t)(dstrow0 + n) * ldt + k0 + 8 * c) = pack8_fp8(s[0 * 33], s[1 * 33], s[2 * 33], s[3 * 33], s[4 * 33], s[5 * 33], s[6 * 33], s[7 * 33], FP8_WSCALE); }
;         else { v4u o; o.x = pk2(s[0 * 33], s[1 * 33]); o.y = pk2(s[2 * 33], s[3 * 33]); o.z = pk2(s[4 * 33], s[5 * 33]); o.w = pk2(s[6 * 33], s[7 * 33]);
;             *(v4u*)(WT + (size_t)(dstrow0 + n) * ldt + k0 + 8 * c) = o; } }
	v_or_b32_e32 v30, 52, v5
	v_mul_lo_u32 v32, s25, v30
	v_mad_u64_u32 v[30:31], s[40:41], s24, v30, 0
	v_add3_u32 v31, v31, s28, v32
	v_or_b32_e32 v32, 54, v5
	v_mul_lo_u32 v34, s25, v32
	v_mad_u64_u32 v[32:33], s[40:41], s24, v32, 0
	v_add3_u32 v33, v33, s28, v34
	v_or_b32_e32 v34, 56, v5
	v_mul_lo_u32 v36, s25, v34
	v_mad_u64_u32 v[34:35], s[40:41], s24, v34, 0
	v_add3_u32 v35, v35, s28, v36
	v_or_b32_e32 v36, 58, v5
	v_mul_lo_u32 v40, s25, v36
	v_mad_u64_u32 v[36:37], s[40:41], s24, v36, 0
	v_add3_u32 v37, v37, s28, v40
	v_or_b32_e32 v40, 60, v5
	v_mul_lo_u32 v42, s25, v40
	v_mad_u64_u32 v[40:41], s[40:41], s24, v40, 0
	v_or_b32_e32 v5, 62, v5
	v_add3_u32 v41, v41, s28, v42
	v_mul_lo_u32 v66, s25, v5
	v_mad_u64_u32 v[42:43], s[40:41], s24, v5, 0
	v_add3_u32 v43, v43, s28, v66
	v_lshl_add_u64 v[26:27], v[26:27], 2, v[10:11]
	v_lshl_add_u64 v[28:29], v[28:29], 2, v[10:11]
	v_lshl_add_u64 v[30:31], v[30:31], 2, v[10:11]
	v_lshl_add_u64 v[32:33], v[32:33], 2, v[10:11]
	v_lshl_add_u64 v[34:35], v[34:35], 2, v[10:11]
	v_lshl_add_u64 v[36:37], v[36:37], 2, v[10:11]
	v_lshl_add_u64 v[40:41], v[40:41], 2, v[10:11]
	v_lshl_add_u64 v[10:11], v[42:43], 2, v[10:11]
	global_load_dword v5, v[26:27], off
	s_nop 0
	global_load_dword v26, v[28:29], off
	global_load_dword v27, v[30:31], off
	s_nop 0
	global_load_dword v28, v[32:33], off
	global_load_dword v29, v[34:35], off
	global_load_dword v30, v[36:37], off
	global_load_dword v31, v[40:41], off
	s_nop 0
	global_load_dword v10, v[10:11], off
	s_waitcnt vmcnt(30)
	ds_write2_b32 v17, v25, v39 offset1:66
	s_waitcnt vmcnt(28)
	ds_write2_b32 v17, v44, v45 offset0:132 offset1:198
	s_waitcnt vmcnt(26)
	ds_write2_b32 v18, v46, v47 offset0:8 offset1:74
	s_waitcnt vmcnt(24)
	ds_write2_b32 v18, v48, v49 offset0:140 offset1:206
	s_waitcnt vmcnt(22)
	ds_write2_b32 v19, v50, v51 offset0:16 offset1:82
	s_waitcnt vmcnt(20)
	ds_write2_b32 v19, v52, v53 offset0:148 offset1:214
	s_waitcnt vmcnt(18)
	ds_write2_b32 v20, v54, v55 offset0:24 offset1:90
	s_waitcnt vmcnt(16)
	ds_write2_b32 v20, v56, v57 offset0:156 offset1:222
	s_waitcnt vmcnt(14)
	ds_write2_b32 v21, v58, v59 offset0:32 offset1:98
	s_waitcnt vmcnt(12)
	ds_write2_b32 v21, v60, v61 offset0:164 offset1:230
	s_waitcnt vmcnt(10)
	ds_write2_b32 v22, v62, v63 offset0:40 offset1:106
	s_waitcnt vmcnt(8)
	ds_write2_b32 v22, v64, v65 offset0:172 offset1:238
	s_waitcnt vmcnt(6)
	ds_write2_b32 v23, v5, v26 offset0:48 offset1:114
	s_waitcnt vmcnt(4)
	ds_write2_b32 v23, v27, v28 offset0:180 offset1:246
	s_waitcnt vmcnt(2)
	ds_write2_b32 v24, v29, v30 offset0:56 offset1:122
	s_waitcnt vmcnt(0)
	ds_write2_b32 v24, v31, v10 offset0:188 offset1:254
	s_waitcnt lgkmcnt(0)
	ds_read2_b32 v[10:11], v13 offset1:8
	ds_read2_b32 v[32:33], v13 offset0:33 offset1:41
	ds_read2_b32 v[34:35], v13 offset0:66 offset1:74
	ds_read2_b32 v[36:37], v13 offset0:99 offset1:107
	ds_read2_b32 v[40:41], v13 offset0:132 offset1:140
	s_waitcnt lgkmcnt(4)
	v_bfe_u32 v5, v10, 16, 1
	v_add3_u32 v5, v10, v5, s47
	s_waitcnt lgkmcnt(3)
	v_bfe_u32 v10, v32, 16, 1
	v_lshrrev_b32_e32 v5, 16, v5
	v_add3_u32 v10, v32, v10, s47
	ds_read2_b32 v[42:43], v13 offset0:165 offset1:173
	v_and_or_b32 v26, v10, s52, v5
	s_waitcnt lgkmcnt(3)
	s_waitcnt lgkmcnt(2)
	ds_read2_b32 v[44:45], v13 offset0:198 offset1:206
	ds_read2_b32 v[46:47], v13 offset0:231 offset1:239
	v_cvt_pk_bf16_f32 v27, v34, v36
	s_waitcnt lgkmcnt(3)
	s_waitcnt lgkmcnt(2)
	v_cvt_pk_bf16_f32 v28, v40, v42
	s_waitcnt lgkmcnt(1)
	s_waitcnt lgkmcnt(0)
	v_cvt_pk_bf16_f32 v29, v44, v46
	v_or_b32_e32 v5, s60, v12
	s_ashr_i32 s0, s60, 31
	v_lshl_add_u64 v[30:31], s[26:27], 1, v[8:9]
	s_mul_i32 s0, s0, s4
	v_mad_u64_u32 v[48:49], s[26:27], v5, s4, 0
	v_bfe_u32 v5, v11, 16, 1
	v_add_u32_e32 v49, s0, v49
	v_add3_u32 v5, v11, v5, s47
	v_bfe_u32 v10, v33, 16, 1
	v_lshl_add_u64 v[48:49], v[48:49], 1, v[30:31]
	v_lshrrev_b32_e32 v5, 16, v5
	v_add3_u32 v10, v33, v10, s47
	global_store_dwordx4 v[48:49], v[26:29], off
	ds_read2_b32 v[32:33], v13 offset0:16 offset1:24
	s_add_i32 s31, s31, s34
	v_and_or_b32 v26, v10, s52, v5
	v_cvt_pk_bf16_f32 v27, v35, v37
	v_cvt_pk_bf16_f32 v28, v41, v43
	v_cvt_pk_bf16_f32 v29, v45, v47
	v_or_b32_e32 v5, s60, v14
	v_mad_u64_u32 v[10:11], s[26:27], v5, s4, 0
	v_add_u32_e32 v11, s0, v11
	v_lshl_add_u64 v[10:11], v[10:11], 1, v[30:31]
	global_store_dwordx4 v[10:11], v[26:29], off
	ds_read2_b32 v[10:11], v13 offset0:49 offset1:57
	ds_read2_b32 v[34:35], v13 offset0:82 offset1:90
	ds_read2_b32 v[36:37], v13 offset0:115 offset1:123
	s_waitcnt lgkmcnt(3)
	v_bfe_u32 v5, v32, 16, 1
	v_add3_u32 v5, v32, v5, s47
	s_waitcnt lgkmcnt(2)
	v_bfe_u32 v25, v10, 16, 1
	ds_read2_b32 v[40:41], v13 offset0:148 offset1:156
	v_lshrrev_b32_e32 v5, 16, v5
	v_add3_u32 v10, v10, v25, s47
	ds_read2_b32 v[42:43], v13 offset0:181 offset1:189
	v_and_or_b32 v26, v10, s52, v5
	s_waitcnt lgkmcnt(3)
	s_waitcnt lgkmcnt(2)
	ds_read2_b32 v[44:45], v13 offset0:214 offset1:222
	ds_read2_b32 v[46:47], v13 offset0:247 offset1:255
	v_cvt_pk_bf16_f32 v27, v34, v36
	s_waitcnt lgkmcnt(3)
	s_waitcnt lgkmcnt(2)
	v_cvt_pk_bf16_f32 v28, v40, v42
	s_waitcnt lgkmcnt(1)
	s_waitcnt lgkmcnt(0)
	v_cvt_pk_bf16_f32 v29, v44, v46
	v_or_b32_e32 v5, s60, v15
	v_mad_u64_u32 v[48:49], s[26:27], v5, s4, 0
	v_add_u32_e32 v49, s0, v49
	v_lshl_add_u64 v[48:49], v[48:49], 1, v[30:31]
	global_store_dwordx4 v[48:49], v[26:29], off
	s_nop 1
	v_cvt_pk_bf16_f32 v26, v33, v11
	v_cvt_pk_bf16_f32 v27, v35, v37
	v_cvt_pk_bf16_f32 v28, v41, v43
	v_cvt_pk_bf16_f32 v29, v45, v47
	v_or_b32_e32 v5, s60, v16
	v_mad_u64_u32 v[10:11], s[26:27], v5, s4, 0
	v_add_u32_e32 v11, s0, v11
	v_lshl_add_u64 v[10:11], v[10:11], 1, v[30:31]
	global_store_dwordx4 v[10:11], v[26:29], off
	s_waitcnt lgkmcnt(0)
	s_add_i32 s0, s54, s31
	s_cmp_lt_i32 s0, s30
	s_cbranch_scc0 .LBB0_24

; __device__ __forceinline__ void unpack8(const v4u& w, float (&f)[8]) { f[0] = bflo(w.x); f[1] = bfhi(w.x); f[2] = bflo(w.y); f[3] = bfhi(w.y); f[4] = bflo(w.z); f[5] = bfhi(w.z); f[6] = bflo(w.w); f[7] = bfhi(w.w); }
; template <bool ZP, bool XF32, bool OUT8 = false>
; __device__ __forceinline__ void norm_phase(LAS unsigned char* lds, const void* xin, const float* gain, const float* sh, const float* sc, bf16* hout, const float* wzt, float* zout, int lane, int wave, int vcu, int G) {
;     ...
;     for (int it_ = 0; it_ < nit; ++it_) {
;         const int m0 = xdeal ? 2048 * (gw >> 8) + 2 * (gw & 255) + 512 * it_ : 2 * gw + it_ * 2 * NGW;
;         if (m0 >= M) break;
;         f32x4 v[2][4][2]; float ss[2] = {0.f, 0.f};
; #pragma unroll
;         for (int r = 0; r < 2; ++r)
; #pragma unroll
;             for (int j = 0; j < 4; ++j) {
;                 if constexpr (XF32) { const float* xr = (const float*)xin + (size_t)(m0 + r) * D + 8 * lane; v[r][j][0] = *(const f32x4*)(xr + 512 * j); v[r][j][1] = *(const f32x4*)(xr + 512 * j + 4); }
;                 else { float f[8]; unpack8(*(const v4u*)((const bf16*)xin + (size_t)(m0 + r) * D + 8 * lane + 512 * j), f); v[r][j][0] = (f32x4){f[0], f[1], f[2], f[3]}; v[r][j][1] = (f32x4){f[4], f[5], f[6], f[7]}; } }
; #pragma unroll
;         for (int r = 0; r < 2; ++r)
; #pragma unroll
;             for (int j = 0; j < 4; ++j)
; #pragma unroll
;                 for (int e = 0; e < 4; ++e) ss[r] += v[r][j][0][e] * v[r][j][0][e] + v[r][j][1][e] * v[r][j][1][e];
.LBB0_174:
	s_ashr_i32 s17, s16, 31
	s_lshl_b64 s[14:15], s[16:17], 13
	v_lshl_add_u64 v[2:3], v[66:67], 0, s[14:15]
	s_add_i32 s14, s16, 1
	s_ashr_i32 s15, s14, 31
	s_lshl_b64 s[18:19], s[14:15], 13
	v_lshl_add_u64 v[4:5], v[66:67], 0, s[18:19]
	global_load_dwordx4 v[54:57], v[2:3], off
	global_load_dwordx4 v[50:53], v[2:3], off offset:16
	global_load_dwordx4 v[46:49], v[2:3], off offset:2048
	global_load_dwordx4 v[42:45], v[2:3], off offset:2064
	global_load_dwordx4 v[22:25], v[4:5], off
	global_load_dwordx4 v[18:21], v[4:5], off offset:16
	global_load_dwordx4 v[14:17], v[4:5], off offset:2048
	global_load_dwordx4 v[10:13], v[4:5], off offset:2064
	v_add_co_u32_e32 v6, vcc, 0x1000, v2
	v_lshl_add_u64 v[26:27], v[4:5], 0, s[6:7]
	s_nop 0
	v_addc_co_u32_e32 v7, vcc, 0, v3, vcc
	v_add_co_u32_e32 v8, vcc, s27, v4
	v_lshl_add_u64 v[34:35], v[2:3], 0, s[6:7]
	s_nop 0
	v_addc_co_u32_e32 v9, vcc, 0, v5, vcc
	global_load_dwordx4 v[30:33], v[8:9], off
	global_load_dwordx4 v[58:61], v[6:7], off
	s_nop 0
	global_load_dwordx4 v[26:29], v[26:27], off offset:16
	v_lshl_add_u64 v[2:3], v[2:3], 0, s[10:11]
	global_load_dwordx4 v[62:65], v[34:35], off offset:16
	v_lshl_add_u64 v[4:5], v[4:5], 0, s[10:11]
	global_load_dwordx4 v[34:37], v[2:3], off offset:16
	global_load_dwordx4 v[38:41], v[6:7], off offset:2048
	s_nop 0
	global_load_dwordx4 v[2:5], v[4:5], off offset:16
	s_nop 0
	global_load_dwordx4 v[6:9], v[8:9], off offset:2048
	s_ashr_i32 s0, s16, 11
	s_mul_hi_i32 s1, s0, 0xc000
	s_mul_i32 s0, s0, 0xc000
	s_add_u32 s20, s13, s0
	s_addc_u32 s21, s22, s1
	s_add_u32 s18, s8, s0
	s_addc_u32 s19, s9, s1
	v_cmp_lt_i32_e32 vcc, v84, v83
	s_lshl_b64 s[16:17], s[16:17], 12
	s_ashr_i32 s0, s14, 11
	v_cndmask_b32_e32 v80, v82, v84, vcc
	v_lshlrev_b32_e32 v80, 2, v80
	v_cmp_lt_i32_e32 vcc, v85, v83
	s_mul_hi_i32 s1, s0, 0xc000
	s_mul_i32 s0, s0, 0xc000
	s_waitcnt vmcnt(15)
	v_mov_b32_e32 v79, v54
	s_waitcnt vmcnt(14)
	v_mov_b32_e32 v91, v50
	v_mov_b32_e32 v95, v51
	s_waitcnt vmcnt(10)
	v_mov_b32_e32 v90, v18
	v_mov_b32_e32 v94, v19
	v_mov_b32_e32 v93, v55
	v_mov_b32_e32 v99, v52
	v_mov_b32_e32 v78, v22
	v_mov_b32_e32 v92, v23
	v_mov_b32_e32 v98, v20
	v_pk_mul_f32 v[90:91], v[90:91], v[90:91]
	v_pk_mul_f32 v[94:95], v[94:95], v[94:95]
	v_mov_b32_e32 v97, v56
	v_mov_b32_e32 v103, v53
	v_mov_b32_e32 v96, v24
	v_mov_b32_e32 v102, v21
	v_pk_mul_f32 v[98:99], v[98:99], v[98:99]
	v_pk_fma_f32 v[78:79], v[78:79], v[78:79], v[90:91]
	v_pk_fma_f32 v[90:91], v[92:93], v[92:93], v[94:95]
	v_mov_b32_e32 v101, v57
	v_mov_b32_e32 v107, v42
	v_mov_b32_e32 v100, v25
	s_waitcnt vmcnt(8)
	v_mov_b32_e32 v106, v10
	v_pk_mul_f32 v[102:103], v[102:103], v[102:103]
	v_pk_fma_f32 v[92:93], v[96:97], v[96:97], v[98:99]
	v_pk_add_f32 v[78:79], v[78:79], v[90:91]
	v_mov_b32_e32 v105, v46
	v_mov_b32_e32 v111, v43
	v_mov_b32_e32 v104, v14
	v_mov_b32_e32 v110, v11
	v_pk_mul_f32 v[106:107], v[106:107], v[106:107]
	v_pk_fma_f32 v[94:95], v[100:101], v[100:101], v[102:103]
	v_pk_add_f32 v[78:79], v[92:93], v[78:79]
	v_mov_b32_e32 v109, v47
	v_mov_b32_e32 v115, v44
	v_mov_b32_e32 v108, v15
	v_mov_b32_e32 v114, v12
	v_pk_mul_f32 v[110:111], v[110:111], v[110:111]
	v_pk_fma_f32 v[96:97], v[104:105], v[104:105], v[106:107]
	v_pk_add_f32 v[78:79], v[94:95], v[78:79]
	v_mov_b32_e32 v113, v48
	v_mov_b32_e32 v119, v45
	v_mov_b32_e32 v112, v16
	v_mov_b32_e32 v118, v13
	v_pk_mul_f32 v[114:115], v[114:115], v[114:115]
	v_pk_fma_f32 v[98:99], v[108:109], v[108:109], v[110:111]
	v_pk_add_f32 v[78:79], v[96:97], v[78:79]
	v_mov_b32_e32 v117, v49
	v_mov_b32_e32 v116, v17
	v_pk_mul_f32 v[118:119], v[118:119], v[118:119]
	s_waitcnt vmcnt(5)
	v_mov_b32_e32 v122, v26
	v_pk_fma_f32 v[100:101], v[112:113], v[112:113], v[114:115]
	s_waitcnt vmcnt(4)
	v_mov_b32_e32 v123, v62
	v_pk_add_f32 v[78:79], v[98:99], v[78:79]
	v_mov_b32_e32 v120, v30
	v_mov_b32_e32 v121, v58
	v_pk_fma_f32 v[102:103], v[116:117], v[116:117], v[118:119]
	v_pk_mul_f32 v[90:91], v[122:123], v[122:123]
	v_pk_add_f32 v[78:79], v[100:101], v[78:79]
	v_pk_fma_f32 v[90:91], v[120:121], v[120:121], v[90:91]
	v_pk_add_f32 v[78:79], v[102:103], v[78:79]
	v_mov_b32_e32 v92, v27
	v_mov_b32_e32 v93, v63
	v_pk_add_f32 v[78:79], v[90:91], v[78:79]
	v_mov_b32_e32 v90, v31
	v_mov_b32_e32 v91, v59
	v_pk_mul_f32 v[92:93], v[92:93], v[92:93]
	global_load_dwordx4 v[98:101], v1, s[18:19]
	global_load_dwordx4 v[110:113], v1, s[18:19] offset:16
	v_pk_fma_f32 v[90:91], v[90:91], v[90:91], v[92:93]
	v_mov_b32_e32 v92, v28
	v_mov_b32_e32 v93, v64
	v_pk_add_f32 v[78:79], v[90:91], v[78:79]
	v_mov_b32_e32 v90, v32
	v_mov_b32_e32 v91, v60
	v_pk_mul_f32 v[92:93], v[92:93], v[92:93]
	global_load_dwordx4 v[102:105], v[68:69], off offset:16
	v_pk_fma_f32 v[90:91], v[90:91], v[90:91], v[92:93]
	v_mov_b32_e32 v92, v29
	v_mov_b32_e32 v93, v65
	v_pk_add_f32 v[78:79], v[90:91], v[78:79]
	v_mov_b32_e32 v90, v33
	v_mov_b32_e32 v91, v61
	v_pk_mul_f32 v[92:93], v[92:93], v[92:93]
	global_load_dwordx4 v[106:109], v1, s[20:21] offset:16
	v_pk_fma_f32 v[90:91], v[90:91], v[90:91], v[92:93]
	s_waitcnt vmcnt(5)
	v_pk_mul_f32 v[92:93], v[2:3], v[2:3]
	v_pk_add_f32 v[78:79], v[90:91], v[78:79]
	v_pk_mul_f32 v[90:91], v[34:35], v[34:35]
	s_waitcnt vmcnt(4)
	v_pk_fma_f32 v[92:93], v[6:7], v[6:7], v[92:93]
	v_pk_fma_f32 v[90:91], v[38:39], v[38:39], v[90:91]
	v_mov_b32_e32 v94, v92
	v_mov_b32_e32 v95, v90
	v_pk_add_f32 v[78:79], v[94:95], v[78:79]
	v_mov_b32_e32 v90, v93
	v_pk_add_f32 v[78:79], v[90:91], v[78:79]
	v_pk_mul_f32 v[90:91], v[36:37], v[36:37]
	v_pk_mul_f32 v[92:93], v[4:5], v[4:5]
	v_pk_fma_f32 v[90:91], v[40:41], v[40:41], v[90:91]
	v_pk_fma_f32 v[92:93], v[8:9], v[8:9], v[92:93]
	v_mov_b32_e32 v95, v90
	v_mov_b32_e32 v94, v92
	v_pk_add_f32 v[78:79], v[94:95], v[78:79]
	v_mov_b32_e32 v90, v93
	v_pk_add_f32 v[78:79], v[90:91], v[78:79]
	global_load_dwordx4 v[90:93], v[68:69], off
	global_load_dwordx4 v[94:97], v1, s[20:21]
	ds_bpermute_b32 v115, v80, v79
	ds_bpermute_b32 v114, v80, v78
	v_cndmask_b32_e32 v80, v82, v85, vcc
	v_lshlrev_b32_e32 v80, 2, v80
	v_cmp_lt_i32_e32 vcc, v86, v83
	s_waitcnt lgkmcnt(0)
; __device__ __forceinline__ unsigned pk2(float lo, float hi) { return f2bf(lo) | (f2bf(hi) << 16); }
; template <bool ZP, bool XF32, bool OUT8 = false>
; __device__ __forceinline__ void norm_phase(LAS unsigned char* lds, const void* xin, const float* gain, const float* sh, const float* sc, bf16* hout, const float* wzt, float* zout, int lane, int wave, int vcu, int G) {
;     ...
;         for (int r = 0; r < 2; ++r) { const int m = m0 + r, b = m >> 11;
;             const float rstd = rsqrtf(wave_sum(ss[r]) * (1.0f / D) + EPS);
; #pragma unroll
;             for (int j = 0; j < 4; ++j) { const int col = 512 * j + 8 * lane;
; #pragma unroll
;                 for (int q = 0; q < 2; ++q) { const f32x4 gg = *(const f32x4*)(gain + col + 4 * q), s1 = *(const f32x4*)(sc + (size_t)b * MODW + col + 4 * q), s0 = *(const f32x4*)(sh + (size_t)b * MODW + col + 4 * q);
;                     v[r][j][q] = (v[r][j][q] * rstd * gg) * (s1 + 1.0f) + s0; }
;                 if constexpr (OUT8) { *(v2u*)((unsigned char*)hout + (size_t)m * D + col) = pack8_fp8(v[r][j][0][0], v[r][j][0][1], v[r][j][0][2], v[r][j][0][3], v[r][j][1][0], v[r][j][1][1], v[r][j][1][2], v[r][j][1][3], FP8_ASCALE); }
;                 else { v4u o; o.x = pk2(v[r][j][0][0], v[r][j][0][1]); o.y = pk2(v[r][j][0][2], v[r][j][0][3]); o.z = pk2(v[r][j][1][0], v[r][j][1][1]); o.w = pk2(v[r][j][1][2], v[r][j][1][3]);
;                     *(v4u*)(hout + (size_t)m * D + col) = o; } }
	v_pk_add_f32 v[78:79], v[78:79], v[114:115]
	ds_bpermute_b32 v115, v80, v79
	ds_bpermute_b32 v114, v80, v78
	v_cndmask_b32_e32 v80, v82, v86, vcc
	v_lshlrev_b32_e32 v80, 2, v80
	v_cmp_lt_i32_e32 vcc, v87, v83
	s_waitcnt lgkmcnt(0)
	v_pk_add_f32 v[78:79], v[78:79], v[114:115]
	ds_bpermute_b32 v115, v80, v79
	ds_bpermute_b32 v114, v80, v78
	v_cndmask_b32_e32 v80, v82, v87, vcc
	v_lshlrev_b32_e32 v80, 2, v80
	v_cmp_lt_i32_e32 vcc, v88, v83
	s_waitcnt lgkmcnt(0)
	v_pk_add_f32 v[78:79], v[78:79], v[114:115]
	ds_bpermute_b32 v115, v80, v79
	ds_bpermute_b32 v114, v80, v78
	v_cndmask_b32_e32 v80, v82, v88, vcc
	v_lshlrev_b32_e32 v80, 2, v80
	v_cmp_lt_i32_e32 vcc, v89, v83
	s_waitcnt lgkmcnt(0)
	v_pk_add_f32 v[78:79], v[78:79], v[114:115]
	ds_bpermute_b32 v115, v80, v79
	ds_bpermute_b32 v114, v80, v78
	v_cndmask_b32_e32 v80, v82, v89, vcc
	v_lshlrev_b32_e32 v80, 2, v80
	s_waitcnt lgkmcnt(0)
	v_pk_add_f32 v[78:79], v[78:79], v[114:115]
	ds_bpermute_b32 v115, v80, v79
	ds_bpermute_b32 v114, v80, v78
	s_waitcnt lgkmcnt(0)
	v_pk_add_f32 v[78:79], v[78:79], v[114:115]
	s_nop 0
	v_pk_fma_f32 v[78:79], v[78:79], s[12:13], v[76:77] op_sel_hi:[1,0,0]
	s_nop 0
	v_mul_f32_e32 v80, 0x4b800000, v79
	v_cmp_gt_f32_e32 vcc, s28, v79
	s_nop 1
	v_cndmask_b32_e32 v79, v79, v80, vcc
	v_rsq_f32_e32 v79, v79
	s_nop 0
	v_mul_f32_e32 v80, 0x45800000, v79
	v_cndmask_b32_e32 v80, v79, v80, vcc
	v_pk_mul_f32 v[56:57], v[56:57], v[80:81] op_sel_hi:[1,0]
	v_pk_mul_f32 v[54:55], v[54:55], v[80:81] op_sel_hi:[1,0]
	v_pk_mul_f32 v[52:53], v[52:53], v[80:81] op_sel_hi:[1,0]
	v_pk_mul_f32 v[50:51], v[50:51], v[80:81] op_sel_hi:[1,0]
	s_waitcnt vmcnt(3)
	v_pk_mul_f32 v[52:53], v[104:105], v[52:53]
	v_pk_mul_f32 v[50:51], v[102:103], v[50:51]
	v_pk_mul_f32 v[48:49], v[48:49], v[80:81] op_sel_hi:[1,0]
	v_pk_mul_f32 v[46:47], v[46:47], v[80:81] op_sel_hi:[1,0]
	v_pk_mul_f32 v[44:45], v[44:45], v[80:81] op_sel_hi:[1,0]
	v_pk_mul_f32 v[42:43], v[42:43], v[80:81] op_sel_hi:[1,0]
	v_pk_mul_f32 v[58:59], v[58:59], v[80:81] op_sel_hi:[1,0]
	v_pk_mul_f32 v[62:63], v[62:63], v[80:81] op_sel_hi:[1,0]
	v_pk_mul_f32 v[40:41], v[40:41], v[80:81] op_sel_hi:[1,0]
	v_pk_mul_f32 v[38:39], v[38:39], v[80:81] op_sel_hi:[1,0]
	v_pk_mul_f32 v[36:37], v[36:37], v[80:81] op_sel_hi:[1,0]
	v_pk_mul_f32 v[34:35], v[34:35], v[80:81] op_sel_hi:[1,0]
	v_cmp_gt_f32_e32 vcc, s28, v78
	s_waitcnt vmcnt(1)
	v_pk_mul_f32 v[54:55], v[90:91], v[54:55]
	v_pk_mul_f32 v[56:57], v[92:93], v[56:57]
	s_waitcnt vmcnt(0)
	v_pk_add_f32 v[90:91], v[96:97], 1.0 op_sel_hi:[1,0]
	v_pk_add_f32 v[92:93], v[94:95], 1.0 op_sel_hi:[1,0]
	v_pk_fma_f32 v[56:57], v[90:91], v[56:57], v[100:101]
	v_pk_fma_f32 v[54:55], v[92:93], v[54:55], v[98:99]
	v_pk_add_f32 v[90:91], v[108:109], 1.0 op_sel_hi:[1,0]
	v_pk_add_f32 v[92:93], v[106:107], 1.0 op_sel_hi:[1,0]
	v_pk_fma_f32 v[90:91], v[90:91], v[52:53], v[112:113]
	v_bfe_u32 v52, v54, 16, 1
	v_add3_u32 v52, v54, v52, s29
	v_bfe_u32 v53, v55, 16, 1
	v_add3_u32 v53, v55, v53, s29
	v_pk_fma_f32 v[50:51], v[92:93], v[50:51], v[110:111]
	v_lshrrev_b32_e32 v52, 16, v52
	v_and_or_b32 v52, v53, s30, v52
	v_cvt_pk_bf16_f32 v53, v56, v57
	v_bfe_u32 v54, v50, 16, 1
	v_add3_u32 v50, v50, v54, s29
	v_bfe_u32 v54, v51, 16, 1
	v_add3_u32 v51, v51, v54, s29
	v_lshrrev_b32_e32 v50, 16, v50
	v_and_or_b32 v54, v51, s30, v50
	v_cvt_pk_bf16_f32 v55, v90, v91
	v_lshl_add_u64 v[50:51], v[74:75], 0, s[16:17]
	global_store_dwordx4 v[50:51], v[52:55], off
	global_load_dwordx4 v[52:55], v[68:69], off offset:2048
	s_nop 0
	global_load_dwordx4 v[90:93], v1, s[20:21] offset:2048
	global_load_dwordx4 v[94:97], v1, s[18:19] offset:2048
	global_load_dwordx4 v[98:101], v[68:69], off offset:2064
	global_load_dwordx4 v[102:105], v1, s[20:21] offset:2064
	global_load_dwordx4 v[106:109], v1, s[18:19] offset:2064
	v_pk_mul_f32 v[56:57], v[60:61], v[80:81] op_sel_hi:[1,0]
	v_pk_mul_f32 v[60:61], v[64:65], v[80:81] op_sel_hi:[1,0]
	s_add_u32 s16, s13, s0
	s_addc_u32 s17, s22, s1
	s_waitcnt vmcnt(5)
	v_pk_mul_f32 v[46:47], v[52:53], v[46:47]
	v_pk_mul_f32 v[48:49], v[54:55], v[48:49]
	s_waitcnt vmcnt(4)
	v_pk_add_f32 v[52:53], v[92:93], 1.0 op_sel_hi:[1,0]
	v_pk_add_f32 v[54:55], v[90:91], 1.0 op_sel_hi:[1,0]
	s_waitcnt vmcnt(3)
	v_pk_fma_f32 v[48:49], v[52:53], v[48:49], v[96:97]
	v_pk_fma_f32 v[46:47], v[54:55], v[46:47], v[94:95]
	s_waitcnt vmcnt(2)
	v_pk_mul_f32 v[42:43], v[98:99], v[42:43]
	v_pk_mul_f32 v[44:45], v[100:101], v[44:45]
	s_waitcnt vmcnt(1)
	v_pk_add_f32 v[52:53], v[104:105], 1.0 op_sel_hi:[1,0]
	v_pk_add_f32 v[54:55], v[102:103], 1.0 op_sel_hi:[1,0]
	s_waitcnt vmcnt(0)
	v_pk_fma_f32 v[52:53], v[52:53], v[44:45], v[108:109]
	v_pk_fma_f32 v[44:45], v[54:55], v[42:43], v[106:107]
	v_bfe_u32 v42, v46, 16, 1
	v_add3_u32 v42, v46, v42, s29
	v_bfe_u32 v43, v47, 16, 1
	v_add3_u32 v43, v47, v43, s29
	v_lshrrev_b32_e32 v42, 16, v42
	v_and_or_b32 v42, v43, s30, v42
	v_cvt_pk_bf16_f32 v43, v48, v49
	v_bfe_u32 v46, v44, 16, 1
	v_add3_u32 v44, v44, v46, s29
	v_bfe_u32 v46, v45, 16, 1
	v_add3_u32 v45, v45, v46, s29
	v_lshrrev_b32_e32 v44, 16, v44
	v_and_or_b32 v44, v45, s30, v44
	v_cvt_pk_bf16_f32 v45, v52, v53
	global_store_dwordx4 v[50:51], v[42:45], off offset:1024
	global_load_dwordx4 v[42:45], v[70:71], off
	s_nop 0
	global_load_dwordx4 v[46:49], v77, s[20:21]
	global_load_dwordx4 v[52:55], v[70:71], off offset:16
	global_load_dwordx4 v[90:93], v77, s[20:21] offset:16
	global_load_dwordx4 v[94:97], v77, s[18:19]
	global_load_dwordx4 v[98:101], v77, s[18:19] offset:16
	s_waitcnt vmcnt(5)
	v_pk_mul_f32 v[42:43], v[58:59], v[42:43]
	v_pk_mul_f32 v[44:45], v[56:57], v[44:45]
	s_waitcnt vmcnt(4)
; __device__ __forceinline__ unsigned pk2(float lo, float hi) { return f2bf(lo) | (f2bf(hi) << 16); }
; template <bool ZP, bool XF32, bool OUT8 = false>
; __device__ __forceinline__ void norm_phase(LAS unsigned char* lds, const void* xin, const float* gain, const float* sh, const float* sc, bf16* hout, const float* wzt, float* zout, int lane, int wave, int vcu, int G) {
;     ...
;         for (int r = 0; r < 2; ++r) { const int m = m0 + r, b = m >> 11;
;             const float rstd = rsqrtf(wave_sum(ss[r]) * (1.0f / D) + EPS);
; #pragma unroll
;             for (int j = 0; j < 4; ++j) { const int col = 512 * j + 8 * lane;
; #pragma unroll
;                 for (int q = 0; q < 2; ++q) { const f32x4 gg = *(const f32x4*)(gain + col + 4 * q), s1 = *(const f32x4*)(sc + (size_t)b * MODW + col + 4 * q), s0 = *(const f32x4*)(sh + (size_t)b * MODW + col + 4 * q);
;                     v[r][j][q] = (v[r][j][q] * rstd * gg) * (s1 + 1.0f) + s0; }
;                 if constexpr (OUT8) { *(v2u*)((unsigned char*)hout + (size_t)m * D + col) = pack8_fp8(v[r][j][0][0], v[r][j][0][1], v[r][j][0][2], v[r][j][0][3], v[r][j][1][0], v[r][j][1][1], v[r][j][1][2], v[r][j][1][3], FP8_ASCALE); }
;                 else { v4u o; o.x = pk2(v[r][j][0][0], v[r][j][0][1]); o.y = pk2(v[r][j][0][2], v[r][j][0][3]); o.z = pk2(v[r][j][1][0], v[r][j][1][1]); o.w = pk2(v[r][j][1][2], v[r][j][1][3]);
;                     *(v4u*)(hout + (size_t)m * D + col) = o; } }
	v_pk_add_f32 v[48:49], v[48:49], 1.0 op_sel_hi:[1,0]
	v_pk_add_f32 v[46:47], v[46:47], 1.0 op_sel_hi:[1,0]
	s_waitcnt vmcnt(3)
	v_pk_mul_f32 v[52:53], v[62:63], v[52:53]
	v_pk_mul_f32 v[54:55], v[60:61], v[54:55]
	s_waitcnt vmcnt(2)
	v_pk_add_f32 v[56:57], v[92:93], 1.0 op_sel_hi:[1,0]
	v_pk_add_f32 v[58:59], v[90:91], 1.0 op_sel_hi:[1,0]
	s_waitcnt vmcnt(1)
	v_pk_fma_f32 v[44:45], v[44:45], v[48:49], v[96:97]
	v_pk_fma_f32 v[42:43], v[42:43], v[46:47], v[94:95]
	s_waitcnt vmcnt(0)
	v_pk_fma_f32 v[46:47], v[54:55], v[56:57], v[100:101]
	v_pk_fma_f32 v[48:49], v[52:53], v[58:59], v[98:99]
	v_bfe_u32 v52, v42, 16, 1
	v_bfe_u32 v54, v44, 16, 1
	v_bfe_u32 v56, v48, 16, 1
	v_bfe_u32 v58, v46, 16, 1
	v_bfe_u32 v53, v43, 16, 1
	v_bfe_u32 v55, v45, 16, 1
	v_bfe_u32 v57, v49, 16, 1
	v_bfe_u32 v59, v47, 16, 1
	v_add3_u32 v42, v42, v52, s29
	v_add3_u32 v44, v44, v54, s29
	v_add3_u32 v48, v48, v56, s29
	v_add3_u32 v46, v46, v58, s29
	v_add3_u32 v43, v43, v53, s29
	v_add3_u32 v45, v45, v55, s29
	v_add3_u32 v49, v49, v57, s29
	v_add3_u32 v47, v47, v59, s29
	v_lshrrev_b32_e32 v42, 16, v42
	v_lshrrev_b32_e32 v44, 16, v44
	v_lshrrev_b32_e32 v48, 16, v48
	v_lshrrev_b32_e32 v46, 16, v46
	v_and_or_b32 v42, v43, s30, v42
	v_and_or_b32 v43, v45, s30, v44
	v_and_or_b32 v44, v49, s30, v48
	v_and_or_b32 v45, v47, s30, v46
	global_store_dwordx4 v[50:51], v[42:45], off offset:2048
	global_load_dwordx4 v[42:45], v[72:73], off
	s_nop 0
	global_load_dwordx4 v[46:49], v81, s[20:21]
	global_load_dwordx4 v[52:55], v[72:73], off offset:16
	global_load_dwordx4 v[56:59], v81, s[20:21] offset:16
	global_load_dwordx4 v[60:63], v81, s[18:19]
	global_load_dwordx4 v[90:93], v81, s[18:19] offset:16
	s_add_u32 s18, s8, s0
	s_addc_u32 s19, s9, s1
	s_lshl_b64 s[14:15], s[14:15], 12
	s_add_i32 s26, s26, 1
	s_addk_i32 s25, 0x200
	s_add_i32 s3, s3, -1
	s_cmp_eq_u32 s3, 0
	s_waitcnt vmcnt(5)
	v_pk_mul_f32 v[38:39], v[38:39], v[42:43]
	v_pk_mul_f32 v[40:41], v[40:41], v[44:45]
	s_waitcnt vmcnt(4)
	v_pk_add_f32 v[42:43], v[48:49], 1.0 op_sel_hi:[1,0]
	v_pk_add_f32 v[44:45], v[46:47], 1.0 op_sel_hi:[1,0]
	s_waitcnt vmcnt(3)
	v_pk_mul_f32 v[34:35], v[34:35], v[52:53]
	v_pk_mul_f32 v[36:37], v[36:37], v[54:55]
	s_waitcnt vmcnt(2)
	v_pk_add_f32 v[46:47], v[58:59], 1.0 op_sel_hi:[1,0]
	v_pk_add_f32 v[48:49], v[56:57], 1.0 op_sel_hi:[1,0]
	s_waitcnt vmcnt(1)
	v_pk_fma_f32 v[40:41], v[40:41], v[42:43], v[62:63]
	v_pk_fma_f32 v[38:39], v[38:39], v[44:45], v[60:61]
	s_waitcnt vmcnt(0)
	v_pk_fma_f32 v[36:37], v[36:37], v[46:47], v[92:93]
	v_pk_fma_f32 v[34:35], v[34:35], v[48:49], v[90:91]
	v_bfe_u32 v42, v38, 16, 1
	v_bfe_u32 v44, v40, 16, 1
	v_bfe_u32 v46, v34, 16, 1
	v_bfe_u32 v47, v35, 16, 1
	v_bfe_u32 v48, v36, 16, 1
	v_bfe_u32 v43, v39, 16, 1
	v_bfe_u32 v45, v41, 16, 1
	v_bfe_u32 v49, v37, 16, 1
	v_add3_u32 v38, v38, v42, s29
	v_add3_u32 v40, v40, v44, s29
	v_add3_u32 v34, v34, v46, s29
	v_add3_u32 v42, v35, v47, s29
	v_add3_u32 v35, v36, v48, s29
	v_add3_u32 v39, v39, v43, s29
	v_add3_u32 v41, v41, v45, s29
	v_add3_u32 v37, v37, v49, s29
	v_lshrrev_b32_e32 v36, 16, v38
	v_lshrrev_b32_e32 v38, 16, v40
	v_lshrrev_b32_e32 v40, 16, v34
	v_lshrrev_b32_e32 v43, 16, v35
	v_and_or_b32 v34, v39, s30, v36
	v_and_or_b32 v35, v41, s30, v38
	v_and_or_b32 v36, v42, s30, v40
	v_and_or_b32 v37, v37, s30, v43
	global_store_dwordx4 v[50:51], v[34:37], off offset:3072
	global_load_dwordx4 v[38:41], v[68:69], off
	global_load_dwordx4 v[42:45], v[68:69], off offset:16
	global_load_dwordx4 v[46:49], v1, s[16:17]
	s_nop 0
	global_load_dwordx4 v[50:53], v1, s[16:17] offset:16
	global_load_dwordx4 v[54:57], v1, s[18:19]
	global_load_dwordx4 v[58:61], v1, s[18:19] offset:16
	v_mul_f32_e32 v34, 0x4b800000, v78
	v_cndmask_b32_e32 v34, v78, v34, vcc
	v_rsq_f32_e32 v36, v34
	v_lshl_add_u64 v[34:35], v[74:75], 0, s[14:15]
	s_cselect_b64 s[14:15], -1, 0
	v_mul_f32_e32 v37, 0x45800000, v36
	v_cndmask_b32_e32 v36, v36, v37, vcc
	v_pk_mul_f32 v[24:25], v[24:25], v[36:37] op_sel_hi:[1,0]
	v_pk_mul_f32 v[22:23], v[22:23], v[36:37] op_sel_hi:[1,0]
	v_pk_mul_f32 v[20:21], v[20:21], v[36:37] op_sel_hi:[1,0]
	v_pk_mul_f32 v[18:19], v[18:19], v[36:37] op_sel_hi:[1,0]
	s_waitcnt vmcnt(5)
	v_pk_mul_f32 v[22:23], v[38:39], v[22:23]
	v_pk_mul_f32 v[24:25], v[40:41], v[24:25]
	s_waitcnt vmcnt(4)
	v_pk_mul_f32 v[18:19], v[42:43], v[18:19]
	v_pk_mul_f32 v[20:21], v[44:45], v[20:21]
	s_waitcnt vmcnt(3)
	v_pk_add_f32 v[38:39], v[48:49], 1.0 op_sel_hi:[1,0]
	v_pk_add_f32 v[40:41], v[46:47], 1.0 op_sel_hi:[1,0]
	s_waitcnt vmcnt(2)
	v_pk_add_f32 v[42:43], v[52:53], 1.0 op_sel_hi:[1,0]
	v_pk_add_f32 v[44:45], v[50:51], 1.0 op_sel_hi:[1,0]
	s_waitcnt vmcnt(1)
	v_pk_fma_f32 v[24:25], v[38:39], v[24:25], v[56:57]
	v_pk_fma_f32 v[22:23], v[40:41], v[22:23], v[54:55]
	s_waitcnt vmcnt(0)
; __device__ __forceinline__ unsigned pk2(float lo, float hi) { return f2bf(lo) | (f2bf(hi) << 16); }
; template <bool ZP, bool XF32, bool OUT8 = false>
; __device__ __forceinline__ void norm_phase(LAS unsigned char* lds, const void* xin, const float* gain, const float* sh, const float* sc, bf16* hout, const float* wzt, float* zout, int lane, int wave, int vcu, int G) {
;     ...
;         for (int r = 0; r < 2; ++r) { const int m = m0 + r, b = m >> 11;
;             const float rstd = rsqrtf(wave_sum(ss[r]) * (1.0f / D) + EPS);
; #pragma unroll
;             for (int j = 0; j < 4; ++j) { const int col = 512 * j + 8 * lane;
; #pragma unroll
;                 for (int q = 0; q < 2; ++q) { const f32x4 gg = *(const f32x4*)(gain + col + 4 * q), s1 = *(const f32x4*)(sc + (size_t)b * MODW + col + 4 * q), s0 = *(const f32x4*)(sh + (size_t)b * MODW + col + 4 * q);
;                     v[r][j][q] = (v[r][j][q] * rstd * gg) * (s1 + 1.0f) + s0; }
;                 if constexpr (OUT8) { *(v2u*)((unsigned char*)hout + (size_t)m * D + col) = pack8_fp8(v[r][j][0][0], v[r][j][0][1], v[r][j][0][2], v[r][j][0][3], v[r][j][1][0], v[r][j][1][1], v[r][j][1][2], v[r][j][1][3], FP8_ASCALE); }
;                 else { v4u o; o.x = pk2(v[r][j][0][0], v[r][j][0][1]); o.y = pk2(v[r][j][0][2], v[r][j][0][3]); o.z = pk2(v[r][j][1][0], v[r][j][1][1]); o.w = pk2(v[r][j][1][2], v[r][j][1][3]);
;                     *(v4u*)(hout + (size_t)m * D + col) = o; } }
	v_pk_fma_f32 v[20:21], v[42:43], v[20:21], v[60:61]
	v_pk_fma_f32 v[18:19], v[44:45], v[18:19], v[58:59]
	v_bfe_u32 v37, v22, 16, 1
	v_bfe_u32 v39, v24, 16, 1
	v_bfe_u32 v41, v18, 16, 1
	v_bfe_u32 v42, v19, 16, 1
	v_bfe_u32 v43, v20, 16, 1
	v_bfe_u32 v38, v23, 16, 1
	v_bfe_u32 v40, v25, 16, 1
	v_bfe_u32 v44, v21, 16, 1
	v_add3_u32 v22, v22, v37, s29
	v_add3_u32 v24, v24, v39, s29
	v_add3_u32 v18, v18, v41, s29
	v_add3_u32 v37, v19, v42, s29
	v_add3_u32 v19, v20, v43, s29
	v_add3_u32 v23, v23, v38, s29
	v_add3_u32 v25, v25, v40, s29
	v_add3_u32 v21, v21, v44, s29
	v_lshrrev_b32_e32 v20, 16, v22
	v_lshrrev_b32_e32 v22, 16, v24
	v_lshrrev_b32_e32 v24, 16, v18
	v_lshrrev_b32_e32 v38, 16, v19
	v_and_or_b32 v18, v23, s30, v20
	v_and_or_b32 v19, v25, s30, v22
	v_and_or_b32 v20, v37, s30, v24
	v_and_or_b32 v21, v21, s30, v38
	global_store_dwordx4 v[34:35], v[18:21], off
	global_load_dwordx4 v[18:21], v[68:69], off offset:2048
	s_nop 0
	global_load_dwordx4 v[22:25], v1, s[16:17] offset:2048
	global_load_dwordx4 v[38:41], v[68:69], off offset:2064
	global_load_dwordx4 v[42:45], v1, s[16:17] offset:2064
	global_load_dwordx4 v[46:49], v1, s[18:19] offset:2048
	global_load_dwordx4 v[50:53], v1, s[18:19] offset:2064
	v_pk_mul_f32 v[16:17], v[16:17], v[36:37] op_sel_hi:[1,0]
	v_pk_mul_f32 v[14:15], v[14:15], v[36:37] op_sel_hi:[1,0]
	v_pk_mul_f32 v[12:13], v[12:13], v[36:37] op_sel_hi:[1,0]
	v_pk_mul_f32 v[10:11], v[10:11], v[36:37] op_sel_hi:[1,0]
	v_pk_mul_f32 v[32:33], v[32:33], v[36:37] op_sel_hi:[1,0]
	v_pk_mul_f32 v[30:31], v[30:31], v[36:37] op_sel_hi:[1,0]
	v_pk_mul_f32 v[28:29], v[28:29], v[36:37] op_sel_hi:[1,0]
	v_pk_mul_f32 v[26:27], v[26:27], v[36:37] op_sel_hi:[1,0]
	v_pk_mul_f32 v[8:9], v[8:9], v[36:37] op_sel_hi:[1,0]
	v_pk_mul_f32 v[6:7], v[6:7], v[36:37] op_sel_hi:[1,0]
	v_pk_mul_f32 v[4:5], v[4:5], v[36:37] op_sel_hi:[1,0]
	v_pk_mul_f32 v[2:3], v[2:3], v[36:37] op_sel_hi:[1,0]
	s_waitcnt vmcnt(5)
	v_pk_mul_f32 v[14:15], v[18:19], v[14:15]
	v_pk_mul_f32 v[16:17], v[20:21], v[16:17]
	s_waitcnt vmcnt(4)
	v_pk_add_f32 v[18:19], v[24:25], 1.0 op_sel_hi:[1,0]
	v_pk_add_f32 v[20:21], v[22:23], 1.0 op_sel_hi:[1,0]
	s_waitcnt vmcnt(3)
	v_pk_mul_f32 v[10:11], v[38:39], v[10:11]
	v_pk_mul_f32 v[12:13], v[40:41], v[12:13]
	s_waitcnt vmcnt(2)
	v_pk_add_f32 v[22:23], v[44:45], 1.0 op_sel_hi:[1,0]
	v_pk_add_f32 v[24:25], v[42:43], 1.0 op_sel_hi:[1,0]
	s_waitcnt vmcnt(1)
	v_pk_fma_f32 v[16:17], v[18:19], v[16:17], v[48:49]
	v_pk_fma_f32 v[14:15], v[20:21], v[14:15], v[46:47]
	s_waitcnt vmcnt(0)
	v_pk_fma_f32 v[12:13], v[22:23], v[12:13], v[52:53]
	v_pk_fma_f32 v[10:11], v[24:25], v[10:11], v[50:51]
	v_bfe_u32 v18, v14, 16, 1
	v_bfe_u32 v20, v16, 16, 1
	v_bfe_u32 v22, v10, 16, 1
	v_bfe_u32 v23, v11, 16, 1
	v_bfe_u32 v24, v12, 16, 1
	v_bfe_u32 v19, v15, 16, 1
	v_bfe_u32 v21, v17, 16, 1
	v_bfe_u32 v25, v13, 16, 1
	v_add3_u32 v14, v14, v18, s29
	v_add3_u32 v16, v16, v20, s29
	v_add3_u32 v10, v10, v22, s29
	v_add3_u32 v18, v11, v23, s29
	v_add3_u32 v11, v12, v24, s29
	v_add3_u32 v15, v15, v19, s29
	v_add3_u32 v17, v17, v21, s29
	v_add3_u32 v13, v13, v25, s29
	v_lshrrev_b32_e32 v12, 16, v14
	v_lshrrev_b32_e32 v14, 16, v16
	v_lshrrev_b32_e32 v16, 16, v10
	v_lshrrev_b32_e32 v19, 16, v11
	v_and_or_b32 v10, v15, s30, v12
	v_and_or_b32 v11, v17, s30, v14
	v_and_or_b32 v12, v18, s30, v16
	v_and_or_b32 v13, v13, s30, v19
	global_store_dwordx4 v[34:35], v[10:13], off offset:1024
	global_load_dwordx4 v[10:13], v[70:71], off
	s_nop 0
	global_load_dwordx4 v[14:17], v77, s[16:17]
	global_load_dwordx4 v[18:21], v[70:71], off offset:16
	global_load_dwordx4 v[22:25], v77, s[16:17] offset:16
	global_load_dwordx4 v[38:41], v77, s[18:19]
	global_load_dwordx4 v[42:45], v77, s[18:19] offset:16
	s_waitcnt vmcnt(5)
	v_pk_mul_f32 v[10:11], v[30:31], v[10:11]
	v_pk_mul_f32 v[12:13], v[32:33], v[12:13]
	s_waitcnt vmcnt(4)
	v_pk_add_f32 v[16:17], v[16:17], 1.0 op_sel_hi:[1,0]
	v_pk_add_f32 v[14:15], v[14:15], 1.0 op_sel_hi:[1,0]
	s_waitcnt vmcnt(3)
	v_pk_mul_f32 v[18:19], v[26:27], v[18:19]
	v_pk_mul_f32 v[20:21], v[28:29], v[20:21]
	s_waitcnt vmcnt(2)
	v_pk_add_f32 v[24:25], v[24:25], 1.0 op_sel_hi:[1,0]
	v_pk_add_f32 v[22:23], v[22:23], 1.0 op_sel_hi:[1,0]
	s_waitcnt vmcnt(1)
	v_pk_fma_f32 v[12:13], v[12:13], v[16:17], v[40:41]
	v_pk_fma_f32 v[10:11], v[10:11], v[14:15], v[38:39]
	s_waitcnt vmcnt(0)
	v_pk_fma_f32 v[14:15], v[20:21], v[24:25], v[44:45]
	v_pk_fma_f32 v[16:17], v[18:19], v[22:23], v[42:43]
	v_bfe_u32 v18, v10, 16, 1
	v_bfe_u32 v20, v12, 16, 1
	v_bfe_u32 v22, v16, 16, 1
	v_bfe_u32 v24, v14, 16, 1
	v_bfe_u32 v19, v11, 16, 1
	v_bfe_u32 v21, v13, 16, 1
	v_bfe_u32 v23, v17, 16, 1
	v_bfe_u32 v25, v15, 16, 1
	v_add3_u32 v10, v10, v18, s29
	v_add3_u32 v12, v12, v20, s29
	v_add3_u32 v16, v16, v22, s29
	v_add3_u32 v14, v14, v24, s29
	v_add3_u32 v11, v11, v19, s29
	v_add3_u32 v13, v13, v21, s29
	v_add3_u32 v17, v17, v23, s29
	v_add3_u32 v15, v15, v25, s29
	v_lshrrev_b32_e32 v10, 16, v10
	v_lshrrev_b32_e32 v12, 16, v12
	v_lshrrev_b32_e32 v16, 16, v16
	v_lshrrev_b32_e32 v14, 16, v14
	v_and_or_b32 v10, v11, s30, v10
	v_and_or_b32 v11, v13, s30, v12
	v_and_or_b32 v12, v17, s30, v16
	v_and_or_b32 v13, v15, s30, v14
	global_store_dwordx4 v[34:35], v[10:13], off offset:2048
	global_load_dwordx4 v[10:13], v[72:73], off
	s_nop 0
	global_load_dwordx4 v[14:17], v81, s[16:17]
	global_load_dwordx4 v[18:21], v[72:73], off offset:16
	global_load_dwordx4 v[22:25], v81, s[16:17] offset:16
	global_load_dwordx4 v[26:29], v81, s[18:19]
	global_load_dwordx4 v[30:33], v81, s[18:19] offset:16
	s_waitcnt vmcnt(5)
	v_pk_mul_f32 v[6:7], v[6:7], v[10:11]
	v_pk_mul_f32 v[8:9], v[8:9], v[12:13]
	s_waitcnt vmcnt(4)
	v_pk_add_f32 v[10:11], v[16:17], 1.0 op_sel_hi:[1,0]
	v_pk_add_f32 v[12:13], v[14:15], 1.0 op_sel_hi:[1,0]
	s_waitcnt vmcnt(3)
	v_pk_mul_f32 v[2:3], v[2:3], v[18:19]
	v_pk_mul_f32 v[4:5], v[4:5], v[20:21]
	s_waitcnt vmcnt(2)
	v_pk_add_f32 v[14:15], v[24:25], 1.0 op_sel_hi:[1,0]
	v_pk_add_f32 v[16:17], v[22:23], 1.0 op_sel_hi:[1,0]
	s_waitcnt vmcnt(1)
	v_pk_fma_f32 v[8:9], v[8:9], v[10:11], v[28:29]
	v_pk_fma_f32 v[6:7], v[6:7], v[12:13], v[26:27]
	s_waitcnt vmcnt(0)
	v_pk_fma_f32 v[4:5], v[4:5], v[14:15], v[32:33]
	v_pk_fma_f32 v[2:3], v[2:3], v[16:17], v[30:31]
	v_bfe_u32 v10, v6, 16, 1
	v_bfe_u32 v12, v8, 16, 1
	v_bfe_u32 v14, v2, 16, 1
	v_bfe_u32 v15, v3, 16, 1
	v_bfe_u32 v16, v4, 16, 1
	v_bfe_u32 v11, v7, 16, 1
	v_bfe_u32 v13, v9, 16, 1
	v_bfe_u32 v17, v5, 16, 1
	v_add3_u32 v6, v6, v10, s29
	v_add3_u32 v8, v8, v12, s29
	v_add3_u32 v2, v2, v14, s29
	v_add3_u32 v10, v3, v15, s29
	v_add3_u32 v3, v4, v16, s29
	v_add3_u32 v7, v7, v11, s29
	v_add3_u32 v9, v9, v13, s29
	v_add3_u32 v5, v5, v17, s29
	v_lshrrev_b32_e32 v4, 16, v6
	v_lshrrev_b32_e32 v6, 16, v8
	v_lshrrev_b32_e32 v8, 16, v2
	v_lshrrev_b32_e32 v11, 16, v3
	v_and_or_b32 v2, v7, s30, v4
	v_and_or_b32 v3, v9, s30, v6
	v_and_or_b32 v4, v10, s30, v8
	v_and_or_b32 v5, v5, s30, v11
	global_store_dwordx4 v[34:35], v[2:5], off offset:3072
	s_branch .LBB0_170

; __device__ __forceinline__ unsigned pk2(float lo, float hi) { return f2bf(lo) | (f2bf(hi) << 16); }
; template <bool ZP, bool XF32, bool OUT8 = false>
; __device__ __forceinline__ void norm_phase(LAS unsigned char* lds, const void* xin, const float* gain, const float* sh, const float* sc, bf16* hout, const float* wzt, float* zout, int lane, int wave, int vcu, int G) {
;     ...
;         for (int r = 0; r < 2; ++r) { const int m = m0 + r, b = m >> 11;
;             const float rstd = rsqrtf(wave_sum(ss[r]) * (1.0f / D) + EPS);
; #pragma unroll
;             for (int j = 0; j < 4; ++j) { const int col = 512 * j + 8 * lane;
; #pragma unroll
;                 for (int q = 0; q < 2; ++q) { const f32x4 gg = *(const f32x4*)(gain + col + 4 * q), s1 = *(const f32x4*)(sc + (size_t)b * MODW + col + 4 * q), s0 = *(const f32x4*)(sh + (size_t)b * MODW + col + 4 * q);
;                     v[r][j][q] = (v[r][j][q] * rstd * gg) * (s1 + 1.0f) + s0; }
;                 if constexpr (OUT8) { *(v2u*)((unsigned char*)hout + (size_t)m * D + col) = pack8_fp8(v[r][j][0][0], v[r][j][0][1], v[r][j][0][2], v[r][j][0][3], v[r][j][1][0], v[r][j][1][1], v[r][j][1][2], v[r][j][1][3], FP8_ASCALE); }
;                 else { v4u o; o.x = pk2(v[r][j][0][0], v[r][j][0][1]); o.y = pk2(v[r][j][0][2], v[r][j][0][3]); o.z = pk2(v[r][j][1][0], v[r][j][1][1]); o.w = pk2(v[r][j][1][2], v[r][j][1][3]);
;                     *(v4u*)(hout + (size_t)m * D + col) = o; } }
.Lnorm_nt_LBB0_679:
	v_pk_add_f32 v[94:95], v[94:95], 1.0 op_sel_hi:[1,0]
	s_waitcnt lgkmcnt(0)
	v_pk_add_f32 v[112:113], v[112:113], v[114:115]
	ds_bpermute_b32 v115, v82, v113
	ds_bpermute_b32 v114, v82, v112
	v_cndmask_b32_e32 v82, v84, v91, vcc
	v_lshlrev_b32_e32 v82, 2, v82
	v_pk_add_f32 v[118:119], v[78:79], 1.0 op_sel_hi:[1,0]
	v_pk_add_f32 v[116:117], v[80:81], 1.0 op_sel_hi:[1,0]
	s_waitcnt lgkmcnt(0)
	v_pk_add_f32 v[112:113], v[112:113], v[114:115]
	ds_bpermute_b32 v115, v82, v113
	ds_bpermute_b32 v114, v82, v112
	v_pk_add_f32 v[92:93], v[92:93], 1.0 op_sel_hi:[1,0]
	v_mov_b32_e32 v121, v41
	v_pk_mov_b32 v[74:75], v[74:75], v[74:75] op_sel:[1,0]
	v_pk_mov_b32 v[76:77], v[76:77], v[76:77] op_sel:[1,0]
	s_waitcnt lgkmcnt(0)
	v_pk_add_f32 v[78:79], v[112:113], v[114:115]
	v_mov_b32_e32 v114, v55
	v_pk_fma_f32 v[78:79], v[78:79], s[6:7], v[16:17] op_sel_hi:[1,0,0]
	v_mov_b32_e32 v115, v59
	v_mul_f32_e32 v80, 0x4b800000, v79
	v_cmp_gt_f32_e32 vcc, s26, v79
	v_mov_b32_e32 v112, v65
	v_mov_b32_e32 v113, v67
	v_cndmask_b32_e32 v79, v79, v80, vcc
	v_rsq_f32_e32 v79, v79
	v_lshl_add_u64 v[80:81], v[14:15], 0, s[12:13]
	s_add_u32 s12, s7, s0
	s_addc_u32 s13, s18, s1
	v_mul_f32_e32 v82, 0x45800000, v79
	v_cndmask_b32_e32 v82, v79, v82, vcc
	v_pk_mul_f32 v[114:115], v[82:83], v[114:115] op_sel_hi:[0,1]
	v_pk_mul_f32 v[112:113], v[82:83], v[112:113] op_sel_hi:[0,1]
	v_pk_mul_f32 v[122:123], v[82:83], v[122:123] op_sel_hi:[0,1]
	v_pk_mul_f32 v[120:121], v[82:83], v[120:121] op_sel_hi:[0,1]
	v_pk_mul_f32 v[76:77], v[82:83], v[76:77] op_sel_hi:[0,1]
	v_cmp_gt_f32_e32 vcc, s26, v78
	v_mov_b32_e32 v65, v66
	v_pk_mul_f32 v[100:101], v[100:101], v[114:115]
	v_pk_mul_f32 v[102:103], v[102:103], v[112:113]
	v_pk_fma_f32 v[100:101], v[118:119], v[100:101], v[108:109]
	v_pk_fma_f32 v[102:103], v[116:117], v[102:103], v[110:111]
	v_mov_b32_e32 v108, v63
	v_mov_b32_e32 v109, v69
	v_mov_b32_e32 v110, v57
	v_mov_b32_e32 v111, v61
	v_pk_mul_f32 v[108:109], v[82:83], v[108:109] op_sel_hi:[0,1]
	v_pk_mul_f32 v[110:111], v[82:83], v[110:111] op_sel_hi:[0,1]
	v_pk_mul_f32 v[96:97], v[96:97], v[110:111]
	v_pk_mul_f32 v[98:99], v[98:99], v[108:109]
	v_pk_fma_f32 v[98:99], v[94:95], v[98:99], v[106:107]
	v_pk_fma_f32 v[94:95], v[92:93], v[96:97], v[104:105]
	v_cvt_pk_bf16_f32 v92, v100, v101
	v_cvt_pk_bf16_f32 v93, v102, v103
	v_cvt_pk_bf16_f32 v94, v94, v95
	v_cvt_pk_bf16_f32 v95, v98, v99
	global_store_dwordx4 v[80:81], v[92:95], off
	s_nop 1
	v_mov_b64_e32 v[92:93], v[152:153]
	v_mov_b64_e32 v[94:95], v[154:155]
	s_nop 0
	s_nop 1
	v_mov_b64_e32 v[96:97], v[156:157]
	v_mov_b64_e32 v[98:99], v[158:159]
	v_mov_b64_e32 v[100:101], v[160:161]
	v_mov_b64_e32 v[102:103], v[162:163]
	v_mov_b64_e32 v[104:105], v[164:165]
	v_mov_b64_e32 v[106:107], v[166:167]
	v_mov_b64_e32 v[108:109], v[168:169]
	v_mov_b64_e32 v[110:111], v[170:171]
	v_mov_b64_e32 v[112:113], v[172:173]
	v_mov_b64_e32 v[114:115], v[174:175]
	v_mov_b32_e32 v118, v43
	v_mov_b32_e32 v119, v27
	v_pk_mul_f32 v[118:119], v[82:83], v[118:119] op_sel_hi:[0,1]
	v_mov_b32_e32 v116, v47
	v_mov_b32_e32 v117, v49
	v_pk_mul_f32 v[116:117], v[82:83], v[116:117] op_sel_hi:[0,1]
	v_mov_b32_e32 v63, v68
	v_mov_b32_e32 v57, v60
	v_mov_b32_e32 v55, v58
	v_mov_b32_e32 v47, v48
	v_mov_b32_e32 v43, v26
	v_pk_mov_b32 v[2:3], v[2:3], v[2:3] op_sel:[1,0]
	v_pk_mov_b32 v[4:5], v[4:5], v[4:5] op_sel:[1,0]
	s_add_i32 s24, s24, 1
	s_addk_i32 s23, 0x200
	s_add_i32 s3, s3, -1
	s_cmp_eq_u32 s3, 0
	v_pk_mul_f32 v[92:93], v[92:93], v[118:119]
	v_pk_add_f32 v[96:97], v[96:97], 1.0 op_sel_hi:[1,0]
	v_pk_mul_f32 v[94:95], v[94:95], v[116:117]
	v_pk_fma_f32 v[92:93], v[96:97], v[92:93], v[100:101]
	v_pk_add_f32 v[98:99], v[98:99], 1.0 op_sel_hi:[1,0]
	v_pk_fma_f32 v[94:95], v[98:99], v[94:95], v[102:103]
	v_mov_b32_e32 v99, v31
	v_mov_b32_e32 v98, v45
	v_pk_mul_f32 v[98:99], v[82:83], v[98:99] op_sel_hi:[0,1]
	v_cvt_pk_bf16_f32 v92, v92, v93
	v_pk_mul_f32 v[98:99], v[104:105], v[98:99]
	v_pk_add_f32 v[102:103], v[108:109], 1.0 op_sel_hi:[1,0]
	v_mov_b32_e32 v96, v51
	v_mov_b32_e32 v97, v53
	v_pk_fma_f32 v[98:99], v[102:103], v[98:99], v[112:113]
	v_pk_mul_f32 v[96:97], v[82:83], v[96:97] op_sel_hi:[0,1]
	v_cvt_pk_bf16_f32 v93, v94, v95
	v_pk_mul_f32 v[96:97], v[106:107], v[96:97]
	v_pk_add_f32 v[100:101], v[110:111], 1.0 op_sel_hi:[1,0]
	v_pk_fma_f32 v[96:97], v[100:101], v[96:97], v[114:115]
	v_cvt_pk_bf16_f32 v94, v98, v99
	v_cvt_pk_bf16_f32 v95, v96, v97
	global_store_dwordx4 v[80:81], v[92:95], off offset:1024
	s_nop 1
	v_mov_b64_e32 v[92:93], v[176:177]
	v_mov_b64_e32 v[94:95], v[178:179]
	s_nop 0
	s_nop 1
	v_mov_b64_e32 v[96:97], v[180:181]
	v_mov_b64_e32 v[98:99], v[182:183]
	v_mov_b64_e32 v[100:101], v[184:185]
	v_mov_b64_e32 v[102:103], v[186:187]
	v_mov_b64_e32 v[104:105], v[188:189]
	v_mov_b64_e32 v[106:107], v[190:191]
	v_mov_b64_e32 v[108:109], v[192:193]
	v_mov_b64_e32 v[110:111], v[194:195]
	v_mov_b64_e32 v[112:113], v[196:197]
	v_mov_b64_e32 v[114:115], v[198:199]
	v_mov_b32_e32 v118, v23
	v_mov_b32_e32 v119, v25
	v_pk_mul_f32 v[118:119], v[82:83], v[118:119] op_sel_hi:[0,1]
	v_mov_b32_e32 v116, v29
	v_mov_b32_e32 v117, v33
	v_pk_mul_f32 v[116:117], v[82:83], v[116:117] op_sel_hi:[0,1]
	v_mov_b32_e32 v51, v52
	v_mov_b32_e32 v45, v30
	v_pk_mul_f32 v[92:93], v[92:93], v[118:119]
	v_pk_add_f32 v[96:97], v[96:97], 1.0 op_sel_hi:[1,0]
	v_pk_mul_f32 v[94:95], v[94:95], v[116:117]
	v_pk_add_f32 v[98:99], v[98:99], 1.0 op_sel_hi:[1,0]
	v_pk_fma_f32 v[92:93], v[96:97], v[92:93], v[108:109]
	v_pk_fma_f32 v[94:95], v[98:99], v[94:95], v[110:111]
	v_cvt_pk_bf16_f32 v92, v92, v93
	v_pk_mul_f32 v[100:101], v[100:101], v[122:123]
; __device__ __forceinline__ unsigned pk2(float lo, float hi) { return f2bf(lo) | (f2bf(hi) << 16); }
; template <bool ZP, bool XF32, bool OUT8 = false>
; __device__ __forceinline__ void norm_phase(LAS unsigned char* lds, const void* xin, const float* gain, const float* sh, const float* sc, bf16* hout, const float* wzt, float* zout, int lane, int wave, int vcu, int G) {
;     ...
;         for (int r = 0; r < 2; ++r) { const int m = m0 + r, b = m >> 11;
;             const float rstd = rsqrtf(wave_sum(ss[r]) * (1.0f / D) + EPS);
; #pragma unroll
;             for (int j = 0; j < 4; ++j) { const int col = 512 * j + 8 * lane;
; #pragma unroll
;                 for (int q = 0; q < 2; ++q) { const f32x4 gg = *(const f32x4*)(gain + col + 4 * q), s1 = *(const f32x4*)(sc + (size_t)b * MODW + col + 4 * q), s0 = *(const f32x4*)(sh + (size_t)b * MODW + col + 4 * q);
;                     v[r][j][q] = (v[r][j][q] * rstd * gg) * (s1 + 1.0f) + s0; }
;                 if constexpr (OUT8) { *(v2u*)((unsigned char*)hout + (size_t)m * D + col) = pack8_fp8(v[r][j][0][0], v[r][j][0][1], v[r][j][0][2], v[r][j][0][3], v[r][j][1][0], v[r][j][1][1], v[r][j][1][2], v[r][j][1][3], FP8_ASCALE); }
;                 else { v4u o; o.x = pk2(v[r][j][0][0], v[r][j][0][1]); o.y = pk2(v[r][j][0][2], v[r][j][0][3]); o.z = pk2(v[r][j][1][0], v[r][j][1][1]); o.w = pk2(v[r][j][1][2], v[r][j][1][3]);
;                     *(v4u*)(hout + (size_t)m * D + col) = o; } }
	v_pk_add_f32 v[104:105], v[104:105], 1.0 op_sel_hi:[1,0]
	v_pk_fma_f32 v[98:99], v[104:105], v[100:101], v[112:113]
	v_cvt_pk_bf16_f32 v93, v94, v95
	v_pk_mul_f32 v[102:103], v[102:103], v[120:121]
	v_pk_add_f32 v[106:107], v[106:107], 1.0 op_sel_hi:[1,0]
	v_pk_fma_f32 v[96:97], v[106:107], v[102:103], v[114:115]
	v_cvt_pk_bf16_f32 v94, v98, v99
	v_cvt_pk_bf16_f32 v95, v96, v97
	global_store_dwordx4 v[80:81], v[92:95], off offset:2048
	s_nop 1
	v_mov_b64_e32 v[92:93], v[200:201]
	v_mov_b64_e32 v[94:95], v[202:203]
	s_nop 0
	s_nop 1
	v_mov_b64_e32 v[96:97], v[204:205]
	v_mov_b64_e32 v[98:99], v[206:207]
	v_mov_b64_e32 v[100:101], v[208:209]
	v_mov_b64_e32 v[102:103], v[210:211]
	v_mov_b64_e32 v[104:105], v[212:213]
	v_mov_b64_e32 v[106:107], v[214:215]
	v_mov_b64_e32 v[108:109], v[216:217]
	v_mov_b64_e32 v[110:111], v[218:219]
	v_mov_b64_e32 v[112:113], v[220:221]
	v_mov_b64_e32 v[114:115], v[222:223]
	v_mov_b32_e32 v116, v71
	v_mov_b32_e32 v117, v70
	v_mov_b32_e32 v70, v73
	v_mov_b32_e32 v71, v72
	v_pk_mul_f32 v[72:73], v[82:83], v[74:75] op_sel_hi:[0,1]
	v_pk_mul_f32 v[74:75], v[82:83], v[116:117] op_sel_hi:[0,1]
	v_pk_mul_f32 v[70:71], v[82:83], v[70:71] op_sel_hi:[0,1]
	v_pk_mul_f32 v[74:75], v[74:75], v[92:93]
	v_pk_mul_f32 v[72:73], v[72:73], v[94:95]
	v_pk_add_f32 v[92:93], v[98:99], 1.0 op_sel_hi:[1,0]
	v_pk_add_f32 v[94:95], v[96:97], 1.0 op_sel_hi:[1,0]
	v_pk_mul_f32 v[70:71], v[70:71], v[100:101]
	v_pk_mul_f32 v[76:77], v[76:77], v[102:103]
	v_pk_add_f32 v[96:97], v[106:107], 1.0 op_sel_hi:[1,0]
	v_pk_add_f32 v[98:99], v[104:105], 1.0 op_sel_hi:[1,0]
	v_pk_fma_f32 v[72:73], v[72:73], v[92:93], v[110:111]
	v_pk_fma_f32 v[74:75], v[74:75], v[94:95], v[108:109]
	v_pk_fma_f32 v[76:77], v[76:77], v[96:97], v[114:115]
	v_pk_fma_f32 v[70:71], v[70:71], v[98:99], v[112:113]
	v_bfe_u32 v31, v70, 16, 1
	v_bfe_u32 v33, v71, 16, 1
	v_add3_u32 v31, v70, v31, s27
	v_add3_u32 v33, v71, v33, s27
	v_lshrrev_b32_e32 v31, 16, v31
	v_cvt_pk_bf16_f32 v70, v74, v75
	v_cvt_pk_bf16_f32 v71, v72, v73
	v_and_or_b32 v72, v33, s25, v31
	v_cvt_pk_bf16_f32 v73, v76, v77
	global_store_dwordx4 v[80:81], v[70:73], off offset:3072
	s_nop 1
	v_mov_b64_e32 v[72:73], v[140:141]
	v_mov_b64_e32 v[74:75], v[142:143]
	s_nop 0
	s_nop 1
	v_mov_b64_e32 v[92:93], v[132:133]
	v_mov_b64_e32 v[94:95], v[134:135]
	v_mov_b64_e32 v[96:97], v[136:137]
	v_mov_b64_e32 v[98:99], v[138:139]
	v_mov_b64_e32 v[100:101], v[128:129]
	v_mov_b64_e32 v[102:103], v[130:131]
	v_mov_b64_e32 v[104:105], v[148:149]
	v_mov_b64_e32 v[106:107], v[150:151]
	v_mov_b64_e32 v[108:109], v[144:145]
	v_mov_b64_e32 v[110:111], v[146:147]
	v_mul_f32_e32 v23, 0x4b800000, v78
	v_cndmask_b32_e32 v23, v78, v23, vcc
	v_rsq_f32_e32 v23, v23
	v_lshl_add_u64 v[70:71], v[14:15], 0, s[8:9]
	s_cselect_b64 s[8:9], -1, 0
	v_mul_f32_e32 v25, 0x45800000, v23
	v_cndmask_b32_e32 v58, v23, v25, vcc
	v_pk_mul_f32 v[60:61], v[58:59], v[64:65] op_sel_hi:[0,1]
	v_pk_mul_f32 v[54:55], v[58:59], v[54:55] op_sel_hi:[0,1]
	v_pk_mul_f32 v[62:63], v[58:59], v[62:63] op_sel_hi:[0,1]
	v_pk_mul_f32 v[56:57], v[58:59], v[56:57] op_sel_hi:[0,1]
	v_pk_mul_f32 v[44:45], v[58:59], v[44:45] op_sel_hi:[0,1]
	v_pk_mul_f32 v[2:3], v[58:59], v[2:3] op_sel_hi:[0,1]
	v_pk_mul_f32 v[4:5], v[58:59], v[4:5] op_sel_hi:[0,1]
	v_pk_add_f32 v[64:65], v[94:95], 1.0 op_sel_hi:[1,0]
	v_pk_mul_f32 v[54:55], v[72:73], v[54:55]
	v_pk_mul_f32 v[60:61], v[74:75], v[60:61]
	v_pk_add_f32 v[66:67], v[92:93], 1.0 op_sel_hi:[1,0]
	v_pk_mul_f32 v[56:57], v[96:97], v[56:57]
	v_pk_mul_f32 v[62:63], v[98:99], v[62:63]
	v_pk_add_f32 v[68:69], v[102:103], 1.0 op_sel_hi:[1,0]
	v_pk_add_f32 v[72:73], v[100:101], 1.0 op_sel_hi:[1,0]
	v_pk_fma_f32 v[60:61], v[64:65], v[60:61], v[106:107]
	v_pk_fma_f32 v[54:55], v[66:67], v[54:55], v[104:105]
	v_pk_fma_f32 v[62:63], v[68:69], v[62:63], v[110:111]
	v_pk_fma_f32 v[56:57], v[72:73], v[56:57], v[108:109]
	v_cvt_pk_bf16_f32 v54, v54, v55
	v_cvt_pk_bf16_f32 v55, v60, v61
	v_cvt_pk_bf16_f32 v56, v56, v57
	v_cvt_pk_bf16_f32 v57, v62, v63
	global_store_dwordx4 v[70:71], v[54:57], off
	s_nop 1
	v_mov_b64_e32 v[54:55], v[152:153]
	v_mov_b64_e32 v[56:57], v[154:155]
	s_nop 0
	s_nop 1
	v_mov_b64_e32 v[60:61], v[156:157]
	v_mov_b64_e32 v[62:63], v[158:159]
	v_mov_b64_e32 v[64:65], v[164:165]
	v_mov_b64_e32 v[66:67], v[166:167]
	v_mov_b64_e32 v[72:73], v[168:169]
	v_mov_b64_e32 v[74:75], v[170:171]
	v_mov_b64_e32 v[76:77], v[160:161]
	v_mov_b64_e32 v[78:79], v[162:163]
	v_mov_b64_e32 v[92:93], v[172:173]
	v_mov_b64_e32 v[94:95], v[174:175]
	v_pk_mul_f32 v[26:27], v[58:59], v[46:47] op_sel_hi:[0,1]
	v_pk_mul_f32 v[30:31], v[58:59], v[42:43] op_sel_hi:[0,1]
	v_pk_mul_f32 v[42:43], v[58:59], v[50:51] op_sel_hi:[0,1]
	v_pk_mul_f32 v[30:31], v[54:55], v[30:31]
	v_pk_mul_f32 v[26:27], v[56:57], v[26:27]
	v_pk_add_f32 v[46:47], v[62:63], 1.0 op_sel_hi:[1,0]
	v_pk_add_f32 v[48:49], v[60:61], 1.0 op_sel_hi:[1,0]
	v_pk_mul_f32 v[44:45], v[64:65], v[44:45]
	v_pk_mul_f32 v[42:43], v[66:67], v[42:43]
	v_pk_add_f32 v[50:51], v[74:75], 1.0 op_sel_hi:[1,0]
	v_pk_add_f32 v[52:53], v[72:73], 1.0 op_sel_hi:[1,0]
; __device__ __forceinline__ unsigned pk2(float lo, float hi) { return f2bf(lo) | (f2bf(hi) << 16); }
; template <bool ZP, bool XF32, bool OUT8 = false>
; __device__ __forceinline__ void norm_phase(LAS unsigned char* lds, const void* xin, const float* gain, const float* sh, const float* sc, bf16* hout, const float* wzt, float* zout, int lane, int wave, int vcu, int G) {
;     ...
;         for (int r = 0; r < 2; ++r) { const int m = m0 + r, b = m >> 11;
;             const float rstd = rsqrtf(wave_sum(ss[r]) * (1.0f / D) + EPS);
; #pragma unroll
;             for (int j = 0; j < 4; ++j) { const int col = 512 * j + 8 * lane;
; #pragma unroll
;                 for (int q = 0; q < 2; ++q) { const f32x4 gg = *(const f32x4*)(gain + col + 4 * q), s1 = *(const f32x4*)(sc + (size_t)b * MODW + col + 4 * q), s0 = *(const f32x4*)(sh + (size_t)b * MODW + col + 4 * q);
;                     v[r][j][q] = (v[r][j][q] * rstd * gg) * (s1 + 1.0f) + s0; }
;                 if constexpr (OUT8) { *(v2u*)((unsigned char*)hout + (size_t)m * D + col) = pack8_fp8(v[r][j][0][0], v[r][j][0][1], v[r][j][0][2], v[r][j][0][3], v[r][j][1][0], v[r][j][1][1], v[r][j][1][2], v[r][j][1][3], FP8_ASCALE); }
;                 else { v4u o; o.x = pk2(v[r][j][0][0], v[r][j][0][1]); o.y = pk2(v[r][j][0][2], v[r][j][0][3]); o.z = pk2(v[r][j][1][0], v[r][j][1][1]); o.w = pk2(v[r][j][1][2], v[r][j][1][3]);
;                     *(v4u*)(hout + (size_t)m * D + col) = o; } }
	v_pk_fma_f32 v[26:27], v[46:47], v[26:27], v[78:79]
	v_pk_fma_f32 v[30:31], v[48:49], v[30:31], v[76:77]
	v_pk_fma_f32 v[42:43], v[50:51], v[42:43], v[94:95]
	v_pk_fma_f32 v[44:45], v[52:53], v[44:45], v[92:93]
	v_bfe_u32 v23, v30, 16, 1
	v_bfe_u32 v25, v31, 16, 1
	v_bfe_u32 v29, v26, 16, 1
	v_bfe_u32 v39, v42, 16, 1
	v_bfe_u32 v33, v27, 16, 1
	v_bfe_u32 v41, v43, 16, 1
	v_add3_u32 v23, v30, v23, s27
	v_add3_u32 v25, v31, v25, s27
	v_add3_u32 v26, v26, v29, s27
	v_add3_u32 v31, v42, v39, s27
	v_add3_u32 v27, v27, v33, s27
	v_add3_u32 v33, v43, v41, s27
	v_lshrrev_b32_e32 v23, 16, v23
	v_lshrrev_b32_e32 v26, 16, v26
	v_lshrrev_b32_e32 v31, 16, v31
	v_and_or_b32 v42, v25, s25, v23
	v_and_or_b32 v43, v27, s25, v26
	v_cvt_pk_bf16_f32 v44, v44, v45
	v_and_or_b32 v45, v33, s25, v31
	global_store_dwordx4 v[70:71], v[42:45], off offset:1024
	s_nop 1
	v_mov_b64_e32 v[42:43], v[176:177]
	v_mov_b64_e32 v[44:45], v[178:179]
	s_nop 0
	s_nop 1
	v_mov_b64_e32 v[46:47], v[180:181]
	v_mov_b64_e32 v[48:49], v[182:183]
	v_mov_b64_e32 v[50:51], v[184:185]
	v_mov_b64_e32 v[52:53], v[186:187]
	v_mov_b64_e32 v[54:55], v[188:189]
	v_mov_b64_e32 v[56:57], v[190:191]
	v_mov_b64_e32 v[60:61], v[192:193]
	v_mov_b64_e32 v[62:63], v[194:195]
	v_mov_b64_e32 v[64:65], v[196:197]
	v_mov_b64_e32 v[66:67], v[198:199]
	v_mov_b32_e32 v39, v40
	v_mov_b32_e32 v35, v36
	v_mov_b32_e32 v29, v32
	v_mov_b32_e32 v23, v24
	v_pk_mul_f32 v[24:25], v[58:59], v[28:29] op_sel_hi:[0,1]
	v_pk_mul_f32 v[22:23], v[58:59], v[22:23] op_sel_hi:[0,1]
	v_pk_mul_f32 v[26:27], v[58:59], v[38:39] op_sel_hi:[0,1]
	v_pk_mul_f32 v[28:29], v[58:59], v[34:35] op_sel_hi:[0,1]
	v_pk_mul_f32 v[22:23], v[22:23], v[42:43]
	v_pk_mul_f32 v[24:25], v[24:25], v[44:45]
	v_pk_add_f32 v[30:31], v[48:49], 1.0 op_sel_hi:[1,0]
	v_pk_add_f32 v[32:33], v[46:47], 1.0 op_sel_hi:[1,0]
	v_pk_mul_f32 v[28:29], v[28:29], v[50:51]
	v_pk_mul_f32 v[26:27], v[26:27], v[52:53]
	v_pk_add_f32 v[34:35], v[56:57], 1.0 op_sel_hi:[1,0]
	v_pk_add_f32 v[36:37], v[54:55], 1.0 op_sel_hi:[1,0]
	v_pk_fma_f32 v[24:25], v[24:25], v[30:31], v[62:63]
	v_pk_fma_f32 v[22:23], v[22:23], v[32:33], v[60:61]
	v_pk_fma_f32 v[26:27], v[26:27], v[34:35], v[66:67]
	v_pk_fma_f32 v[28:29], v[28:29], v[36:37], v[64:65]
	v_bfe_u32 v30, v22, 16, 1
	v_bfe_u32 v32, v24, 16, 1
	v_bfe_u32 v34, v28, 16, 1
	v_bfe_u32 v36, v26, 16, 1
	v_bfe_u32 v31, v23, 16, 1
	v_bfe_u32 v33, v25, 16, 1
	v_bfe_u32 v35, v29, 16, 1
	v_bfe_u32 v37, v27, 16, 1
	v_add3_u32 v22, v22, v30, s27
	v_add3_u32 v24, v24, v32, s27
	v_add3_u32 v28, v28, v34, s27
	v_add3_u32 v26, v26, v36, s27
	v_add3_u32 v23, v23, v31, s27
	v_add3_u32 v25, v25, v33, s27
	v_add3_u32 v29, v29, v35, s27
	v_add3_u32 v27, v27, v37, s27
	v_lshrrev_b32_e32 v22, 16, v22
	v_lshrrev_b32_e32 v24, 16, v24
	v_lshrrev_b32_e32 v28, 16, v28
	v_lshrrev_b32_e32 v26, 16, v26
	v_and_or_b32 v22, v23, s25, v22
	v_and_or_b32 v23, v25, s25, v24
	v_and_or_b32 v24, v29, s25, v28
	v_and_or_b32 v25, v27, s25, v26
	global_store_dwordx4 v[70:71], v[22:25], off offset:2048
	s_nop 1
	v_mov_b64_e32 v[22:23], v[200:201]
	v_mov_b64_e32 v[24:25], v[202:203]
	s_nop 0
	s_nop 1
	v_mov_b64_e32 v[26:27], v[204:205]
	v_mov_b64_e32 v[28:29], v[206:207]
	v_mov_b64_e32 v[30:31], v[208:209]
	v_mov_b64_e32 v[32:33], v[210:211]
	v_mov_b64_e32 v[34:35], v[212:213]
	v_mov_b64_e32 v[36:37], v[214:215]
	v_mov_b64_e32 v[38:39], v[216:217]
	v_mov_b64_e32 v[40:41], v[218:219]
	v_mov_b64_e32 v[42:43], v[220:221]
	v_mov_b64_e32 v[44:45], v[222:223]
	v_mov_b32_e32 v46, v21
	v_mov_b32_e32 v47, v20
	v_mov_b32_e32 v20, v19
	v_mov_b32_e32 v21, v18
	v_pk_mul_f32 v[18:19], v[58:59], v[46:47] op_sel_hi:[0,1]
	v_pk_mul_f32 v[20:21], v[58:59], v[20:21] op_sel_hi:[0,1]
	v_pk_mul_f32 v[18:19], v[18:19], v[22:23]
	v_pk_mul_f32 v[2:3], v[2:3], v[24:25]
	v_pk_add_f32 v[22:23], v[28:29], 1.0 op_sel_hi:[1,0]
	v_pk_add_f32 v[24:25], v[26:27], 1.0 op_sel_hi:[1,0]
	v_pk_mul_f32 v[20:21], v[20:21], v[30:31]
	v_pk_mul_f32 v[4:5], v[4:5], v[32:33]
	v_pk_add_f32 v[26:27], v[36:37], 1.0 op_sel_hi:[1,0]
	v_pk_add_f32 v[28:29], v[34:35], 1.0 op_sel_hi:[1,0]
	v_pk_fma_f32 v[2:3], v[2:3], v[22:23], v[40:41]
	v_pk_fma_f32 v[18:19], v[18:19], v[24:25], v[38:39]
	v_pk_fma_f32 v[4:5], v[4:5], v[26:27], v[44:45]
	v_pk_fma_f32 v[20:21], v[20:21], v[28:29], v[42:43]
	v_bfe_u32 v22, v18, 16, 1
	v_bfe_u32 v24, v2, 16, 1
	v_bfe_u32 v26, v20, 16, 1
	v_bfe_u32 v28, v4, 16, 1
	v_bfe_u32 v23, v19, 16, 1
	v_bfe_u32 v25, v3, 16, 1
	v_bfe_u32 v27, v21, 16, 1
	v_bfe_u32 v29, v5, 16, 1
	v_add3_u32 v18, v18, v22, s27
	v_add3_u32 v2, v2, v24, s27
	v_add3_u32 v20, v20, v26, s27
	v_add3_u32 v4, v4, v28, s27
	v_add3_u32 v19, v19, v23, s27
	v_add3_u32 v3, v3, v25, s27
	v_add3_u32 v21, v21, v27, s27
	v_add3_u32 v5, v5, v29, s27
	v_lshrrev_b32_e32 v18, 16, v18
	v_lshrrev_b32_e32 v22, 16, v2
	v_lshrrev_b32_e32 v20, 16, v20
	v_lshrrev_b32_e32 v23, 16, v4
	v_and_or_b32 v2, v19, s25, v18
	v_and_or_b32 v3, v3, s25, v22
	v_and_or_b32 v4, v21, s25, v20
	v_and_or_b32 v5, v5, s25, v23
	global_store_dwordx4 v[70:71], v[2:5], off offset:3072
	s_branch .LBB0_678

; __device__ __forceinline__ unsigned pk2(float lo, float hi) { return f2bf(lo) | (f2bf(hi) << 16); }
; template <bool ZP, bool XF32, bool OUT8 = false>
; __device__ __forceinline__ void norm_phase(LAS unsigned char* lds, const void* xin, const float* gain, const float* sh, const float* sc, bf16* hout, const float* wzt, float* zout, int lane, int wave, int vcu, int G) {
;     ...
;         for (int r = 0; r < 2; ++r) { const int m = m0 + r, b = m >> 11;
;             const float rstd = rsqrtf(wave_sum(ss[r]) * (1.0f / D) + EPS);
; #pragma unroll
;             for (int j = 0; j < 4; ++j) { const int col = 512 * j + 8 * lane;
; #pragma unroll
;                 for (int q = 0; q < 2; ++q) { const f32x4 gg = *(const f32x4*)(gain + col + 4 * q), s1 = *(const f32x4*)(sc + (size_t)b * MODW + col + 4 * q), s0 = *(const f32x4*)(sh + (size_t)b * MODW + col + 4 * q);
;                     v[r][j][q] = (v[r][j][q] * rstd * gg) * (s1 + 1.0f) + s0; }
;                 if constexpr (OUT8) { *(v2u*)((unsigned char*)hout + (size_t)m * D + col) = pack8_fp8(v[r][j][0][0], v[r][j][0][1], v[r][j][0][2], v[r][j][0][3], v[r][j][1][0], v[r][j][1][1], v[r][j][1][2], v[r][j][1][3], FP8_ASCALE); }
;                 else { v4u o; o.x = pk2(v[r][j][0][0], v[r][j][0][1]); o.y = pk2(v[r][j][0][2], v[r][j][0][3]); o.z = pk2(v[r][j][1][0], v[r][j][1][1]); o.w = pk2(v[r][j][1][2], v[r][j][1][3]);
;                     *(v4u*)(hout + (size_t)m * D + col) = o; } }
.Lnorm_nt_LBB0_937:
	v_pk_add_f32 v[96:97], v[96:97], 1.0 op_sel_hi:[1,0]
	s_waitcnt lgkmcnt(0)
	v_pk_add_f32 v[114:115], v[114:115], v[116:117]
	ds_bpermute_b32 v117, v84, v115
	ds_bpermute_b32 v116, v84, v114
	v_cndmask_b32_e32 v84, v86, v93, vcc
	v_lshlrev_b32_e32 v84, 2, v84
	v_pk_add_f32 v[120:121], v[80:81], 1.0 op_sel_hi:[1,0]
	v_pk_add_f32 v[118:119], v[82:83], 1.0 op_sel_hi:[1,0]
	s_waitcnt lgkmcnt(0)
	v_pk_add_f32 v[114:115], v[114:115], v[116:117]
	ds_bpermute_b32 v117, v84, v115
	ds_bpermute_b32 v116, v84, v114
	v_pk_add_f32 v[94:95], v[94:95], 1.0 op_sel_hi:[1,0]
	v_mov_b32_e32 v123, v43
	v_pk_mov_b32 v[76:77], v[76:77], v[76:77] op_sel:[1,0]
	v_pk_mov_b32 v[78:79], v[78:79], v[78:79] op_sel:[1,0]
	s_waitcnt lgkmcnt(0)
	v_pk_add_f32 v[80:81], v[114:115], v[116:117]
	v_mov_b32_e32 v116, v57
	v_pk_fma_f32 v[80:81], v[80:81], s[6:7], v[18:19] op_sel_hi:[1,0,0]
	v_mov_b32_e32 v117, v61
	v_mul_f32_e32 v82, 0x4b800000, v81
	v_cmp_gt_f32_e32 vcc, s26, v81
	v_mov_b32_e32 v114, v67
	v_mov_b32_e32 v115, v69
	v_cndmask_b32_e32 v81, v81, v82, vcc
	v_rsq_f32_e32 v81, v81
	v_lshl_add_u64 v[82:83], v[16:17], 0, s[12:13]
	s_add_u32 s12, s7, s0
	s_addc_u32 s13, s18, s1
	v_mul_f32_e32 v84, 0x45800000, v81
	v_cndmask_b32_e32 v84, v81, v84, vcc
	v_pk_mul_f32 v[116:117], v[84:85], v[116:117] op_sel_hi:[0,1]
	v_pk_mul_f32 v[114:115], v[84:85], v[114:115] op_sel_hi:[0,1]
	v_pk_mul_f32 v[124:125], v[84:85], v[124:125] op_sel_hi:[0,1]
	v_pk_mul_f32 v[122:123], v[84:85], v[122:123] op_sel_hi:[0,1]
	v_pk_mul_f32 v[78:79], v[84:85], v[78:79] op_sel_hi:[0,1]
	v_cmp_gt_f32_e32 vcc, s26, v80
	v_mov_b32_e32 v67, v68
	v_pk_mul_f32 v[102:103], v[102:103], v[116:117]
	v_pk_mul_f32 v[104:105], v[104:105], v[114:115]
	v_pk_fma_f32 v[102:103], v[120:121], v[102:103], v[110:111]
	v_pk_fma_f32 v[104:105], v[118:119], v[104:105], v[112:113]
	v_mov_b32_e32 v110, v65
	v_mov_b32_e32 v111, v71
	v_mov_b32_e32 v112, v59
	v_mov_b32_e32 v113, v63
	v_pk_mul_f32 v[110:111], v[84:85], v[110:111] op_sel_hi:[0,1]
	v_pk_mul_f32 v[112:113], v[84:85], v[112:113] op_sel_hi:[0,1]
	v_pk_mul_f32 v[98:99], v[98:99], v[112:113]
	v_pk_mul_f32 v[100:101], v[100:101], v[110:111]
	v_pk_fma_f32 v[100:101], v[96:97], v[100:101], v[108:109]
	v_pk_fma_f32 v[96:97], v[94:95], v[98:99], v[106:107]
	v_cvt_pk_bf16_f32 v94, v102, v103
	v_cvt_pk_bf16_f32 v95, v104, v105
	v_cvt_pk_bf16_f32 v96, v96, v97
	v_cvt_pk_bf16_f32 v97, v100, v101
	global_store_dwordx4 v[82:83], v[94:97], off
	s_nop 1
	v_mov_b64_e32 v[94:95], v[152:153]
	v_mov_b64_e32 v[96:97], v[154:155]
	s_nop 0
	s_nop 1
	v_mov_b64_e32 v[98:99], v[156:157]
	v_mov_b64_e32 v[100:101], v[158:159]
	v_mov_b64_e32 v[102:103], v[160:161]
	v_mov_b64_e32 v[104:105], v[162:163]
	v_mov_b64_e32 v[106:107], v[164:165]
	v_mov_b64_e32 v[108:109], v[166:167]
	v_mov_b64_e32 v[110:111], v[168:169]
	v_mov_b64_e32 v[112:113], v[170:171]
	v_mov_b64_e32 v[114:115], v[172:173]
	v_mov_b64_e32 v[116:117], v[174:175]
	v_mov_b32_e32 v120, v45
	v_mov_b32_e32 v121, v29
	v_pk_mul_f32 v[120:121], v[84:85], v[120:121] op_sel_hi:[0,1]
	v_mov_b32_e32 v118, v49
	v_mov_b32_e32 v119, v51
	v_pk_mul_f32 v[118:119], v[84:85], v[118:119] op_sel_hi:[0,1]
	v_mov_b32_e32 v65, v70
	v_mov_b32_e32 v59, v62
	v_mov_b32_e32 v57, v60
	v_mov_b32_e32 v49, v50
	v_mov_b32_e32 v45, v28
	v_pk_mov_b32 v[2:3], v[2:3], v[2:3] op_sel:[1,0]
	v_pk_mov_b32 v[4:5], v[4:5], v[4:5] op_sel:[1,0]
	s_add_i32 s24, s24, 1
	s_addk_i32 s23, 0x200
	s_add_i32 s3, s3, -1
	s_cmp_eq_u32 s3, 0
	v_pk_mul_f32 v[94:95], v[94:95], v[120:121]
	v_pk_add_f32 v[98:99], v[98:99], 1.0 op_sel_hi:[1,0]
	v_pk_mul_f32 v[96:97], v[96:97], v[118:119]
	v_pk_fma_f32 v[94:95], v[98:99], v[94:95], v[102:103]
	v_pk_add_f32 v[100:101], v[100:101], 1.0 op_sel_hi:[1,0]
	v_pk_fma_f32 v[96:97], v[100:101], v[96:97], v[104:105]
	v_mov_b32_e32 v101, v33
	v_mov_b32_e32 v100, v47
	v_pk_mul_f32 v[100:101], v[84:85], v[100:101] op_sel_hi:[0,1]
	v_cvt_pk_bf16_f32 v94, v94, v95
	v_pk_mul_f32 v[100:101], v[106:107], v[100:101]
	v_pk_add_f32 v[104:105], v[110:111], 1.0 op_sel_hi:[1,0]
	v_mov_b32_e32 v98, v53
	v_mov_b32_e32 v99, v55
	v_pk_fma_f32 v[100:101], v[104:105], v[100:101], v[114:115]
	v_pk_mul_f32 v[98:99], v[84:85], v[98:99] op_sel_hi:[0,1]
	v_cvt_pk_bf16_f32 v95, v96, v97
	v_pk_mul_f32 v[98:99], v[108:109], v[98:99]
	v_pk_add_f32 v[102:103], v[112:113], 1.0 op_sel_hi:[1,0]
	v_pk_fma_f32 v[98:99], v[102:103], v[98:99], v[116:117]
	v_cvt_pk_bf16_f32 v96, v100, v101
	v_cvt_pk_bf16_f32 v97, v98, v99
	global_store_dwordx4 v[82:83], v[94:97], off offset:1024
	s_nop 1
	v_mov_b64_e32 v[94:95], v[176:177]
	v_mov_b64_e32 v[96:97], v[178:179]
	s_nop 0
	s_nop 1
	v_mov_b64_e32 v[98:99], v[180:181]
	v_mov_b64_e32 v[100:101], v[182:183]
	v_mov_b64_e32 v[102:103], v[184:185]
	v_mov_b64_e32 v[104:105], v[186:187]
	v_mov_b64_e32 v[106:107], v[188:189]
	v_mov_b64_e32 v[108:109], v[190:191]
	v_mov_b64_e32 v[110:111], v[192:193]
	v_mov_b64_e32 v[112:113], v[194:195]
	v_mov_b64_e32 v[114:115], v[196:197]
	v_mov_b64_e32 v[116:117], v[198:199]
	v_mov_b32_e32 v120, v25
	v_mov_b32_e32 v121, v27
	v_pk_mul_f32 v[120:121], v[84:85], v[120:121] op_sel_hi:[0,1]
	v_mov_b32_e32 v118, v31
	v_mov_b32_e32 v119, v35
	v_pk_mul_f32 v[118:119], v[84:85], v[118:119] op_sel_hi:[0,1]
	v_mov_b32_e32 v53, v54
	v_mov_b32_e32 v47, v32
	v_pk_mul_f32 v[94:95], v[94:95], v[120:121]
	v_pk_add_f32 v[98:99], v[98:99], 1.0 op_sel_hi:[1,0]
	v_pk_mul_f32 v[96:97], v[96:97], v[118:119]
	v_pk_add_f32 v[100:101], v[100:101], 1.0 op_sel_hi:[1,0]
	v_pk_fma_f32 v[94:95], v[98:99], v[94:95], v[110:111]
	v_pk_fma_f32 v[96:97], v[100:101], v[96:97], v[112:113]
	v_cvt_pk_bf16_f32 v94, v94, v95
; __device__ __forceinline__ unsigned pk2(float lo, float hi) { return f2bf(lo) | (f2bf(hi) << 16); }
; template <bool ZP, bool XF32, bool OUT8 = false>
; __device__ __forceinline__ void norm_phase(LAS unsigned char* lds, const void* xin, const float* gain, const float* sh, const float* sc, bf16* hout, const float* wzt, float* zout, int lane, int wave, int vcu, int G) {
;     ...
;         for (int r = 0; r < 2; ++r) { const int m = m0 + r, b = m >> 11;
;             const float rstd = rsqrtf(wave_sum(ss[r]) * (1.0f / D) + EPS);
; #pragma unroll
;             for (int j = 0; j < 4; ++j) { const int col = 512 * j + 8 * lane;
; #pragma unroll
;                 for (int q = 0; q < 2; ++q) { const f32x4 gg = *(const f32x4*)(gain + col + 4 * q), s1 = *(const f32x4*)(sc + (size_t)b * MODW + col + 4 * q), s0 = *(const f32x4*)(sh + (size_t)b * MODW + col + 4 * q);
;                     v[r][j][q] = (v[r][j][q] * rstd * gg) * (s1 + 1.0f) + s0; }
;                 if constexpr (OUT8) { *(v2u*)((unsigned char*)hout + (size_t)m * D + col) = pack8_fp8(v[r][j][0][0], v[r][j][0][1], v[r][j][0][2], v[r][j][0][3], v[r][j][1][0], v[r][j][1][1], v[r][j][1][2], v[r][j][1][3], FP8_ASCALE); }
;                 else { v4u o; o.x = pk2(v[r][j][0][0], v[r][j][0][1]); o.y = pk2(v[r][j][0][2], v[r][j][0][3]); o.z = pk2(v[r][j][1][0], v[r][j][1][1]); o.w = pk2(v[r][j][1][2], v[r][j][1][3]);
;                     *(v4u*)(hout + (size_t)m * D + col) = o; } }
	v_pk_mul_f32 v[102:103], v[102:103], v[124:125]
	v_pk_add_f32 v[106:107], v[106:107], 1.0 op_sel_hi:[1,0]
	v_pk_fma_f32 v[100:101], v[106:107], v[102:103], v[114:115]
	v_cvt_pk_bf16_f32 v95, v96, v97
	v_pk_mul_f32 v[104:105], v[104:105], v[122:123]
	v_pk_add_f32 v[108:109], v[108:109], 1.0 op_sel_hi:[1,0]
	v_pk_fma_f32 v[98:99], v[108:109], v[104:105], v[116:117]
	v_cvt_pk_bf16_f32 v96, v100, v101
	v_cvt_pk_bf16_f32 v97, v98, v99
	global_store_dwordx4 v[82:83], v[94:97], off offset:2048
	s_nop 1
	v_mov_b64_e32 v[94:95], v[200:201]
	v_mov_b64_e32 v[96:97], v[202:203]
	s_nop 0
	s_nop 1
	v_mov_b64_e32 v[98:99], v[204:205]
	v_mov_b64_e32 v[100:101], v[206:207]
	v_mov_b64_e32 v[102:103], v[208:209]
	v_mov_b64_e32 v[104:105], v[210:211]
	v_mov_b64_e32 v[106:107], v[212:213]
	v_mov_b64_e32 v[108:109], v[214:215]
	v_mov_b64_e32 v[110:111], v[216:217]
	v_mov_b64_e32 v[112:113], v[218:219]
	v_mov_b64_e32 v[114:115], v[220:221]
	v_mov_b64_e32 v[116:117], v[222:223]
	v_mov_b32_e32 v118, v73
	v_mov_b32_e32 v119, v72
	v_mov_b32_e32 v72, v75
	v_mov_b32_e32 v73, v74
	v_pk_mul_f32 v[74:75], v[84:85], v[76:77] op_sel_hi:[0,1]
	v_pk_mul_f32 v[76:77], v[84:85], v[118:119] op_sel_hi:[0,1]
	v_pk_mul_f32 v[72:73], v[84:85], v[72:73] op_sel_hi:[0,1]
	v_pk_mul_f32 v[76:77], v[76:77], v[94:95]
	v_pk_mul_f32 v[74:75], v[74:75], v[96:97]
	v_pk_add_f32 v[94:95], v[100:101], 1.0 op_sel_hi:[1,0]
	v_pk_add_f32 v[96:97], v[98:99], 1.0 op_sel_hi:[1,0]
	v_pk_mul_f32 v[72:73], v[72:73], v[102:103]
	v_pk_mul_f32 v[78:79], v[78:79], v[104:105]
	v_pk_add_f32 v[98:99], v[108:109], 1.0 op_sel_hi:[1,0]
	v_pk_add_f32 v[100:101], v[106:107], 1.0 op_sel_hi:[1,0]
	v_pk_fma_f32 v[74:75], v[74:75], v[94:95], v[112:113]
	v_pk_fma_f32 v[76:77], v[76:77], v[96:97], v[110:111]
	v_pk_fma_f32 v[78:79], v[78:79], v[98:99], v[116:117]
	v_pk_fma_f32 v[72:73], v[72:73], v[100:101], v[114:115]
	v_bfe_u32 v33, v72, 16, 1
	v_bfe_u32 v35, v73, 16, 1
	v_add3_u32 v33, v72, v33, s27
	v_add3_u32 v35, v73, v35, s27
	v_lshrrev_b32_e32 v33, 16, v33
	v_cvt_pk_bf16_f32 v72, v76, v77
	v_cvt_pk_bf16_f32 v73, v74, v75
	v_and_or_b32 v74, v35, s25, v33
	v_cvt_pk_bf16_f32 v75, v78, v79
	global_store_dwordx4 v[82:83], v[72:75], off offset:3072
	s_nop 1
	v_mov_b64_e32 v[74:75], v[140:141]
	v_mov_b64_e32 v[76:77], v[142:143]
	s_nop 0
	s_nop 1
	v_mov_b64_e32 v[94:95], v[132:133]
	v_mov_b64_e32 v[96:97], v[134:135]
	v_mov_b64_e32 v[98:99], v[136:137]
	v_mov_b64_e32 v[100:101], v[138:139]
	v_mov_b64_e32 v[102:103], v[128:129]
	v_mov_b64_e32 v[104:105], v[130:131]
	v_mov_b64_e32 v[106:107], v[148:149]
	v_mov_b64_e32 v[108:109], v[150:151]
	v_mov_b64_e32 v[110:111], v[144:145]
	v_mov_b64_e32 v[112:113], v[146:147]
	v_mul_f32_e32 v25, 0x4b800000, v80
	v_cndmask_b32_e32 v25, v80, v25, vcc
	v_rsq_f32_e32 v25, v25
	v_lshl_add_u64 v[72:73], v[16:17], 0, s[8:9]
	s_cselect_b64 s[8:9], -1, 0
	v_mul_f32_e32 v27, 0x45800000, v25
	v_cndmask_b32_e32 v60, v25, v27, vcc
	v_pk_mul_f32 v[62:63], v[60:61], v[66:67] op_sel_hi:[0,1]
	v_pk_mul_f32 v[56:57], v[60:61], v[56:57] op_sel_hi:[0,1]
	v_pk_mul_f32 v[64:65], v[60:61], v[64:65] op_sel_hi:[0,1]
	v_pk_mul_f32 v[58:59], v[60:61], v[58:59] op_sel_hi:[0,1]
	v_pk_mul_f32 v[46:47], v[60:61], v[46:47] op_sel_hi:[0,1]
	v_pk_mul_f32 v[2:3], v[60:61], v[2:3] op_sel_hi:[0,1]
	v_pk_mul_f32 v[4:5], v[60:61], v[4:5] op_sel_hi:[0,1]
	v_pk_add_f32 v[66:67], v[96:97], 1.0 op_sel_hi:[1,0]
	v_pk_mul_f32 v[56:57], v[74:75], v[56:57]
	v_pk_mul_f32 v[62:63], v[76:77], v[62:63]
	v_pk_add_f32 v[68:69], v[94:95], 1.0 op_sel_hi:[1,0]
	v_pk_mul_f32 v[58:59], v[98:99], v[58:59]
	v_pk_mul_f32 v[64:65], v[100:101], v[64:65]
	v_pk_add_f32 v[70:71], v[104:105], 1.0 op_sel_hi:[1,0]
	v_pk_add_f32 v[74:75], v[102:103], 1.0 op_sel_hi:[1,0]
	v_pk_fma_f32 v[62:63], v[66:67], v[62:63], v[108:109]
	v_pk_fma_f32 v[56:57], v[68:69], v[56:57], v[106:107]
	v_pk_fma_f32 v[64:65], v[70:71], v[64:65], v[112:113]
	v_pk_fma_f32 v[58:59], v[74:75], v[58:59], v[110:111]
	v_cvt_pk_bf16_f32 v56, v56, v57
	v_cvt_pk_bf16_f32 v57, v62, v63
	v_cvt_pk_bf16_f32 v58, v58, v59
	v_cvt_pk_bf16_f32 v59, v64, v65
	global_store_dwordx4 v[72:73], v[56:59], off
	s_nop 1
	v_mov_b64_e32 v[56:57], v[152:153]
	v_mov_b64_e32 v[58:59], v[154:155]
	s_nop 0
	s_nop 1
	v_mov_b64_e32 v[62:63], v[156:157]
	v_mov_b64_e32 v[64:65], v[158:159]
	v_mov_b64_e32 v[66:67], v[164:165]
	v_mov_b64_e32 v[68:69], v[166:167]
	v_mov_b64_e32 v[74:75], v[168:169]
	v_mov_b64_e32 v[76:77], v[170:171]
	v_mov_b64_e32 v[78:79], v[160:161]
	v_mov_b64_e32 v[80:81], v[162:163]
	v_mov_b64_e32 v[94:95], v[172:173]
	v_mov_b64_e32 v[96:97], v[174:175]
	v_pk_mul_f32 v[28:29], v[60:61], v[48:49] op_sel_hi:[0,1]
	v_pk_mul_f32 v[32:33], v[60:61], v[44:45] op_sel_hi:[0,1]
	v_pk_mul_f32 v[44:45], v[60:61], v[52:53] op_sel_hi:[0,1]
	v_pk_mul_f32 v[32:33], v[56:57], v[32:33]
	v_pk_mul_f32 v[28:29], v[58:59], v[28:29]
	v_pk_add_f32 v[48:49], v[64:65], 1.0 op_sel_hi:[1,0]
	v_pk_add_f32 v[50:51], v[62:63], 1.0 op_sel_hi:[1,0]
	v_pk_mul_f32 v[46:47], v[66:67], v[46:47]
	v_pk_mul_f32 v[44:45], v[68:69], v[44:45]
	v_pk_add_f32 v[52:53], v[76:77], 1.0 op_sel_hi:[1,0]
; __device__ __forceinline__ unsigned pk2(float lo, float hi) { return f2bf(lo) | (f2bf(hi) << 16); }
; template <bool ZP, bool XF32, bool OUT8 = false>
; __device__ __forceinline__ void norm_phase(LAS unsigned char* lds, const void* xin, const float* gain, const float* sh, const float* sc, bf16* hout, const float* wzt, float* zout, int lane, int wave, int vcu, int G) {
;     ...
;             for (int j = 0; j < 4; ++j) { const int col = 512 * j + 8 * lane;
; #pragma unroll
;                 for (int q = 0; q < 2; ++q) { const f32x4 gg = *(const f32x4*)(gain + col + 4 * q), s1 = *(const f32x4*)(sc + (size_t)b * MODW + col + 4 * q), s0 = *(const f32x4*)(sh + (size_t)b * MODW + col + 4 * q);
;                     v[r][j][q] = (v[r][j][q] * rstd * gg) * (s1 + 1.0f) + s0; }
;                 if constexpr (OUT8) { *(v2u*)((unsigned char*)hout + (size_t)m * D + col) = pack8_fp8(v[r][j][0][0], v[r][j][0][1], v[r][j][0][2], v[r][j][0][3], v[r][j][1][0], v[r][j][1][1], v[r][j][1][2], v[r][j][1][3], FP8_ASCALE); }
;                 else { v4u o; o.x = pk2(v[r][j][0][0], v[r][j][0][1]); o.y = pk2(v[r][j][0][2], v[r][j][0][3]); o.z = pk2(v[r][j][1][0], v[r][j][1][1]); o.w = pk2(v[r][j][1][2], v[r][j][1][3]);
;                     *(v4u*)(hout + (size_t)m * D + col) = o; } }
	v_pk_add_f32 v[54:55], v[74:75], 1.0 op_sel_hi:[1,0]
	v_pk_fma_f32 v[28:29], v[48:49], v[28:29], v[80:81]
	v_pk_fma_f32 v[32:33], v[50:51], v[32:33], v[78:79]
	v_pk_fma_f32 v[44:45], v[52:53], v[44:45], v[96:97]
	v_pk_fma_f32 v[46:47], v[54:55], v[46:47], v[94:95]
	v_bfe_u32 v25, v32, 16, 1
	v_bfe_u32 v27, v33, 16, 1
	v_bfe_u32 v31, v28, 16, 1
	v_bfe_u32 v41, v44, 16, 1
	v_bfe_u32 v35, v29, 16, 1
	v_bfe_u32 v43, v45, 16, 1
	v_add3_u32 v25, v32, v25, s27
	v_add3_u32 v27, v33, v27, s27
	v_add3_u32 v28, v28, v31, s27
	v_add3_u32 v33, v44, v41, s27
	v_add3_u32 v29, v29, v35, s27
	v_add3_u32 v35, v45, v43, s27
	v_lshrrev_b32_e32 v25, 16, v25
	v_lshrrev_b32_e32 v28, 16, v28
	v_lshrrev_b32_e32 v33, 16, v33
	v_and_or_b32 v44, v27, s25, v25
	v_and_or_b32 v45, v29, s25, v28
	v_cvt_pk_bf16_f32 v46, v46, v47
	v_and_or_b32 v47, v35, s25, v33
	global_store_dwordx4 v[72:73], v[44:47], off offset:1024
	s_nop 1
	v_mov_b64_e32 v[44:45], v[176:177]
	v_mov_b64_e32 v[46:47], v[178:179]
	s_nop 0
	s_nop 1
	v_mov_b64_e32 v[48:49], v[180:181]
	v_mov_b64_e32 v[50:51], v[182:183]
	v_mov_b64_e32 v[52:53], v[184:185]
	v_mov_b64_e32 v[54:55], v[186:187]
	v_mov_b64_e32 v[56:57], v[188:189]
	v_mov_b64_e32 v[58:59], v[190:191]
	v_mov_b64_e32 v[62:63], v[192:193]
	v_mov_b64_e32 v[64:65], v[194:195]
	v_mov_b64_e32 v[66:67], v[196:197]
	v_mov_b64_e32 v[68:69], v[198:199]
	v_mov_b32_e32 v41, v42
	v_mov_b32_e32 v37, v38
	v_mov_b32_e32 v31, v34
	v_mov_b32_e32 v25, v26
	v_pk_mul_f32 v[26:27], v[60:61], v[30:31] op_sel_hi:[0,1]
	v_pk_mul_f32 v[24:25], v[60:61], v[24:25] op_sel_hi:[0,1]
	v_pk_mul_f32 v[28:29], v[60:61], v[40:41] op_sel_hi:[0,1]
	v_pk_mul_f32 v[30:31], v[60:61], v[36:37] op_sel_hi:[0,1]
	v_pk_mul_f32 v[24:25], v[24:25], v[44:45]
	v_pk_mul_f32 v[26:27], v[26:27], v[46:47]
	v_pk_add_f32 v[32:33], v[50:51], 1.0 op_sel_hi:[1,0]
	v_pk_add_f32 v[34:35], v[48:49], 1.0 op_sel_hi:[1,0]
	v_pk_mul_f32 v[30:31], v[30:31], v[52:53]
	v_pk_mul_f32 v[28:29], v[28:29], v[54:55]
	v_pk_add_f32 v[36:37], v[58:59], 1.0 op_sel_hi:[1,0]
	v_pk_add_f32 v[38:39], v[56:57], 1.0 op_sel_hi:[1,0]
	v_pk_fma_f32 v[26:27], v[26:27], v[32:33], v[64:65]
	v_pk_fma_f32 v[24:25], v[24:25], v[34:35], v[62:63]
	v_pk_fma_f32 v[28:29], v[28:29], v[36:37], v[68:69]
	v_pk_fma_f32 v[30:31], v[30:31], v[38:39], v[66:67]
	v_bfe_u32 v32, v24, 16, 1
	v_bfe_u32 v34, v26, 16, 1
	v_bfe_u32 v36, v30, 16, 1
	v_bfe_u32 v38, v28, 16, 1
	v_bfe_u32 v33, v25, 16, 1
	v_bfe_u32 v35, v27, 16, 1
	v_bfe_u32 v37, v31, 16, 1
	v_bfe_u32 v39, v29, 16, 1
	v_add3_u32 v24, v24, v32, s27
	v_add3_u32 v26, v26, v34, s27
	v_add3_u32 v30, v30, v36, s27
	v_add3_u32 v28, v28, v38, s27
	v_add3_u32 v25, v25, v33, s27
	v_add3_u32 v27, v27, v35, s27
	v_add3_u32 v31, v31, v37, s27
	v_add3_u32 v29, v29, v39, s27
	v_lshrrev_b32_e32 v24, 16, v24
	v_lshrrev_b32_e32 v26, 16, v26
	v_lshrrev_b32_e32 v30, 16, v30
	v_lshrrev_b32_e32 v28, 16, v28
	v_and_or_b32 v24, v25, s25, v24
	v_and_or_b32 v25, v27, s25, v26
	v_and_or_b32 v26, v31, s25, v30
	v_and_or_b32 v27, v29, s25, v28
	global_store_dwordx4 v[72:73], v[24:27], off offset:2048
	s_nop 1
	v_mov_b64_e32 v[24:25], v[200:201]
	v_mov_b64_e32 v[26:27], v[202:203]
	s_nop 0
	s_nop 1
	v_mov_b64_e32 v[28:29], v[204:205]
	v_mov_b64_e32 v[30:31], v[206:207]
	v_mov_b64_e32 v[32:33], v[208:209]
	v_mov_b64_e32 v[34:35], v[210:211]
	v_mov_b64_e32 v[36:37], v[212:213]
	v_mov_b64_e32 v[38:39], v[214:215]
	v_mov_b64_e32 v[40:41], v[216:217]
	v_mov_b64_e32 v[42:43], v[218:219]
	v_mov_b64_e32 v[44:45], v[220:221]
	v_mov_b64_e32 v[46:47], v[222:223]
	v_mov_b32_e32 v48, v23
	v_mov_b32_e32 v49, v22
	v_mov_b32_e32 v22, v21
	v_mov_b32_e32 v23, v20
	v_pk_mul_f32 v[20:21], v[60:61], v[48:49] op_sel_hi:[0,1]
	v_pk_mul_f32 v[22:23], v[60:61], v[22:23] op_sel_hi:[0,1]
	v_pk_mul_f32 v[20:21], v[20:21], v[24:25]
	v_pk_mul_f32 v[2:3], v[2:3], v[26:27]
	v_pk_add_f32 v[24:25], v[30:31], 1.0 op_sel_hi:[1,0]
	v_pk_add_f32 v[26:27], v[28:29], 1.0 op_sel_hi:[1,0]
	v_pk_mul_f32 v[22:23], v[22:23], v[32:33]
	v_pk_mul_f32 v[4:5], v[4:5], v[34:35]
	v_pk_add_f32 v[28:29], v[38:39], 1.0 op_sel_hi:[1,0]
	v_pk_add_f32 v[30:31], v[36:37], 1.0 op_sel_hi:[1,0]
	v_pk_fma_f32 v[2:3], v[2:3], v[24:25], v[42:43]
	v_pk_fma_f32 v[20:21], v[20:21], v[26:27], v[40:41]
	v_pk_fma_f32 v[4:5], v[4:5], v[28:29], v[46:47]
	v_pk_fma_f32 v[22:23], v[22:23], v[30:31], v[44:45]
	v_bfe_u32 v24, v20, 16, 1
	v_bfe_u32 v26, v2, 16, 1
	v_bfe_u32 v28, v22, 16, 1
	v_bfe_u32 v30, v4, 16, 1
	v_bfe_u32 v25, v21, 16, 1
	v_bfe_u32 v27, v3, 16, 1
	v_bfe_u32 v29, v23, 16, 1
	v_bfe_u32 v31, v5, 16, 1
	v_add3_u32 v20, v20, v24, s27
	v_add3_u32 v2, v2, v26, s27
	v_add3_u32 v22, v22, v28, s27
	v_add3_u32 v4, v4, v30, s27
	v_add3_u32 v21, v21, v25, s27
	v_add3_u32 v3, v3, v27, s27
	v_add3_u32 v23, v23, v29, s27
	v_add3_u32 v5, v5, v31, s27
	v_lshrrev_b32_e32 v20, 16, v20
	v_lshrrev_b32_e32 v24, 16, v2
	v_lshrrev_b32_e32 v22, 16, v22
	v_lshrrev_b32_e32 v25, 16, v4
	v_and_or_b32 v2, v21, s25, v20
	v_and_or_b32 v3, v3, s25, v24
	v_and_or_b32 v4, v23, s25, v22
	v_and_or_b32 v5, v5, s25, v25
	global_store_dwordx4 v[72:73], v[2:5], off offset:3072
	s_branch .LBB0_936

; __device__ __forceinline__ unsigned pk2(float lo, float hi) { return f2bf(lo) | (f2bf(hi) << 16); }
; __device__ __forceinline__ void unpack8(const v4u& w, float (&f)[8]) { f[0] = bflo(w.x); f[1] = bfhi(w.x); f[2] = bflo(w.y); f[3] = bfhi(w.y); f[4] = bflo(w.z); f[5] = bfhi(w.z); f[6] = bflo(w.w); f[7] = bfhi(w.w); }
; __device__ __forceinline__ void conv_phase(const bf16* Bg, const bf16* CU, bf16* Y, const float* cw, int tid, int vcu, int G) {
;     ...
;         for (int r0 = 0; r0 < 32; r0 += 8) { v4u cw[8], bw[8];
; #pragma unroll
;             for (int u = 0; u < 8; ++u) { const size_t off = (size_t)(m0 + r0 + u) * D + col; cw[u] = *(const v4u*)(CU + off); bw[u] = *(const v4u*)(Bg + off); }
; #pragma unroll
;             for (int u = 0; u < 8; ++u) { const size_t off = (size_t)(m0 + r0 + u) * D + col;
;                 float cu[8], bg[8], y[8]; unpack8(cw[u], cu); unpack8(bw[u], bg);
; #pragma unroll
;                 for (int e = 0; e < 8; ++e) { y[e] = bg[e] * (w0[e] * p2[e] + w1[e] * p1[e] + w2[e] * cu[e]); p2[e] = p1[e]; p1[e] = cu[e]; }
;                 v4u w; w.x = pk2(y[0], y[1]); w.y = pk2(y[2], y[3]); w.z = pk2(y[4], y[5]); w.w = pk2(y[6], y[7]);
;                 *(v4u*)(Y + off) = w; } }
.LBB0_1114:
	v_add_co_u32_e32 v26, vcc, 0xfbff9000, v68
	v_pk_mul_f32 v[88:89], v[4:5], v[78:79]
	s_nop 0
	v_addc_co_u32_e32 v27, vcc, -1, v69, vcc
	v_add_co_u32_e32 v28, vcc, 0xf7ff9000, v68
	v_pk_mul_f32 v[110:111], v[8:9], v[74:75]
	s_nop 0
	v_addc_co_u32_e32 v29, vcc, -1, v69, vcc
	v_add_co_u32_e32 v30, vcc, 0xfbffa000, v68
	v_pk_mul_f32 v[92:93], v[2:3], v[80:81]
	s_nop 0
	v_addc_co_u32_e32 v31, vcc, -1, v69, vcc
	global_load_dwordx4 v[94:97], v[30:31], off
	v_add_co_u32_e32 v30, vcc, 0xf7ffa000, v68
	s_mov_b64 s[6:7], vcc
	v_add_co_u32_e32 v32, vcc, 0xfbffb000, v68
	v_pk_mul_f32 v[112:113], v[6:7], v[76:77]
	s_nop 0
	v_addc_co_u32_e32 v33, vcc, -1, v69, vcc
	global_load_dwordx4 v[114:117], v[32:33], off
	v_add_co_u32_e32 v32, vcc, 0xf7ffb000, v68
	s_mov_b64 s[8:9], vcc
	v_add_co_u32_e32 v34, vcc, 0xfbffc000, v68
	v_pk_fma_f32 v[112:113], v[10:11], v[84:85], v[112:113]
	s_nop 0
	v_addc_co_u32_e32 v35, vcc, -1, v69, vcc
	global_load_dwordx4 v[120:123], v[34:35], off
	v_add_co_u32_e32 v34, vcc, 0xf7ffc000, v68
	v_pk_fma_f32 v[110:111], v[12:13], v[82:83], v[110:111]
	s_nop 0
	v_addc_co_u32_e32 v35, vcc, -1, v69, vcc
	global_load_dwordx4 v[124:127], v[34:35], off
	global_load_dwordx4 v[46:49], v[26:27], off
	global_load_dwordx4 v[42:45], v[28:29], off
	v_addc_co_u32_e64 v31, vcc, -1, v69, s[6:7]
	v_addc_co_u32_e64 v33, vcc, -1, v69, s[8:9]
	v_add_co_u32_e32 v26, vcc, 0xfbffd000, v68
	global_load_dwordx4 v[34:37], v[30:31], off
	s_nop 0
	v_addc_co_u32_e32 v27, vcc, -1, v69, vcc
	v_add_co_u32_e32 v28, vcc, 0xf7ffd000, v68
	global_load_dwordx4 v[30:33], v[32:33], off
	s_nop 0
	v_addc_co_u32_e32 v29, vcc, -1, v69, vcc
	global_load_dwordx4 v[128:131], v[26:27], off
	global_load_dwordx4 v[132:135], v[28:29], off
	v_add_co_u32_e32 v26, vcc, 0xfbffe000, v68
	v_pk_fma_f32 v[92:93], v[18:19], v[72:73], v[92:93]
	s_nop 0
	v_addc_co_u32_e32 v27, vcc, -1, v69, vcc
	v_add_co_u32_e32 v28, vcc, 0xf7ffe000, v68
	v_pk_fma_f32 v[88:89], v[20:21], v[70:71], v[88:89]
	s_nop 0
	v_addc_co_u32_e32 v29, vcc, -1, v69, vcc
	global_load_dwordx4 v[62:65], v[26:27], off
	global_load_dwordx4 v[58:61], v[28:29], off
	v_add_co_u32_e32 v26, vcc, 0xfbfff000, v68
	s_add_i32 s37, s37, 8
	s_nop 0
	v_addc_co_u32_e32 v27, vcc, -1, v69, vcc
	v_add_co_u32_e32 v28, vcc, 0xf7fff000, v68
	s_cmp_gt_u32 s37, 23
	s_nop 0
	v_addc_co_u32_e32 v29, vcc, -1, v69, vcc
	global_load_dwordx4 v[50:53], v[26:27], off
	global_load_dwordx4 v[38:41], v[28:29], off
	v_add_co_u32_e32 v26, vcc, 0xfc000000, v68
	s_waitcnt vmcnt(13)
	v_lshlrev_b32_e32 v103, 16, v95
	v_addc_co_u32_e32 v27, vcc, -1, v69, vcc
	v_add_co_u32_e32 v28, vcc, 0xf8000000, v68
	v_lshlrev_b32_e32 v102, 16, v94
	s_nop 0
	v_addc_co_u32_e32 v29, vcc, -1, v69, vcc
	global_load_dwordx4 v[54:57], v[26:27], off
	s_nop 0
	global_load_dwordx4 v[26:29], v[28:29], off
	s_waitcnt vmcnt(14)
	v_lshlrev_b32_e32 v109, 16, v115
	v_lshlrev_b32_e32 v108, 16, v114
	v_pk_mul_f32 v[86:87], v[10:11], v[108:109]
	v_and_b32_e32 v107, 0xffff0000, v115
	v_pk_fma_f32 v[86:87], v[6:7], v[102:103], v[86:87]
	v_and_b32_e32 v106, 0xffff0000, v114
	v_and_b32_e32 v105, 0xffff0000, v95
	v_and_b32_e32 v104, 0xffff0000, v94
	v_lshlrev_b32_e32 v101, 16, v117
	s_waitcnt vmcnt(13)
	v_lshlrev_b32_e32 v79, 16, v121
	v_lshlrev_b32_e32 v78, 16, v120
	v_pk_fma_f32 v[86:87], v[14:15], v[78:79], v[86:87]
	v_lshlrev_b32_e32 v100, 16, v116
	s_waitcnt vmcnt(12)
	v_lshlrev_b32_e32 v75, 16, v125
	v_lshlrev_b32_e32 v74, 16, v124
	v_pk_mul_f32 v[74:75], v[86:87], v[74:75]
	v_pk_mul_f32 v[86:87], v[12:13], v[106:107]
	v_and_b32_e32 v81, 0xffff0000, v121
	v_and_b32_e32 v80, 0xffff0000, v120
	v_pk_fma_f32 v[86:87], v[8:9], v[104:105], v[86:87]
	v_lshlrev_b32_e32 v95, 16, v97
	v_lshlrev_b32_e32 v94, 16, v96
	v_pk_mul_f32 v[114:115], v[18:19], v[100:101]
	v_and_b32_e32 v77, 0xffff0000, v125
	v_and_b32_e32 v76, 0xffff0000, v124
	v_pk_fma_f32 v[86:87], v[16:17], v[80:81], v[86:87]
	v_lshlrev_b32_e32 v121, 16, v123
	v_lshlrev_b32_e32 v120, 16, v122
	v_pk_fma_f32 v[114:115], v[2:3], v[94:95], v[114:115]
	v_pk_mul_f32 v[76:77], v[86:87], v[76:77]
	v_and_b32_e32 v99, 0xffff0000, v117
	v_and_b32_e32 v98, 0xffff0000, v116
	v_lshlrev_b32_e32 v87, 16, v127
	v_lshlrev_b32_e32 v86, 16, v126
	v_pk_fma_f32 v[114:115], v[22:23], v[120:121], v[114:115]
	v_and_b32_e32 v97, 0xffff0000, v97
	v_and_b32_e32 v96, 0xffff0000, v96
	v_pk_mul_f32 v[86:87], v[114:115], v[86:87]
	v_pk_mul_f32 v[114:115], v[20:21], v[98:99]
	v_and_b32_e32 v123, 0xffff0000, v123
	v_and_b32_e32 v122, 0xffff0000, v122
	v_pk_fma_f32 v[114:115], v[4:5], v[96:97], v[114:115]
	v_and_b32_e32 v91, 0xffff0000, v127
	v_and_b32_e32 v90, 0xffff0000, v126
	v_pk_fma_f32 v[114:115], v[24:25], v[122:123], v[114:115]
	v_bfe_u32 v116, v76, 16, 1
	v_pk_mul_f32 v[90:91], v[114:115], v[90:91]
	v_bfe_u32 v115, v77, 16, 1
	v_bfe_u32 v66, v91, 16, 1
	v_bfe_u32 v114, v90, 16, 1
	v_add3_u32 v66, v91, v66, s30
	v_bfe_u32 v91, v86, 16, 1
	v_add3_u32 v116, v76, v116, s30
	v_add3_u32 v115, v77, v115, s30
	v_add3_u32 v76, v90, v114, s30
	v_bfe_u32 v77, v74, 16, 1
	v_bfe_u32 v90, v75, 16, 1
	v_bfe_u32 v114, v87, 16, 1
	v_add3_u32 v86, v86, v91, s30
	v_add3_u32 v87, v87, v114, s30
	v_add3_u32 v75, v75, v90, s30
	v_add3_u32 v74, v74, v77, s30
	v_lshrrev_b32_e32 v86, 16, v86
	v_lshrrev_b32_e32 v74, 16, v74
	v_lshrrev_b32_e32 v75, 16, v75
	v_lshrrev_b32_e32 v77, 16, v87
	v_and_or_b32 v76, v76, s28, v86
	v_add_co_u32_e32 v86, vcc, s31, v68
	v_pk_mul_f32 v[90:91], v[10:11], v[78:79]
	v_and_or_b32 v77, v66, s28, v77
	v_and_or_b32 v75, v115, s28, v75
	v_and_or_b32 v74, v116, s28, v74
	v_addc_co_u32_e32 v87, vcc, -1, v69, vcc
	s_waitcnt vmcnt(7)
; __device__ __forceinline__ unsigned pk2(float lo, float hi) { return f2bf(lo) | (f2bf(hi) << 16); }
; __device__ __forceinline__ void unpack8(const v4u& w, float (&f)[8]) { f[0] = bflo(w.x); f[1] = bfhi(w.x); f[2] = bflo(w.y); f[3] = bfhi(w.y); f[4] = bflo(w.z); f[5] = bfhi(w.z); f[6] = bflo(w.w); f[7] = bfhi(w.w); }
; __device__ __forceinline__ void conv_phase(const bf16* Bg, const bf16* CU, bf16* Y, const float* cw, int tid, int vcu, int G) {
;     ...
;             for (int u = 0; u < 8; ++u) { const size_t off = (size_t)(m0 + r0 + u) * D + col; cw[u] = *(const v4u*)(CU + off); bw[u] = *(const v4u*)(Bg + off); }
; #pragma unroll
;             for (int u = 0; u < 8; ++u) { const size_t off = (size_t)(m0 + r0 + u) * D + col;
;                 float cu[8], bg[8], y[8]; unpack8(cw[u], cu); unpack8(bw[u], bg);
; #pragma unroll
;                 for (int e = 0; e < 8; ++e) { y[e] = bg[e] * (w0[e] * p2[e] + w1[e] * p1[e] + w2[e] * cu[e]); p2[e] = p1[e]; p1[e] = cu[e]; }
;                 v4u w; w.x = pk2(y[0], y[1]); w.y = pk2(y[2], y[3]); w.z = pk2(y[4], y[5]); w.w = pk2(y[6], y[7]);
;                 *(v4u*)(Y + off) = w; } }
	v_lshlrev_b32_e32 v125, 16, v129
	v_lshlrev_b32_e32 v124, 16, v128
	v_pk_fma_f32 v[90:91], v[6:7], v[108:109], v[90:91]
	global_store_dwordx4 v[86:87], v[74:77], off offset:-4096
	v_pk_fma_f32 v[90:91], v[14:15], v[124:125], v[90:91]
	v_and_b32_e32 v127, 0xffff0000, v129
	s_waitcnt vmcnt(7)
	v_lshlrev_b32_e32 v75, 16, v133
	v_lshlrev_b32_e32 v74, 16, v132
	v_pk_mul_f32 v[74:75], v[90:91], v[74:75]
	v_pk_mul_f32 v[90:91], v[12:13], v[80:81]
	v_and_b32_e32 v126, 0xffff0000, v128
	v_pk_fma_f32 v[90:91], v[8:9], v[106:107], v[90:91]
	v_lshlrev_b32_e32 v117, 16, v131
	v_lshlrev_b32_e32 v116, 16, v130
	v_and_b32_e32 v115, 0xffff0000, v131
	v_and_b32_e32 v114, 0xffff0000, v130
	v_pk_mul_f32 v[130:131], v[18:19], v[120:121]
	v_and_b32_e32 v77, 0xffff0000, v133
	v_and_b32_e32 v76, 0xffff0000, v132
	v_pk_fma_f32 v[90:91], v[16:17], v[126:127], v[90:91]
	v_pk_fma_f32 v[130:131], v[2:3], v[100:101], v[130:131]
	v_pk_mul_f32 v[76:77], v[90:91], v[76:77]
	v_lshlrev_b32_e32 v91, 16, v135
	v_lshlrev_b32_e32 v90, 16, v134
	v_pk_fma_f32 v[130:131], v[22:23], v[116:117], v[130:131]
	v_and_b32_e32 v129, 0xffff0000, v135
	v_pk_mul_f32 v[90:91], v[130:131], v[90:91]
	v_pk_mul_f32 v[130:131], v[20:21], v[122:123]
	v_and_b32_e32 v128, 0xffff0000, v134
	v_pk_fma_f32 v[130:131], v[4:5], v[98:99], v[130:131]
	s_nop 0
	v_pk_fma_f32 v[130:131], v[24:25], v[114:115], v[130:131]
	s_nop 0
	v_pk_mul_f32 v[128:129], v[130:131], v[128:129]
	v_bfe_u32 v130, v77, 16, 1
	v_bfe_u32 v66, v129, 16, 1
	v_bfe_u32 v119, v128, 16, 1
	v_bfe_u32 v131, v76, 16, 1
	v_add3_u32 v131, v76, v131, s30
	v_add3_u32 v130, v77, v130, s30
	v_add3_u32 v76, v128, v119, s30
	v_add3_u32 v66, v129, v66, s30
	v_bfe_u32 v77, v74, 16, 1
	v_bfe_u32 v119, v75, 16, 1
	v_bfe_u32 v128, v90, 16, 1
	v_bfe_u32 v129, v91, 16, 1
	v_add3_u32 v91, v91, v129, s30
	v_add3_u32 v90, v90, v128, s30
	v_add3_u32 v75, v75, v119, s30
	v_add3_u32 v74, v74, v77, s30
	v_lshrrev_b32_e32 v74, 16, v74
	v_lshrrev_b32_e32 v75, 16, v75
	v_lshrrev_b32_e32 v90, 16, v90
	v_lshrrev_b32_e32 v77, 16, v91
	v_and_or_b32 v77, v66, s28, v77
	v_and_or_b32 v76, v76, s28, v90
	v_and_or_b32 v75, v130, s28, v75
	v_and_or_b32 v74, v131, s28, v74
	global_store_dwordx4 v[86:87], v[74:77], off
	s_waitcnt vmcnt(7)
	v_lshlrev_b32_e32 v87, 16, v63
	v_lshlrev_b32_e32 v86, 16, v62
	v_pk_mul_f32 v[76:77], v[10:11], v[124:125]
	s_waitcnt vmcnt(6)
	v_lshlrev_b32_e32 v75, 16, v59
	v_pk_fma_f32 v[76:77], v[6:7], v[78:79], v[76:77]
	v_lshlrev_b32_e32 v74, 16, v58
	v_pk_fma_f32 v[76:77], v[14:15], v[86:87], v[76:77]
	v_and_b32_e32 v63, 0xffff0000, v63
	v_pk_mul_f32 v[74:75], v[76:77], v[74:75]
	v_pk_mul_f32 v[76:77], v[12:13], v[126:127]
	v_and_b32_e32 v62, 0xffff0000, v62
	v_pk_fma_f32 v[76:77], v[8:9], v[80:81], v[76:77]
	v_pk_mul_f32 v[78:79], v[18:19], v[116:117]
	v_and_b32_e32 v59, 0xffff0000, v59
	v_and_b32_e32 v58, 0xffff0000, v58
	v_pk_fma_f32 v[76:77], v[16:17], v[62:63], v[76:77]
	v_lshlrev_b32_e32 v91, 16, v65
	v_lshlrev_b32_e32 v90, 16, v64
	v_pk_fma_f32 v[78:79], v[2:3], v[120:121], v[78:79]
	v_pk_mul_f32 v[76:77], v[76:77], v[58:59]
	v_and_b32_e32 v59, 0xffff0000, v65
	v_and_b32_e32 v58, 0xffff0000, v64
	v_lshlrev_b32_e32 v65, 16, v61
	v_lshlrev_b32_e32 v64, 16, v60
	v_pk_fma_f32 v[78:79], v[22:23], v[90:91], v[78:79]
	v_and_b32_e32 v61, 0xffff0000, v61
	v_pk_mul_f32 v[64:65], v[78:79], v[64:65]
	v_pk_mul_f32 v[78:79], v[20:21], v[114:115]
	v_and_b32_e32 v60, 0xffff0000, v60
	v_pk_fma_f32 v[78:79], v[4:5], v[122:123], v[78:79]
	v_bfe_u32 v80, v76, 16, 1
	v_pk_fma_f32 v[78:79], v[24:25], v[58:59], v[78:79]
	v_add3_u32 v80, v76, v80, s30
	v_pk_mul_f32 v[60:61], v[78:79], v[60:61]
	v_bfe_u32 v79, v77, 16, 1
	v_bfe_u32 v66, v61, 16, 1
	v_bfe_u32 v78, v60, 16, 1
	v_add3_u32 v79, v77, v79, s30
	v_bfe_u32 v77, v64, 16, 1
	v_add3_u32 v60, v60, v78, s30
	v_add3_u32 v61, v61, v66, s30
	v_bfe_u32 v66, v74, 16, 1
	v_bfe_u32 v76, v75, 16, 1
	v_bfe_u32 v78, v65, 16, 1
	v_add3_u32 v64, v64, v77, s30
	v_add3_u32 v65, v65, v78, s30
	v_add3_u32 v75, v75, v76, s30
	v_add3_u32 v66, v74, v66, s30
	v_lshrrev_b32_e32 v64, 16, v64
	v_lshrrev_b32_e32 v66, 16, v66
	v_lshrrev_b32_e32 v74, 16, v75
	v_lshrrev_b32_e32 v65, 16, v65
	v_and_or_b32 v76, v60, s28, v64
	v_add_co_u32_e32 v60, vcc, s27, v68
	v_and_or_b32 v77, v61, s28, v65
	v_and_or_b32 v75, v79, s28, v74
	v_and_or_b32 v74, v80, s28, v66
	v_addc_co_u32_e32 v61, vcc, -1, v69, vcc
	global_store_dwordx4 v[60:61], v[74:77], off
	s_waitcnt vmcnt(6)
	v_lshlrev_b32_e32 v80, 16, v52
	v_and_b32_e32 v78, 0xffff0000, v52
	v_lshlrev_b32_e32 v76, 16, v50
	v_and_b32_e32 v74, 0xffff0000, v50
	v_lshlrev_b32_e32 v77, 16, v51
	v_and_b32_e32 v75, 0xffff0000, v51
	v_lshlrev_b32_e32 v81, 16, v53
	v_and_b32_e32 v79, 0xffff0000, v53
	s_waitcnt vmcnt(4)
; __device__ __forceinline__ void unpack8(const v4u& w, float (&f)[8]) { f[0] = bflo(w.x); f[1] = bfhi(w.x); f[2] = bflo(w.y); f[3] = bfhi(w.y); f[4] = bflo(w.z); f[5] = bfhi(w.z); f[6] = bflo(w.w); f[7] = bfhi(w.w); }
; __device__ __forceinline__ void conv_phase(const bf16* Bg, const bf16* CU, bf16* Y, const float* cw, int tid, int vcu, int G) {
;     ...
;             for (int u = 0; u < 8; ++u) { const size_t off = (size_t)(m0 + r0 + u) * D + col;
;                 float cu[8], bg[8], y[8]; unpack8(cw[u], cu); unpack8(bw[u], bg);
; #pragma unroll
;                 for (int e = 0; e < 8; ++e) { y[e] = bg[e] * (w0[e] * p2[e] + w1[e] * p1[e] + w2[e] * cu[e]); p2[e] = p1[e]; p1[e] = cu[e]; }
	v_lshlrev_b32_e32 v52, 16, v54
	v_and_b32_e32 v60, 0xffff0000, v54
	v_lshlrev_b32_e32 v53, 16, v55
	v_and_b32_e32 v61, 0xffff0000, v55
	v_lshlrev_b32_e32 v50, 16, v56
	v_and_b32_e32 v54, 0xffff0000, v56
	v_lshlrev_b32_e32 v51, 16, v57
	v_and_b32_e32 v55, 0xffff0000, v57
	v_lshlrev_b32_e32 v57, 16, v47
	v_lshlrev_b32_e32 v56, 16, v46
	v_lshlrev_b32_e32 v65, 16, v43
	v_lshlrev_b32_e32 v64, 16, v42
	v_pk_fma_f32 v[112:113], v[14:15], v[56:57], v[112:113]
	v_and_b32_e32 v47, 0xffff0000, v47
	v_and_b32_e32 v46, 0xffff0000, v46
	v_pk_mul_f32 v[64:65], v[112:113], v[64:65]
	v_pk_mul_f32 v[112:113], v[10:11], v[56:57]
	v_and_b32_e32 v43, 0xffff0000, v43
	v_and_b32_e32 v42, 0xffff0000, v42
	v_pk_fma_f32 v[110:111], v[16:17], v[46:47], v[110:111]
	v_pk_fma_f32 v[84:85], v[6:7], v[84:85], v[112:113]
	v_pk_mul_f32 v[42:43], v[110:111], v[42:43]
	v_lshlrev_b32_e32 v111, 16, v35
	v_lshlrev_b32_e32 v110, 16, v34
	v_pk_fma_f32 v[84:85], v[14:15], v[102:103], v[84:85]
	v_pk_mul_f32 v[102:103], v[10:11], v[102:103]
	v_pk_mul_f32 v[84:85], v[84:85], v[110:111]
	v_pk_mul_f32 v[110:111], v[12:13], v[46:47]
	v_and_b32_e32 v35, 0xffff0000, v35
	v_pk_fma_f32 v[82:83], v[8:9], v[82:83], v[110:111]
	v_and_b32_e32 v34, 0xffff0000, v34
	v_pk_fma_f32 v[82:83], v[16:17], v[104:105], v[82:83]
	v_pk_fma_f32 v[56:57], v[6:7], v[56:57], v[102:103]
	v_pk_mul_f32 v[34:35], v[82:83], v[34:35]
	v_lshlrev_b32_e32 v83, 16, v31
	v_lshlrev_b32_e32 v82, 16, v30
	v_pk_mul_f32 v[104:105], v[12:13], v[104:105]
	v_pk_fma_f32 v[56:57], v[14:15], v[108:109], v[56:57]
	v_pk_fma_f32 v[46:47], v[8:9], v[46:47], v[104:105]
	v_pk_mul_f32 v[56:57], v[56:57], v[82:83]
	v_pk_mul_f32 v[82:83], v[10:11], v[86:87]
	v_and_b32_e32 v31, 0xffff0000, v31
	v_and_b32_e32 v30, 0xffff0000, v30
	v_pk_fma_f32 v[46:47], v[16:17], v[106:107], v[46:47]
	v_pk_fma_f32 v[82:83], v[6:7], v[124:125], v[82:83]
	v_pk_mul_f32 v[102:103], v[12:13], v[62:63]
	v_pk_mul_f32 v[46:47], v[46:47], v[30:31]
	v_lshlrev_b32_e32 v31, 16, v39
	v_lshlrev_b32_e32 v30, 16, v38
	v_pk_fma_f32 v[102:103], v[8:9], v[126:127], v[102:103]
	v_pk_fma_f32 v[82:83], v[14:15], v[76:77], v[82:83]
	v_and_b32_e32 v39, 0xffff0000, v39
	v_and_b32_e32 v38, 0xffff0000, v38
	v_pk_mul_f32 v[82:83], v[82:83], v[30:31]
	v_pk_fma_f32 v[30:31], v[16:17], v[74:75], v[102:103]
	v_lshlrev_b32_e32 v103, 16, v45
	v_pk_mul_f32 v[38:39], v[30:31], v[38:39]
	v_lshlrev_b32_e32 v31, 16, v49
	v_lshlrev_b32_e32 v30, 16, v48
	v_lshlrev_b32_e32 v102, 16, v44
	v_pk_fma_f32 v[92:93], v[22:23], v[30:31], v[92:93]
	v_and_b32_e32 v49, 0xffff0000, v49
	v_and_b32_e32 v48, 0xffff0000, v48
	v_pk_mul_f32 v[92:93], v[92:93], v[102:103]
	v_pk_mul_f32 v[102:103], v[18:19], v[30:31]
	v_and_b32_e32 v45, 0xffff0000, v45
	v_and_b32_e32 v44, 0xffff0000, v44
	v_pk_fma_f32 v[88:89], v[24:25], v[48:49], v[88:89]
	v_pk_fma_f32 v[72:73], v[2:3], v[72:73], v[102:103]
	v_pk_mul_f32 v[44:45], v[88:89], v[44:45]
	v_lshlrev_b32_e32 v89, 16, v37
	v_lshlrev_b32_e32 v88, 16, v36
	v_pk_fma_f32 v[72:73], v[22:23], v[94:95], v[72:73]
	v_and_b32_e32 v37, 0xffff0000, v37
	v_pk_mul_f32 v[72:73], v[72:73], v[88:89]
	v_pk_mul_f32 v[88:89], v[20:21], v[48:49]
	v_and_b32_e32 v36, 0xffff0000, v36
	v_pk_fma_f32 v[70:71], v[4:5], v[70:71], v[88:89]
	v_pk_mul_f32 v[88:89], v[18:19], v[94:95]
	v_pk_fma_f32 v[70:71], v[24:25], v[96:97], v[70:71]
	v_pk_fma_f32 v[30:31], v[2:3], v[30:31], v[88:89]
	v_pk_mul_f32 v[36:37], v[70:71], v[36:37]
	v_lshlrev_b32_e32 v71, 16, v33
	v_lshlrev_b32_e32 v70, 16, v32
	v_pk_mul_f32 v[94:95], v[20:21], v[96:97]
	v_pk_fma_f32 v[30:31], v[22:23], v[100:101], v[30:31]
	v_and_b32_e32 v33, 0xffff0000, v33
	v_pk_mul_f32 v[70:71], v[30:31], v[70:71]
	v_pk_fma_f32 v[30:31], v[4:5], v[48:49], v[94:95]
	v_and_b32_e32 v32, 0xffff0000, v32
	v_pk_fma_f32 v[30:31], v[24:25], v[98:99], v[30:31]
	v_pk_mul_f32 v[88:89], v[20:21], v[58:59]
	v_pk_mul_f32 v[48:49], v[30:31], v[32:33]
	v_lshlrev_b32_e32 v31, 16, v41
	v_lshlrev_b32_e32 v30, 16, v40
	v_and_b32_e32 v33, 0xffff0000, v41
	v_and_b32_e32 v32, 0xffff0000, v40
	v_pk_mul_f32 v[40:41], v[18:19], v[90:91]
	v_pk_fma_f32 v[88:89], v[4:5], v[114:115], v[88:89]
	v_pk_fma_f32 v[40:41], v[2:3], v[116:117], v[40:41]
	s_nop 0
	v_pk_fma_f32 v[40:41], v[22:23], v[80:81], v[40:41]
	s_nop 0
	v_pk_mul_f32 v[40:41], v[40:41], v[30:31]
	v_pk_fma_f32 v[30:31], v[24:25], v[78:79], v[88:89]
	s_nop 0
	v_pk_mul_f32 v[88:89], v[30:31], v[32:33]
	v_bfe_u32 v30, v45, 16, 1
	v_bfe_u32 v32, v43, 16, 1
	v_bfe_u32 v33, v42, 16, 1
	v_bfe_u32 v31, v44, 16, 1
	v_add3_u32 v42, v42, v33, s30
	v_add3_u32 v43, v43, v32, s30
	v_add3_u32 v30, v45, v30, s30
	v_bfe_u32 v32, v64, 16, 1
	v_bfe_u32 v33, v65, 16, 1
; __device__ __forceinline__ unsigned pk2(float lo, float hi) { return f2bf(lo) | (f2bf(hi) << 16); }
; __device__ __forceinline__ void unpack8(const v4u& w, float (&f)[8]) { f[0] = bflo(w.x); f[1] = bfhi(w.x); f[2] = bflo(w.y); f[3] = bfhi(w.y); f[4] = bflo(w.z); f[5] = bfhi(w.z); f[6] = bflo(w.w); f[7] = bfhi(w.w); }
; __device__ __forceinline__ void conv_phase(const bf16* Bg, const bf16* CU, bf16* Y, const float* cw, int tid, int vcu, int G) {
;     ...
;     for (int task = gtid; task < 256 * 512; task += NT) {
;     ...
;             for (int u = 0; u < 8; ++u) { const size_t off = (size_t)(m0 + r0 + u) * D + col;
;                 float cu[8], bg[8], y[8]; unpack8(cw[u], cu); unpack8(bw[u], bg);
; #pragma unroll
;                 for (int e = 0; e < 8; ++e) { y[e] = bg[e] * (w0[e] * p2[e] + w1[e] * p1[e] + w2[e] * cu[e]); p2[e] = p1[e]; p1[e] = cu[e]; }
;                 v4u w; w.x = pk2(y[0], y[1]); w.y = pk2(y[2], y[3]); w.z = pk2(y[4], y[5]); w.w = pk2(y[6], y[7]);
;                 *(v4u*)(Y + off) = w; } }
	v_bfe_u32 v45, v93, 16, 1
	v_add3_u32 v31, v44, v31, s30
	v_bfe_u32 v44, v92, 16, 1
	v_add3_u32 v45, v93, v45, s30
	v_add3_u32 v33, v65, v33, s30
	v_add3_u32 v32, v64, v32, s30
	v_add3_u32 v44, v92, v44, s30
	v_lshrrev_b32_e32 v64, 16, v32
	v_lshrrev_b32_e32 v65, 16, v33
	v_lshrrev_b32_e32 v33, 16, v45
	v_lshrrev_b32_e32 v32, 16, v44
	v_and_or_b32 v33, v30, s28, v33
	v_and_or_b32 v30, v42, s28, v64
	v_add_co_u32_e32 v42, vcc, s34, v68
	v_and_or_b32 v32, v31, s28, v32
	v_and_or_b32 v31, v43, s28, v65
	v_addc_co_u32_e32 v43, vcc, -1, v69, vcc
	global_store_dwordx4 v[42:43], v[30:33], off offset:-4096
	s_nop 1
	v_bfe_u32 v30, v37, 16, 1
	v_bfe_u32 v31, v36, 16, 1
	v_bfe_u32 v32, v35, 16, 1
	v_bfe_u32 v33, v34, 16, 1
	v_add3_u32 v34, v34, v33, s30
	v_add3_u32 v35, v35, v32, s30
	v_add3_u32 v31, v36, v31, s30
	v_add3_u32 v30, v37, v30, s30
	v_bfe_u32 v32, v84, 16, 1
	v_bfe_u32 v33, v85, 16, 1
	v_bfe_u32 v36, v72, 16, 1
	v_bfe_u32 v37, v73, 16, 1
	v_add3_u32 v37, v73, v37, s30
	v_add3_u32 v36, v72, v36, s30
	v_add3_u32 v33, v85, v33, s30
	v_add3_u32 v32, v84, v32, s30
	v_lshrrev_b32_e32 v44, 16, v32
	v_lshrrev_b32_e32 v45, 16, v33
	v_lshrrev_b32_e32 v32, 16, v36
	v_lshrrev_b32_e32 v33, 16, v37
	v_and_or_b32 v33, v30, s28, v33
	v_and_or_b32 v32, v31, s28, v32
	v_and_or_b32 v31, v35, s28, v45
	v_and_or_b32 v30, v34, s28, v44
	global_store_dwordx4 v[42:43], v[30:33], off
	s_nop 1
	v_bfe_u32 v32, v47, 16, 1
	v_bfe_u32 v33, v46, 16, 1
	v_add3_u32 v34, v46, v33, s30
	v_add3_u32 v35, v47, v32, s30
	v_bfe_u32 v32, v56, 16, 1
	v_bfe_u32 v33, v57, 16, 1
	v_add3_u32 v33, v57, v33, s30
	v_add3_u32 v32, v56, v32, s30
	v_lshrrev_b32_e32 v42, 16, v32
	v_lshrrev_b32_e32 v43, 16, v33
	v_cvt_pk_bf16_f32 v33, v71, v49
	v_and_or_b32 v30, v34, s28, v42
	v_add_co_u32_e32 v34, vcc, s35, v68
	v_cvt_pk_bf16_f32 v32, v70, v48
	v_and_or_b32 v31, v35, s28, v43
	v_addc_co_u32_e32 v35, vcc, -1, v69, vcc
	global_store_dwordx4 v[34:35], v[30:33], off
	s_nop 1
	v_bfe_u32 v32, v39, 16, 1
	v_bfe_u32 v33, v38, 16, 1
	v_add3_u32 v34, v38, v33, s30
	v_add3_u32 v35, v39, v32, s30
	v_bfe_u32 v32, v82, 16, 1
	v_bfe_u32 v33, v83, 16, 1
	v_add3_u32 v33, v83, v33, s30
	v_add3_u32 v32, v82, v32, s30
	v_lshrrev_b32_e32 v38, 16, v32
	v_lshrrev_b32_e32 v39, 16, v33
	v_cvt_pk_bf16_f32 v33, v41, v89
	v_cvt_pk_bf16_f32 v32, v40, v88
	v_and_or_b32 v31, v35, s28, v39
	v_and_or_b32 v30, v34, s28, v38
	global_store_dwordx4 v[68:69], v[30:33], off offset:-4096
	v_pk_mul_f32 v[34:35], v[18:19], v[80:81]
	v_mov_b64_e32 v[82:83], v[60:61]
	v_pk_mul_f32 v[32:33], v[10:11], v[76:77]
	s_waitcnt vmcnt(7)
	v_lshlrev_b32_e32 v31, 16, v27
	v_pk_fma_f32 v[32:33], v[6:7], v[86:87], v[32:33]
	v_lshlrev_b32_e32 v30, 16, v26
	v_pk_fma_f32 v[32:33], v[14:15], v[52:53], v[32:33]
	v_and_b32_e32 v27, 0xffff0000, v27
	v_pk_mul_f32 v[30:31], v[32:33], v[30:31]
	v_pk_mul_f32 v[32:33], v[12:13], v[74:75]
	v_and_b32_e32 v26, 0xffff0000, v26
	v_pk_fma_f32 v[32:33], v[8:9], v[62:63], v[32:33]
	v_pk_fma_f32 v[34:35], v[2:3], v[90:91], v[34:35]
	v_pk_fma_f32 v[32:33], v[16:17], v[60:61], v[32:33]
	v_pk_fma_f32 v[34:35], v[22:23], v[50:51], v[34:35]
	v_pk_mul_f32 v[26:27], v[32:33], v[26:27]
	v_lshlrev_b32_e32 v33, 16, v29
	v_lshlrev_b32_e32 v32, 16, v28
	v_pk_mul_f32 v[32:33], v[34:35], v[32:33]
	v_pk_mul_f32 v[34:35], v[20:21], v[78:79]
	v_and_b32_e32 v29, 0xffff0000, v29
	v_pk_fma_f32 v[34:35], v[4:5], v[58:59], v[34:35]
	v_and_b32_e32 v28, 0xffff0000, v28
	v_pk_fma_f32 v[34:35], v[24:25], v[54:55], v[34:35]
	v_bfe_u32 v36, v27, 16, 1
	v_pk_mul_f32 v[28:29], v[34:35], v[28:29]
	v_bfe_u32 v37, v26, 16, 1
	v_bfe_u32 v34, v29, 16, 1
	v_bfe_u32 v35, v28, 16, 1
	v_add3_u32 v26, v26, v37, s30
	v_add3_u32 v27, v27, v36, s30
	v_add3_u32 v28, v28, v35, s30
	v_add3_u32 v29, v29, v34, s30
	v_bfe_u32 v34, v30, 16, 1
	v_bfe_u32 v35, v31, 16, 1
	v_bfe_u32 v36, v32, 16, 1
	v_bfe_u32 v37, v33, 16, 1
	v_add3_u32 v33, v33, v37, s30
	v_add3_u32 v32, v32, v36, s30
	v_add3_u32 v31, v31, v35, s30
	v_add3_u32 v30, v30, v34, s30
	v_lshrrev_b32_e32 v30, 16, v30
	v_lshrrev_b32_e32 v31, 16, v31
	v_lshrrev_b32_e32 v32, 16, v32
	v_lshrrev_b32_e32 v33, 16, v33
	v_and_or_b32 v29, v29, s28, v33
	v_and_or_b32 v28, v28, s28, v32
	v_and_or_b32 v27, v27, s28, v31
	v_and_or_b32 v26, v26, s28, v30
	global_store_dwordx4 v[68:69], v[26:29], off
	v_lshl_add_u64 v[68:69], v[68:69], 0, s[24:25]
	v_mov_b64_e32 v[84:85], v[52:53]
	v_mov_b64_e32 v[70:71], v[54:55]
	v_mov_b64_e32 v[72:73], v[50:51]
	s_cbranch_scc0 .LBB0_1114
	v_add_u32_e32 v1, s3, v1
	v_cmp_lt_i32_e32 vcc, s36, v1
	s_or_b64 s[18:19], vcc, s[18:19]
	v_add_u32_e32 v118, s26, v118
	s_andn2_b64 exec, exec, s[18:19]
	s_cbranch_execnz .LBB0_1111

; __device__ __forceinline__ void unpack8(const v4u& w, float (&f)[8]) { f[0] = bflo(w.x); f[1] = bfhi(w.x); f[2] = bflo(w.y); f[3] = bfhi(w.y); f[4] = bflo(w.z); f[5] = bfhi(w.z); f[6] = bflo(w.w); f[7] = bfhi(w.w); }
; __device__ __forceinline__ float wave_sum(float v) {
; #pragma unroll
;     for (int o = 1; o < 64; o <<= 1) v += __shfl_xor(v, o);
;     return v;
; template <bool ZP, bool XF32, bool OUT8 = false>
; __device__ __forceinline__ void norm_phase(LAS unsigned char* lds, const void* xin, const float* gain, const float* sh, const float* sc, bf16* hout, const float* wzt, float* zout, int lane, int wave, int vcu, int G) {
;     ...
;         const int m0 = xdeal ? 2048 * (gw >> 8) + 2 * (gw & 255) + 512 * it_ : 2 * gw + it_ * 2 * NGW;
;         if (m0 >= M) break;
;         f32x4 v[2][4][2]; float ss[2] = {0.f, 0.f};
; #pragma unroll
;         for (int r = 0; r < 2; ++r)
; #pragma unroll
;             for (int j = 0; j < 4; ++j) {
;                 if constexpr (XF32) { const float* xr = (const float*)xin + (size_t)(m0 + r) * D + 8 * lane; v[r][j][0] = *(const f32x4*)(xr + 512 * j); v[r][j][1] = *(const f32x4*)(xr + 512 * j + 4); }
;                 else { float f[8]; unpack8(*(const v4u*)((const bf16*)xin + (size_t)(m0 + r) * D + 8 * lane + 512 * j), f); v[r][j][0] = (f32x4){f[0], f[1], f[2], f[3]}; v[r][j][1] = (f32x4){f[4], f[5], f[6], f[7]}; } }
; #pragma unroll
;         for (int r = 0; r < 2; ++r)
; #pragma unroll
;             for (int j = 0; j < 4; ++j)
; #pragma unroll
;                 for (int e = 0; e < 4; ++e) ss[r] += v[r][j][0][e] * v[r][j][0][e] + v[r][j][1][e] * v[r][j][1][e];
; #pragma unroll
;         for (int r = 0; r < 2; ++r) { const int m = m0 + r, b = m >> 11;
;             const float rstd = rsqrtf(wave_sum(ss[r]) * (1.0f / D) + EPS);
.LBB0_1557:
	s_ashr_i32 s19, s18, 31
	s_lshl_b64 s[24:25], s[18:19], 12
	s_add_i32 s20, s18, 1
	v_lshl_add_u64 v[2:3], v[58:59], 0, s[24:25]
	s_ashr_i32 s21, s20, 31
	global_load_dwordx4 v[18:21], v[2:3], off offset:1024
	global_load_dwordx4 v[10:13], v[2:3], off offset:3072
	global_load_dwordx4 v[14:17], v[2:3], off
	global_load_dwordx4 v[46:49], v[2:3], off offset:2048
	s_lshl_b64 s[22:23], s[20:21], 12
	s_waitcnt lgkmcnt(1)
	v_lshl_add_u64 v[6:7], v[58:59], 0, s[22:23]
	global_load_dwordx4 v[50:53], v[6:7], off offset:1024
	global_load_dwordx4 v[54:57], v[6:7], off
	global_load_dwordx4 v[2:5], v[6:7], off offset:3072
	global_load_dwordx4 v[74:77], v[6:7], off offset:2048
	s_ashr_i32 s0, s18, 11
	s_mul_hi_i32 s1, s0, 0xc000
	s_mul_i32 s0, s0, 0xc000
	s_add_u32 s26, s17, s0
	s_addc_u32 s27, s30, s1
	s_add_u32 s28, s31, s0
	s_addc_u32 s29, s34, s1
	v_and_b32_e32 v1, 64, v216
	v_add_u32_e32 v1, 64, v1
	s_ashr_i32 s0, s20, 11
	s_mul_hi_i32 s1, s0, 0xc000
	s_mul_i32 s0, s0, 0xc000
	s_waitcnt vmcnt(7)
	v_and_b32_e32 v7, 0xffff0000, v18
	s_waitcnt vmcnt(6)
	v_and_b32_e32 v40, 0xffff0000, v12
	v_lshlrev_b32_e32 v41, 16, v12
	v_and_b32_e32 v44, 0xffff0000, v13
	v_lshlrev_b32_e32 v45, 16, v13
	v_and_b32_e32 v38, 0xffff0000, v10
	v_lshlrev_b32_e32 v39, 16, v10
	v_and_b32_e32 v42, 0xffff0000, v11
	v_lshlrev_b32_e32 v43, 16, v11
	s_waitcnt vmcnt(5)
	v_lshlrev_b32_e32 v25, 16, v16
	v_and_b32_e32 v29, 0xffff0000, v16
	s_waitcnt vmcnt(4)
	v_lshlrev_b32_e32 v125, 16, v46
	v_and_b32_e32 v127, 0xffff0000, v46
	v_lshlrev_b32_e32 v129, 16, v47
	v_and_b32_e32 v131, 0xffff0000, v47
	v_lshlrev_b32_e32 v133, 16, v48
	v_and_b32_e32 v137, 0xffff0000, v48
	v_lshlrev_b32_e32 v135, 16, v49
	v_and_b32_e32 v139, 0xffff0000, v49
	v_pk_mul_f32 v[46:47], v[40:41], v[40:41]
	v_pk_mul_f32 v[48:49], v[44:45], v[44:45]
	s_waitcnt vmcnt(2)
	v_lshlrev_b32_e32 v24, 16, v56
	v_and_b32_e32 v28, 0xffff0000, v56
	v_lshlrev_b32_e32 v23, 16, v14
	v_and_b32_e32 v27, 0xffff0000, v14
	v_lshlrev_b32_e32 v31, 16, v17
	v_lshlrev_b32_e32 v22, 16, v54
	v_and_b32_e32 v26, 0xffff0000, v54
	v_lshlrev_b32_e32 v30, 16, v57
	v_pk_fma_f32 v[78:79], v[38:39], v[38:39], v[46:47]
	v_pk_fma_f32 v[88:89], v[42:43], v[42:43], v[48:49]
	v_pk_mul_f32 v[46:47], v[24:25], v[24:25]
	v_pk_mul_f32 v[48:49], v[28:29], v[28:29]
	v_lshlrev_b32_e32 v33, 16, v15
	v_and_b32_e32 v37, 0xffff0000, v17
	v_and_b32_e32 v6, 0xffff0000, v50
	v_lshlrev_b32_e32 v32, 16, v55
	v_and_b32_e32 v36, 0xffff0000, v57
	v_lshlrev_b32_e32 v10, 16, v50
	v_lshlrev_b32_e32 v14, 16, v51
	v_and_b32_e32 v16, 0xffff0000, v51
	v_pk_mul_f32 v[50:51], v[30:31], v[30:31]
	v_pk_fma_f32 v[46:47], v[22:23], v[22:23], v[46:47]
	v_pk_fma_f32 v[48:49], v[26:27], v[26:27], v[48:49]
	s_waitcnt lgkmcnt(0)
	v_and_b32_e32 v9, 0xffff0000, v20
	v_and_b32_e32 v35, 0xffff0000, v15
	v_lshlrev_b32_e32 v11, 16, v18
	v_lshlrev_b32_e32 v13, 16, v20
	v_and_b32_e32 v8, 0xffff0000, v52
	v_and_b32_e32 v34, 0xffff0000, v55
	v_lshlrev_b32_e32 v12, 16, v52
	v_lshlrev_b32_e32 v18, 16, v53
	v_and_b32_e32 v20, 0xffff0000, v53
	v_pk_mul_f32 v[52:53], v[36:37], v[36:37]
	v_pk_fma_f32 v[50:51], v[32:33], v[32:33], v[50:51]
	v_pk_add_f32 v[46:47], v[46:47], v[48:49]
	v_pk_fma_f32 v[48:49], v[34:35], v[34:35], v[52:53]
	v_pk_add_f32 v[46:47], v[50:51], v[46:47]
	v_lshlrev_b32_e32 v15, 16, v19
	v_pk_add_f32 v[46:47], v[48:49], v[46:47]
	v_pk_mul_f32 v[48:49], v[12:13], v[12:13]
	v_and_b32_e32 v17, 0xffff0000, v19
	v_pk_fma_f32 v[48:49], v[10:11], v[10:11], v[48:49]
	v_lshlrev_b32_e32 v19, 16, v21
	v_pk_add_f32 v[46:47], v[48:49], v[46:47]
	v_pk_mul_f32 v[48:49], v[8:9], v[8:9]
	v_and_b32_e32 v21, 0xffff0000, v21
	v_pk_fma_f32 v[48:49], v[6:7], v[6:7], v[48:49]
	s_waitcnt vmcnt(1)
	v_and_b32_e32 v140, 0xffff0000, v4
	v_pk_add_f32 v[46:47], v[48:49], v[46:47]
	v_pk_mul_f32 v[48:49], v[18:19], v[18:19]
	v_lshlrev_b32_e32 v141, 16, v4
	v_pk_fma_f32 v[48:49], v[14:15], v[14:15], v[48:49]
	s_waitcnt vmcnt(0)
	v_lshlrev_b32_e32 v132, 16, v76
	v_pk_add_f32 v[46:47], v[48:49], v[46:47]
	v_pk_mul_f32 v[48:49], v[20:21], v[20:21]
	v_and_b32_e32 v142, 0xffff0000, v2
	v_lshlrev_b32_e32 v143, 16, v2
	v_lshlrev_b32_e32 v124, 16, v74
	v_pk_mul_f32 v[54:55], v[140:141], v[140:141]
	v_pk_fma_f32 v[48:49], v[16:17], v[16:17], v[48:49]
	v_pk_mul_f32 v[56:57], v[132:133], v[132:133]
	v_and_b32_e32 v136, 0xffff0000, v76
	v_pk_fma_f32 v[90:91], v[142:143], v[142:143], v[54:55]
	v_pk_add_f32 v[54:55], v[48:49], v[46:47]
	v_pk_fma_f32 v[56:57], v[124:125], v[124:125], v[56:57]
	v_and_b32_e32 v126, 0xffff0000, v74
	v_pk_add_f32 v[54:55], v[56:57], v[54:55]
	v_pk_mul_f32 v[56:57], v[136:137], v[136:137]
	v_lshlrev_b32_e32 v134, 16, v77
	v_pk_fma_f32 v[56:57], v[126:127], v[126:127], v[56:57]
	v_lshlrev_b32_e32 v128, 16, v75
	v_pk_add_f32 v[54:55], v[56:57], v[54:55]
	v_pk_mul_f32 v[56:57], v[134:135], v[134:135]
	v_and_b32_e32 v138, 0xffff0000, v77
	v_pk_fma_f32 v[56:57], v[128:129], v[128:129], v[56:57]
	v_and_b32_e32 v130, 0xffff0000, v75
	v_pk_add_f32 v[54:55], v[56:57], v[54:55]
	v_pk_mul_f32 v[56:57], v[138:139], v[138:139]
	global_load_dwordx4 v[46:49], v213, s[26:27] offset:16
	global_load_dwordx4 v[50:53], v213, s[26:27]
	v_pk_fma_f32 v[56:57], v[130:131], v[130:131], v[56:57]
	v_and_b32_e32 v146, 0xffff0000, v5
	v_pk_add_f32 v[54:55], v[56:57], v[54:55]
	v_mov_b32_e32 v56, v91
	v_mov_b32_e32 v57, v79
	v_pk_add_f32 v[92:93], v[56:57], v[54:55]
	global_load_dwordx4 v[54:57], v[62:63], off offset:16
	global_load_dwordx4 v[74:77], v[62:63], off
	global_load_dwordx4 v[80:83], v213, s[28:29] offset:16
	global_load_dwordx4 v[84:87], v213, s[28:29]
	v_lshlrev_b32_e32 v147, 16, v5
	v_xor_b32_e32 v4, 1, v216
	v_and_b32_e32 v144, 0xffff0000, v3
	v_lshlrev_b32_e32 v145, 16, v3
	v_pk_mul_f32 v[2:3], v[146:147], v[146:147]
	v_cmp_lt_i32_e32 vcc, v4, v1
	v_pk_fma_f32 v[2:3], v[144:145], v[144:145], v[2:3]
	v_mov_b32_e32 v91, v78
	v_cndmask_b32_e32 v4, v216, v4, vcc
	v_lshlrev_b32_e32 v217, 2, v4
	v_pk_add_f32 v[4:5], v[90:91], v[92:93]
	v_mov_b32_e32 v78, v3
	v_mov_b32_e32 v79, v89
	v_pk_add_f32 v[4:5], v[78:79], v[4:5]
	v_mov_b32_e32 v3, v88
	v_pk_add_f32 v[2:3], v[2:3], v[4:5]
	ds_bpermute_b32 v5, v217, v3
	ds_bpermute_b32 v4, v217, v2
	v_xor_b32_e32 v78, 2, v216
	v_cmp_lt_i32_e32 vcc, v78, v1
	v_mov_b32_e32 v90, v23
	v_mov_b32_e32 v91, v27
	v_cndmask_b32_e32 v78, v216, v78, vcc
	v_lshlrev_b32_e32 v218, 2, v78
	s_waitcnt lgkmcnt(0)
; __device__ __forceinline__ unsigned pk2(float lo, float hi) { return f2bf(lo) | (f2bf(hi) << 16); }
; template <bool ZP, bool XF32, bool OUT8 = false>
; __device__ __forceinline__ void norm_phase(LAS unsigned char* lds, const void* xin, const float* gain, const float* sh, const float* sc, bf16* hout, const float* wzt, float* zout, int lane, int wave, int vcu, int G) {
;     ...
;         for (int r = 0; r < 2; ++r) { const int m = m0 + r, b = m >> 11;
;             const float rstd = rsqrtf(wave_sum(ss[r]) * (1.0f / D) + EPS);
; #pragma unroll
;             for (int j = 0; j < 4; ++j) { const int col = 512 * j + 8 * lane;
; #pragma unroll
;                 for (int q = 0; q < 2; ++q) { const f32x4 gg = *(const f32x4*)(gain + col + 4 * q), s1 = *(const f32x4*)(sc + (size_t)b * MODW + col + 4 * q), s0 = *(const f32x4*)(sh + (size_t)b * MODW + col + 4 * q);
;                     v[r][j][q] = (v[r][j][q] * rstd * gg) * (s1 + 1.0f) + s0; }
;                 if constexpr (OUT8) { *(v2u*)((unsigned char*)hout + (size_t)m * D + col) = pack8_fp8(v[r][j][0][0], v[r][j][0][1], v[r][j][0][2], v[r][j][0][3], v[r][j][1][0], v[r][j][1][1], v[r][j][1][2], v[r][j][1][3], FP8_ASCALE); }
;                 else { v4u o; o.x = pk2(v[r][j][0][0], v[r][j][0][1]); o.y = pk2(v[r][j][0][2], v[r][j][0][3]); o.z = pk2(v[r][j][1][0], v[r][j][1][1]); o.w = pk2(v[r][j][1][2], v[r][j][1][3]);
;                     *(v4u*)(hout + (size_t)m * D + col) = o; } }
	v_pk_add_f32 v[2:3], v[2:3], v[4:5]
	ds_bpermute_b32 v5, v218, v3
	ds_bpermute_b32 v4, v218, v2
	v_xor_b32_e32 v78, 4, v216
	v_cmp_lt_i32_e32 vcc, v78, v1
	v_mov_b32_e32 v79, v35
	v_mov_b32_e32 v110, v133
	v_cndmask_b32_e32 v78, v216, v78, vcc
	v_lshlrev_b32_e32 v219, 2, v78
	s_waitcnt lgkmcnt(0)
	v_pk_add_f32 v[2:3], v[2:3], v[4:5]
	ds_bpermute_b32 v5, v219, v3
	ds_bpermute_b32 v4, v219, v2
	v_xor_b32_e32 v78, 8, v216
	v_cmp_lt_i32_e32 vcc, v78, v1
	v_mov_b32_e32 v111, v137
	v_mov_b32_e32 v108, v135
	v_cndmask_b32_e32 v78, v216, v78, vcc
	v_lshlrev_b32_e32 v220, 2, v78
	s_waitcnt lgkmcnt(0)
	v_pk_add_f32 v[2:3], v[2:3], v[4:5]
	ds_bpermute_b32 v5, v220, v3
	ds_bpermute_b32 v4, v220, v2
	v_xor_b32_e32 v78, 16, v216
	v_cmp_lt_i32_e32 vcc, v78, v1
	v_mov_b32_e32 v109, v139
	v_pk_mov_b32 v[42:43], v[42:43], v[42:43] op_sel:[1,0]
	v_cndmask_b32_e32 v78, v216, v78, vcc
	v_lshlrev_b32_e32 v221, 2, v78
	s_waitcnt lgkmcnt(0)
	v_pk_add_f32 v[2:3], v[2:3], v[4:5]
	ds_bpermute_b32 v5, v221, v3
	ds_bpermute_b32 v4, v221, v2
	v_xor_b32_e32 v78, 32, v216
	v_cmp_lt_i32_e32 vcc, v78, v1
	v_pk_mov_b32 v[44:45], v[44:45], v[44:45] op_sel:[1,0]
	v_mov_b32_e32 v23, v26
	v_cndmask_b32_e32 v1, v216, v78, vcc
	v_lshlrev_b32_e32 v222, 2, v1
	s_waitcnt lgkmcnt(0)
	v_pk_add_f32 v[2:3], v[2:3], v[4:5]
	ds_bpermute_b32 v5, v222, v3
	ds_bpermute_b32 v4, v222, v2
	v_mov_b32_e32 v78, v33
	v_mov_b32_e32 v33, v34
	v_mov_b32_e32 v135, v138
	v_mov_b32_e32 v133, v136
	s_waitcnt lgkmcnt(0)
	v_pk_add_f32 v[2:3], v[2:3], v[4:5]
	v_lshl_add_u64 v[4:5], v[70:71], 0, s[24:25]
	v_pk_fma_f32 v[2:3], v[2:3], s[16:17], v[72:73] op_sel_hi:[1,0,0]
	s_add_u32 s24, s17, s0
	v_mul_f32_e32 v1, 0x4b800000, v3
	v_cmp_gt_f32_e32 vcc, s40, v3
	s_waitcnt vmcnt(5)
	v_pk_add_f32 v[88:89], v[46:47], 1.0 op_sel_hi:[1,0]
	s_waitcnt vmcnt(4)
	v_pk_add_f32 v[50:51], v[50:51], 1.0 op_sel_hi:[1,0]
	v_cndmask_b32_e32 v1, v3, v1, vcc
	v_rsq_f32_e32 v1, v1
	v_pk_add_f32 v[52:53], v[52:53], 1.0 op_sel_hi:[1,0]
	v_pk_add_f32 v[48:49], v[48:49], 1.0 op_sel_hi:[1,0]
	s_addc_u32 s25, s30, s1
	v_mul_f32_e32 v3, 0x45800000, v1
	v_cndmask_b32_e32 v46, v1, v3, vcc
	v_pk_mul_f32 v[90:91], v[46:47], v[90:91] op_sel_hi:[0,1]
	v_pk_mul_f32 v[78:79], v[46:47], v[78:79] op_sel_hi:[0,1]
	s_waitcnt vmcnt(2)
	v_pk_mul_f32 v[90:91], v[74:75], v[90:91]
	v_pk_mul_f32 v[74:75], v[76:77], v[78:79]
	s_waitcnt vmcnt(0)
	v_pk_fma_f32 v[78:79], v[50:51], v[90:91], v[84:85]
	v_mov_b32_e32 v50, v31
	v_mov_b32_e32 v51, v37
	v_pk_mul_f32 v[50:51], v[46:47], v[50:51] op_sel_hi:[0,1]
	v_pk_fma_f32 v[74:75], v[52:53], v[74:75], v[86:87]
	v_mov_b32_e32 v52, v25
	v_mov_b32_e32 v53, v29
	v_pk_mul_f32 v[50:51], v[56:57], v[50:51]
	v_pk_mul_f32 v[52:53], v[46:47], v[52:53] op_sel_hi:[0,1]
	v_pk_fma_f32 v[76:77], v[48:49], v[50:51], v[82:83]
	v_cvt_pk_bf16_f32 v48, v78, v79
	v_pk_mul_f32 v[52:53], v[54:55], v[52:53]
	v_pk_fma_f32 v[82:83], v[88:89], v[52:53], v[80:81]
	v_cvt_pk_bf16_f32 v49, v74, v75
	v_cvt_pk_bf16_f32 v50, v82, v83
	v_cvt_pk_bf16_f32 v51, v76, v77
	global_store_dwordx4 v[4:5], v[48:51], off
	global_load_dwordx4 v[48:51], v[64:65], off
	s_nop 0
	global_load_dwordx4 v[52:55], v213, s[26:27] offset:2048
	global_load_dwordx4 v[84:87], v213, s[28:29] offset:2048
	global_load_dwordx4 v[88:91], v[64:65], off offset:16
	global_load_dwordx4 v[92:95], v213, s[26:27] offset:2064
	global_load_dwordx4 v[96:99], v213, s[28:29] offset:2064
	v_mov_b32_e32 v80, v11
	v_mov_b32_e32 v81, v7
	v_pk_mul_f32 v[80:81], v[46:47], v[80:81] op_sel_hi:[0,1]
	v_mov_b32_e32 v56, v15
	v_mov_b32_e32 v57, v17
	v_pk_mul_f32 v[56:57], v[46:47], v[56:57] op_sel_hi:[0,1]
	v_pk_mul_f32 v[108:109], v[46:47], v[108:109] op_sel_hi:[0,1]
	v_pk_mul_f32 v[44:45], v[46:47], v[44:45] op_sel_hi:[0,1]
	v_cmp_gt_f32_e32 vcc, s40, v2
	v_mov_b32_e32 v31, v36
	v_mov_b32_e32 v25, v28
	v_mov_b32_e32 v136, v143
	v_mov_b32_e32 v137, v142
	v_mov_b32_e32 v138, v141
	v_mov_b32_e32 v139, v140
	v_pk_mov_b32 v[144:145], v[144:145], v[144:145] op_sel:[1,0]
	v_pk_mov_b32 v[146:147], v[146:147], v[146:147] op_sel:[1,0]
	s_waitcnt vmcnt(5)
	v_pk_mul_f32 v[48:49], v[48:49], v[80:81]
	s_waitcnt vmcnt(4)
	v_pk_add_f32 v[52:53], v[52:53], 1.0 op_sel_hi:[1,0]
	v_pk_mul_f32 v[50:51], v[50:51], v[56:57]
	s_waitcnt vmcnt(3)
	v_pk_fma_f32 v[84:85], v[52:53], v[48:49], v[84:85]
	v_mov_b32_e32 v48, v19
	v_mov_b32_e32 v49, v21
	v_pk_add_f32 v[54:55], v[54:55], 1.0 op_sel_hi:[1,0]
	v_pk_mul_f32 v[48:49], v[46:47], v[48:49] op_sel_hi:[0,1]
	v_pk_fma_f32 v[80:81], v[54:55], v[50:51], v[86:87]
	v_mov_b32_e32 v50, v13
	v_mov_b32_e32 v51, v9
	s_waitcnt vmcnt(2)
	v_pk_mul_f32 v[48:49], v[90:91], v[48:49]
	s_waitcnt vmcnt(1)
	v_pk_add_f32 v[52:53], v[94:95], 1.0 op_sel_hi:[1,0]
	v_pk_mul_f32 v[50:51], v[46:47], v[50:51] op_sel_hi:[0,1]
	s_waitcnt vmcnt(0)
	v_pk_fma_f32 v[86:87], v[52:53], v[48:49], v[98:99]
	v_cvt_pk_bf16_f32 v48, v84, v85
	v_pk_mul_f32 v[50:51], v[88:89], v[50:51]
	v_pk_add_f32 v[54:55], v[92:93], 1.0 op_sel_hi:[1,0]
	v_pk_fma_f32 v[88:89], v[54:55], v[50:51], v[96:97]
	v_cvt_pk_bf16_f32 v49, v80, v81
	v_cvt_pk_bf16_f32 v50, v88, v89
	v_cvt_pk_bf16_f32 v51, v86, v87
	global_store_dwordx4 v[4:5], v[48:51], off offset:1024
	global_load_dwordx4 v[48:51], v[66:67], off
	s_nop 0
	global_load_dwordx4 v[52:55], v214, s[26:27]
	global_load_dwordx4 v[92:95], v214, s[28:29]
	global_load_dwordx4 v[96:99], v[66:67], off offset:16
	global_load_dwordx4 v[100:103], v214, s[26:27] offset:16
	global_load_dwordx4 v[104:107], v214, s[28:29] offset:16
	v_mov_b32_e32 v56, v129
	v_mov_b32_e32 v57, v131
	v_mov_b32_e32 v90, v125
	v_mov_b32_e32 v91, v127
	v_pk_mul_f32 v[56:57], v[46:47], v[56:57] op_sel_hi:[0,1]
	v_pk_mul_f32 v[90:91], v[46:47], v[90:91] op_sel_hi:[0,1]
	v_mov_b32_e32 v19, v20
	v_mov_b32_e32 v129, v130
	v_mov_b32_e32 v125, v126
	s_waitcnt vmcnt(5)
; __device__ __forceinline__ unsigned pk2(float lo, float hi) { return f2bf(lo) | (f2bf(hi) << 16); }
; template <bool ZP, bool XF32, bool OUT8 = false>
; __device__ __forceinline__ void norm_phase(LAS unsigned char* lds, const void* xin, const float* gain, const float* sh, const float* sc, bf16* hout, const float* wzt, float* zout, int lane, int wave, int vcu, int G) {
;     ...
;         for (int r = 0; r < 2; ++r) { const int m = m0 + r, b = m >> 11;
;             const float rstd = rsqrtf(wave_sum(ss[r]) * (1.0f / D) + EPS);
; #pragma unroll
;             for (int j = 0; j < 4; ++j) { const int col = 512 * j + 8 * lane;
; #pragma unroll
;                 for (int q = 0; q < 2; ++q) { const f32x4 gg = *(const f32x4*)(gain + col + 4 * q), s1 = *(const f32x4*)(sc + (size_t)b * MODW + col + 4 * q), s0 = *(const f32x4*)(sh + (size_t)b * MODW + col + 4 * q);
;                     v[r][j][q] = (v[r][j][q] * rstd * gg) * (s1 + 1.0f) + s0; }
;                 if constexpr (OUT8) { *(v2u*)((unsigned char*)hout + (size_t)m * D + col) = pack8_fp8(v[r][j][0][0], v[r][j][0][1], v[r][j][0][2], v[r][j][0][3], v[r][j][1][0], v[r][j][1][1], v[r][j][1][2], v[r][j][1][3], FP8_ASCALE); }
;                 else { v4u o; o.x = pk2(v[r][j][0][0], v[r][j][0][1]); o.y = pk2(v[r][j][0][2], v[r][j][0][3]); o.z = pk2(v[r][j][1][0], v[r][j][1][1]); o.w = pk2(v[r][j][1][2], v[r][j][1][3]);
;                     *(v4u*)(hout + (size_t)m * D + col) = o; } }
	v_pk_mul_f32 v[48:49], v[48:49], v[90:91]
	v_pk_mul_f32 v[50:51], v[50:51], v[56:57]
	s_waitcnt vmcnt(4)
	v_pk_add_f32 v[54:55], v[54:55], 1.0 op_sel_hi:[1,0]
	v_pk_add_f32 v[52:53], v[52:53], 1.0 op_sel_hi:[1,0]
	s_waitcnt vmcnt(3)
	v_pk_fma_f32 v[90:91], v[54:55], v[50:51], v[94:95]
	v_pk_fma_f32 v[94:95], v[52:53], v[48:49], v[92:93]
	v_pk_mul_f32 v[48:49], v[46:47], v[110:111] op_sel_hi:[0,1]
	s_waitcnt vmcnt(2)
	v_pk_mul_f32 v[48:49], v[96:97], v[48:49]
	s_waitcnt vmcnt(1)
	v_pk_add_f32 v[54:55], v[100:101], 1.0 op_sel_hi:[1,0]
	s_waitcnt vmcnt(0)
	v_pk_fma_f32 v[96:97], v[54:55], v[48:49], v[104:105]
	v_cvt_pk_bf16_f32 v48, v94, v95
	v_cvt_pk_bf16_f32 v49, v90, v91
	v_pk_mul_f32 v[50:51], v[98:99], v[108:109]
	v_pk_add_f32 v[52:53], v[102:103], 1.0 op_sel_hi:[1,0]
	v_pk_fma_f32 v[92:93], v[52:53], v[50:51], v[106:107]
	v_cvt_pk_bf16_f32 v50, v96, v97
	v_cvt_pk_bf16_f32 v51, v92, v93
	global_store_dwordx4 v[4:5], v[48:51], off offset:2048
	global_load_dwordx4 v[48:51], v[68:69], off
	s_nop 0
	global_load_dwordx4 v[52:55], v215, s[26:27]
	global_load_dwordx4 v[98:101], v[68:69], off offset:16
	global_load_dwordx4 v[102:105], v215, s[26:27] offset:16
	global_load_dwordx4 v[106:109], v215, s[28:29]
	global_load_dwordx4 v[110:113], v215, s[28:29] offset:16
	v_mov_b32_e32 v56, v39
	v_mov_b32_e32 v57, v38
	v_mov_b32_e32 v38, v41
	v_mov_b32_e32 v39, v40
	v_pk_mul_f32 v[40:41], v[46:47], v[42:43] op_sel_hi:[0,1]
	v_pk_mul_f32 v[42:43], v[46:47], v[56:57] op_sel_hi:[0,1]
	v_pk_mul_f32 v[38:39], v[46:47], v[38:39] op_sel_hi:[0,1]
	s_add_u32 s26, s31, s0
	s_addc_u32 s27, s34, s1
	s_waitcnt vmcnt(5)
	v_pk_mul_f32 v[42:43], v[48:49], v[42:43]
	v_pk_mul_f32 v[40:41], v[50:51], v[40:41]
	s_waitcnt vmcnt(4)
	v_pk_add_f32 v[46:47], v[54:55], 1.0 op_sel_hi:[1,0]
	v_pk_add_f32 v[48:49], v[52:53], 1.0 op_sel_hi:[1,0]
	s_waitcnt vmcnt(3)
	v_pk_mul_f32 v[38:39], v[38:39], v[98:99]
	v_pk_mul_f32 v[44:45], v[44:45], v[100:101]
	s_waitcnt vmcnt(2)
	v_pk_add_f32 v[50:51], v[104:105], 1.0 op_sel_hi:[1,0]
	v_pk_add_f32 v[52:53], v[102:103], 1.0 op_sel_hi:[1,0]
	s_waitcnt vmcnt(1)
	v_pk_fma_f32 v[100:101], v[40:41], v[46:47], v[108:109]
	v_pk_fma_f32 v[104:105], v[42:43], v[48:49], v[106:107]
	s_waitcnt vmcnt(0)
	v_pk_fma_f32 v[102:103], v[44:45], v[50:51], v[112:113]
	v_pk_fma_f32 v[106:107], v[38:39], v[52:53], v[110:111]
	v_cvt_pk_bf16_f32 v38, v104, v105
	v_cvt_pk_bf16_f32 v39, v100, v101
	v_cvt_pk_bf16_f32 v40, v106, v107
	v_cvt_pk_bf16_f32 v41, v102, v103
	global_store_dwordx4 v[4:5], v[38:41], off offset:3072
	global_load_dwordx4 v[38:41], v[62:63], off
	s_nop 0
	global_load_dwordx4 v[42:45], v213, s[24:25]
	global_load_dwordx4 v[46:49], v[62:63], off offset:16
	global_load_dwordx4 v[50:53], v213, s[24:25] offset:16
	global_load_dwordx4 v[54:57], v213, s[26:27]
	global_load_dwordx4 v[114:117], v213, s[26:27] offset:16
	v_mul_f32_e32 v1, 0x4b800000, v2
	v_cndmask_b32_e32 v1, v2, v1, vcc
	v_rsq_f32_e32 v1, v1
	v_lshl_add_u64 v[98:99], v[70:71], 0, s[22:23]
	v_mov_b32_e32 v13, v8
	v_mov_b32_e32 v15, v16
	v_mul_f32_e32 v2, 0x45800000, v1
	v_cndmask_b32_e32 v148, v1, v2, vcc
	v_pk_mul_f32 v[2:3], v[148:149], v[32:33] op_sel_hi:[0,1]
	v_pk_mul_f32 v[4:5], v[148:149], v[22:23] op_sel_hi:[0,1]
	v_pk_mul_f32 v[22:23], v[148:149], v[30:31] op_sel_hi:[0,1]
	v_pk_mul_f32 v[24:25], v[148:149], v[24:25] op_sel_hi:[0,1]
	v_pk_mul_f32 v[12:13], v[148:149], v[12:13] op_sel_hi:[0,1]
	v_pk_mul_f32 v[126:127], v[148:149], v[128:129] op_sel_hi:[0,1]
	v_pk_mul_f32 v[124:125], v[148:149], v[124:125] op_sel_hi:[0,1]
	v_pk_mul_f32 v[128:129], v[148:149], v[134:135] op_sel_hi:[0,1]
	v_pk_mul_f32 v[130:131], v[148:149], v[132:133] op_sel_hi:[0,1]
	v_pk_mul_f32 v[242:243], v[148:149], v[136:137] op_sel_hi:[0,1]
	v_pk_mul_f32 v[246:247], v[148:149], v[138:139] op_sel_hi:[0,1]
	v_pk_mul_f32 v[240:241], v[148:149], v[144:145] op_sel_hi:[0,1]
	v_pk_mul_f32 v[244:245], v[148:149], v[146:147] op_sel_hi:[0,1]
	s_waitcnt vmcnt(4)
	v_pk_add_f32 v[26:27], v[44:45], 1.0 op_sel_hi:[1,0]
	v_pk_mul_f32 v[4:5], v[38:39], v[4:5]
	v_pk_mul_f32 v[2:3], v[40:41], v[2:3]
	v_pk_add_f32 v[28:29], v[42:43], 1.0 op_sel_hi:[1,0]
	s_waitcnt vmcnt(3)
	v_pk_mul_f32 v[24:25], v[46:47], v[24:25]
	v_pk_mul_f32 v[22:23], v[48:49], v[22:23]
	s_waitcnt vmcnt(2)
	v_pk_add_f32 v[30:31], v[52:53], 1.0 op_sel_hi:[1,0]
	v_pk_add_f32 v[32:33], v[50:51], 1.0 op_sel_hi:[1,0]
	s_waitcnt vmcnt(1)
	v_pk_fma_f32 v[108:109], v[26:27], v[2:3], v[56:57]
	v_pk_fma_f32 v[112:113], v[28:29], v[4:5], v[54:55]
	s_waitcnt vmcnt(0)
	v_pk_fma_f32 v[110:111], v[30:31], v[22:23], v[116:117]
	v_pk_fma_f32 v[114:115], v[32:33], v[24:25], v[114:115]
	v_cvt_pk_bf16_f32 v2, v112, v113
	v_cvt_pk_bf16_f32 v3, v108, v109
	v_cvt_pk_bf16_f32 v4, v114, v115
	v_cvt_pk_bf16_f32 v5, v110, v111
	global_store_dwordx4 v[98:99], v[2:5], off
	global_load_dwordx4 v[2:5], v[64:65], off
	s_nop 0
	global_load_dwordx4 v[22:25], v213, s[24:25] offset:2048
	global_load_dwordx4 v[26:29], v[64:65], off offset:16
	global_load_dwordx4 v[30:33], v213, s[24:25] offset:2064
	global_load_dwordx4 v[34:37], v213, s[26:27] offset:2048
	global_load_dwordx4 v[38:41], v213, s[26:27] offset:2064
	v_mov_b32_e32 v11, v6
	v_pk_mul_f32 v[6:7], v[148:149], v[14:15] op_sel_hi:[0,1]
	v_pk_mul_f32 v[8:9], v[148:149], v[10:11] op_sel_hi:[0,1]
	v_pk_mul_f32 v[10:11], v[148:149], v[18:19] op_sel_hi:[0,1]
	s_waitcnt vmcnt(5)
	v_pk_mul_f32 v[2:3], v[2:3], v[8:9]
	v_pk_mul_f32 v[4:5], v[4:5], v[6:7]
	s_waitcnt vmcnt(4)
	v_pk_add_f32 v[6:7], v[24:25], 1.0 op_sel_hi:[1,0]
	v_pk_add_f32 v[8:9], v[22:23], 1.0 op_sel_hi:[1,0]
	s_waitcnt vmcnt(3)
; #define LAS __attribute__((address_space(3)))
; __device__ __forceinline__ unsigned pk2(float lo, float hi) { return f2bf(lo) | (f2bf(hi) << 16); }
; template <bool ZP, bool XF32, bool OUT8 = false>
; __device__ __forceinline__ void norm_phase(LAS unsigned char* lds, const void* xin, const float* gain, const float* sh, const float* sc, bf16* hout, const float* wzt, float* zout, int lane, int wave, int vcu, int G) {
;     ...
;             for (int j = 0; j < 4; ++j) { const int col = 512 * j + 8 * lane;
; #pragma unroll
;                 for (int q = 0; q < 2; ++q) { const f32x4 gg = *(const f32x4*)(gain + col + 4 * q), s1 = *(const f32x4*)(sc + (size_t)b * MODW + col + 4 * q), s0 = *(const f32x4*)(sh + (size_t)b * MODW + col + 4 * q);
;                     v[r][j][q] = (v[r][j][q] * rstd * gg) * (s1 + 1.0f) + s0; }
;                 if constexpr (OUT8) { *(v2u*)((unsigned char*)hout + (size_t)m * D + col) = pack8_fp8(v[r][j][0][0], v[r][j][0][1], v[r][j][0][2], v[r][j][0][3], v[r][j][1][0], v[r][j][1][1], v[r][j][1][2], v[r][j][1][3], FP8_ASCALE); }
;                 else { v4u o; o.x = pk2(v[r][j][0][0], v[r][j][0][1]); o.y = pk2(v[r][j][0][2], v[r][j][0][3]); o.z = pk2(v[r][j][1][0], v[r][j][1][1]); o.w = pk2(v[r][j][1][2], v[r][j][1][3]);
;                     *(v4u*)(hout + (size_t)m * D + col) = o; } }
;         }
;         if constexpr (ZP) {
;             float p0[16], p1[16];
; #pragma unroll
;             for (int rr = 0; rr < 16; ++rr) { p0[rr] = 0.f; p1[rr] = 0.f;
; #pragma unroll
;                 for (int j = 0; j < 4; ++j) { const f32x4 w0 = *(const LAS f32x4*)(wl + (((rr * 4 + j) * 2 + 0) * 64 + lane) * 4), w1 = *(const LAS f32x4*)(wl + (((rr * 4 + j) * 2 + 1) * 64 + lane) * 4);
; #pragma unroll
;                     for (int e = 0; e < 4; ++e) { p0[rr] += v[0][j][0][e] * w0[e] + v[0][j][1][e] * w1[e]; p1[rr] += v[1][j][0][e] * w0[e] + v[1][j][1][e] * w1[e]; } } }
	v_pk_mul_f32 v[12:13], v[26:27], v[12:13]
	v_pk_mul_f32 v[10:11], v[28:29], v[10:11]
	s_waitcnt vmcnt(2)
	v_pk_add_f32 v[14:15], v[32:33], 1.0 op_sel_hi:[1,0]
	v_pk_add_f32 v[16:17], v[30:31], 1.0 op_sel_hi:[1,0]
	s_waitcnt vmcnt(1)
	v_pk_fma_f32 v[116:117], v[6:7], v[4:5], v[36:37]
	v_pk_fma_f32 v[120:121], v[8:9], v[2:3], v[34:35]
	s_waitcnt vmcnt(0)
	v_pk_fma_f32 v[118:119], v[14:15], v[10:11], v[40:41]
	v_pk_fma_f32 v[122:123], v[16:17], v[12:13], v[38:39]
	v_cvt_pk_bf16_f32 v2, v120, v121
	v_cvt_pk_bf16_f32 v3, v116, v117
	v_cvt_pk_bf16_f32 v4, v122, v123
	v_cvt_pk_bf16_f32 v5, v118, v119
	global_store_dwordx4 v[98:99], v[2:5], off offset:1024
	global_load_dwordx4 v[10:13], v[66:67], off
	global_load_dwordx4 v[14:17], v214, s[24:25]
	global_load_dwordx4 v[6:9], v[66:67], off offset:16
	s_nop 0
	global_load_dwordx4 v[2:5], v214, s[24:25] offset:16
	ds_read_b128 v[18:21], v73
	ds_read_b128 v[22:25], v73 offset:1024
	global_load_dwordx4 v[224:227], v214, s[26:27] offset:16
	global_load_dwordx4 v[228:231], v214, s[26:27]
	ds_read_b128 v[26:29], v73 offset:2048
	ds_read_b128 v[30:33], v73 offset:3072
	ds_read_b128 v[38:41], v73 offset:4096
	ds_read_b128 v[42:45], v73 offset:5120
	ds_read_b128 v[34:37], v73 offset:6144
	ds_read_b128 v[46:49], v73 offset:7168
	ds_read_b128 v[232:235], v73 offset:8192
	ds_read_b128 v[236:239], v73 offset:9216
	ds_read_b128 v[50:53], v73 offset:10240
	ds_read_b128 v[54:57], v73 offset:11264
	s_waitcnt lgkmcnt(6)
	v_mul_f32_e32 v223, v96, v42
	v_fmac_f32_e32 v223, v94, v38
	v_mul_f32_e32 v1, v82, v22
	v_mul_f32_e32 v132, v83, v23
	v_fmac_f32_e32 v1, v78, v18
	v_mul_f32_e32 v133, v76, v24
	s_waitcnt lgkmcnt(2)
	v_mul_f32_e32 v135, v82, v236
	v_fmac_f32_e32 v132, v79, v19
	v_add_f32_e32 v1, 0, v1
	v_mul_f32_e32 v134, v77, v25
	v_mul_f32_e32 v136, v83, v237
	v_fmac_f32_e32 v133, v74, v20
	v_fmac_f32_e32 v135, v78, v232
	v_add_f32_e32 v1, v132, v1
	v_mul_f32_e32 v137, v76, v238
	v_fmac_f32_e32 v134, v75, v21
	v_fmac_f32_e32 v136, v79, v233
	v_add_f32_e32 v135, 0, v135
	v_add_f32_e32 v1, v133, v1
	v_mul_f32_e32 v133, v88, v30
	v_mul_f32_e32 v138, v77, v239
	v_fmac_f32_e32 v137, v74, v234
	v_add_f32_e32 v132, v136, v135
	v_add_f32_e32 v1, v134, v1
	v_mul_f32_e32 v134, v89, v31
	v_fmac_f32_e32 v133, v84, v26
	v_fmac_f32_e32 v138, v75, v235
	v_add_f32_e32 v132, v137, v132
	v_mul_f32_e32 v135, v86, v32
	s_waitcnt lgkmcnt(0)
	v_mul_f32_e32 v137, v88, v54
	v_fmac_f32_e32 v134, v85, v27
	v_add_f32_e32 v1, v133, v1
	v_add_f32_e32 v132, v138, v132
	v_mul_f32_e32 v136, v87, v33
	v_mul_f32_e32 v138, v89, v55
	v_fmac_f32_e32 v135, v80, v28
	v_fmac_f32_e32 v137, v84, v50
	v_add_f32_e32 v1, v134, v1
	v_fmac_f32_e32 v136, v81, v29
	v_fmac_f32_e32 v138, v85, v51
	v_add_f32_e32 v132, v137, v132
	v_add_f32_e32 v1, v135, v1
	v_add_f32_e32 v148, v138, v132
	v_add_f32_e32 v1, v136, v1
	v_add_f32_e32 v1, v223, v1
	s_waitcnt vmcnt(5)
	v_pk_mul_f32 v[10:11], v[124:125], v[10:11]
	v_pk_mul_f32 v[12:13], v[126:127], v[12:13]
	s_waitcnt vmcnt(4)
	v_pk_add_f32 v[16:17], v[16:17], 1.0 op_sel_hi:[1,0]
	v_pk_add_f32 v[14:15], v[14:15], 1.0 op_sel_hi:[1,0]
	s_waitcnt vmcnt(3)
	v_pk_mul_f32 v[6:7], v[130:131], v[6:7]
	v_pk_mul_f32 v[124:125], v[128:129], v[8:9]
	s_waitcnt vmcnt(2)
	v_pk_add_f32 v[4:5], v[4:5], 1.0 op_sel_hi:[1,0]
	v_pk_add_f32 v[2:3], v[2:3], 1.0 op_sel_hi:[1,0]
	s_waitcnt vmcnt(0)
	v_pk_fma_f32 v[8:9], v[12:13], v[16:17], v[230:231]
	v_pk_fma_f32 v[12:13], v[10:11], v[14:15], v[228:229]
	v_pk_fma_f32 v[10:11], v[124:125], v[4:5], v[226:227]
	v_pk_fma_f32 v[14:15], v[6:7], v[2:3], v[224:225]
	v_cvt_pk_bf16_f32 v2, v12, v13
	v_cvt_pk_bf16_f32 v3, v8, v9
	v_cvt_pk_bf16_f32 v4, v14, v15
	v_cvt_pk_bf16_f32 v5, v10, v11
	global_store_dwordx4 v[98:99], v[2:5], off offset:2048
	global_load_dwordx4 v[124:127], v[68:69], off offset:16
	global_load_dwordx4 v[128:131], v[68:69], off
	global_load_dwordx4 v[132:135], v215, s[24:25] offset:16
	global_load_dwordx4 v[136:139], v215, s[24:25]
	global_load_dwordx4 v[140:143], v215, s[26:27] offset:16
	global_load_dwordx4 v[144:147], v215, s[26:27]
	v_mul_f32_e32 v2, v97, v43
	v_mul_f32_e32 v3, v92, v44
	v_fmac_f32_e32 v2, v95, v39
	v_mul_f32_e32 v4, v93, v45
	v_fmac_f32_e32 v3, v90, v40
	v_add_f32_e32 v1, v2, v1
	v_fmac_f32_e32 v4, v91, v41
	v_add_f32_e32 v1, v3, v1
	v_mul_f32_e32 v2, v106, v46
	v_add_f32_e32 v1, v4, v1
	v_mul_f32_e32 v3, v107, v47
	v_fmac_f32_e32 v2, v104, v34
	v_mul_f32_e32 v4, v102, v48
	v_fmac_f32_e32 v3, v105, v35
	v_add_f32_e32 v1, v2, v1
	v_mul_f32_e32 v5, v103, v49
	v_fmac_f32_e32 v4, v100, v36
	v_add_f32_e32 v1, v3, v1
	v_fmac_f32_e32 v5, v101, v37
	v_add_f32_e32 v1, v4, v1
	v_add_f32_e32 v5, v5, v1
	v_mul_f32_e32 v1, v114, v22
	v_mul_f32_e32 v2, v115, v23
	v_fmac_f32_e32 v1, v112, v18
	v_mul_f32_e32 v3, v110, v24
	v_mul_f32_e32 v6, v114, v236
	v_fmac_f32_e32 v2, v113, v19
	v_add_f32_e32 v1, 0, v1
	v_mul_f32_e32 v4, v111, v25
	v_mul_f32_e32 v7, v115, v237
	v_fmac_f32_e32 v3, v108, v20
	v_fmac_f32_e32 v6, v112, v232
	v_add_f32_e32 v1, v2, v1
	v_mul_f32_e32 v16, v110, v238
	v_fmac_f32_e32 v4, v109, v21
	v_fmac_f32_e32 v7, v113, v233
	v_add_f32_e32 v6, 0, v6
	v_add_f32_e32 v1, v3, v1
	v_mul_f32_e32 v3, v122, v30
	v_mul_f32_e32 v17, v111, v239
	v_fmac_f32_e32 v16, v108, v234
	v_add_f32_e32 v2, v7, v6
	v_add_f32_e32 v1, v4, v1
	v_mul_f32_e32 v4, v123, v31
	v_fmac_f32_e32 v3, v120, v26
	v_fmac_f32_e32 v17, v109, v235
	v_add_f32_e32 v2, v16, v2
	v_mul_f32_e32 v6, v118, v32
	v_mul_f32_e32 v16, v122, v54
	v_fmac_f32_e32 v4, v121, v27
	v_add_f32_e32 v1, v3, v1
	v_add_f32_e32 v2, v17, v2
	v_mul_f32_e32 v7, v119, v33
	v_fmac_f32_e32 v6, v116, v28
	v_fmac_f32_e32 v16, v120, v50
	v_add_f32_e32 v1, v4, v1
	v_fmac_f32_e32 v7, v117, v29
	v_add_f32_e32 v28, v16, v2
	v_add_f32_e32 v1, v6, v1
	v_mul_f32_e32 v2, v14, v42
	v_add_f32_e32 v1, v7, v1
	v_mul_f32_e32 v3, v15, v43
	v_fmac_f32_e32 v2, v12, v38
	v_mul_f32_e32 v4, v10, v44
	v_fmac_f32_e32 v3, v13, v39
	v_add_f32_e32 v1, v2, v1
	v_mul_f32_e32 v6, v11, v45
	v_fmac_f32_e32 v4, v8, v40
	v_add_f32_e32 v1, v3, v1
	v_fmac_f32_e32 v6, v9, v41
	v_add_f32_e32 v1, v4, v1
	v_add_f32_e32 v4, v6, v1
	v_mul_f32_e32 v30, v123, v55
	v_fmac_f32_e32 v30, v121, v51
	v_mul_f32_e32 v33, v87, v57
	s_waitcnt vmcnt(5)
; #define LAS __attribute__((address_space(3)))
; __device__ __forceinline__ unsigned pk2(float lo, float hi) { return f2bf(lo) | (f2bf(hi) << 16); }
; template <bool ZP, bool XF32, bool OUT8 = false>
; __device__ __forceinline__ void norm_phase(LAS unsigned char* lds, const void* xin, const float* gain, const float* sh, const float* sc, bf16* hout, const float* wzt, float* zout, int lane, int wave, int vcu, int G) {
;     ...
;                 for (int q = 0; q < 2; ++q) { const f32x4 gg = *(const f32x4*)(gain + col + 4 * q), s1 = *(const f32x4*)(sc + (size_t)b * MODW + col + 4 * q), s0 = *(const f32x4*)(sh + (size_t)b * MODW + col + 4 * q);
;                     v[r][j][q] = (v[r][j][q] * rstd * gg) * (s1 + 1.0f) + s0; }
;                 if constexpr (OUT8) { *(v2u*)((unsigned char*)hout + (size_t)m * D + col) = pack8_fp8(v[r][j][0][0], v[r][j][0][1], v[r][j][0][2], v[r][j][0][3], v[r][j][1][0], v[r][j][1][1], v[r][j][1][2], v[r][j][1][3], FP8_ASCALE); }
;                 else { v4u o; o.x = pk2(v[r][j][0][0], v[r][j][0][1]); o.y = pk2(v[r][j][0][2], v[r][j][0][3]); o.z = pk2(v[r][j][1][0], v[r][j][1][1]); o.w = pk2(v[r][j][1][2], v[r][j][1][3]);
;                     *(v4u*)(hout + (size_t)m * D + col) = o; } }
;         }
;         if constexpr (ZP) {
;             float p0[16], p1[16];
; #pragma unroll
;             for (int rr = 0; rr < 16; ++rr) { p0[rr] = 0.f; p1[rr] = 0.f;
; #pragma unroll
;                 for (int j = 0; j < 4; ++j) { const f32x4 w0 = *(const LAS f32x4*)(wl + (((rr * 4 + j) * 2 + 0) * 64 + lane) * 4), w1 = *(const LAS f32x4*)(wl + (((rr * 4 + j) * 2 + 1) * 64 + lane) * 4);
; #pragma unroll
;                     for (int e = 0; e < 4; ++e) { p0[rr] += v[0][j][0][e] * w0[e] + v[0][j][1][e] * w1[e]; p1[rr] += v[1][j][0][e] * w0[e] + v[1][j][1][e] * w1[e]; } } }
	v_pk_mul_f32 v[20:21], v[246:247], v[124:125]
	s_waitcnt vmcnt(4)
	v_pk_mul_f32 v[6:7], v[240:241], v[130:131]
	s_waitcnt vmcnt(3)
	v_pk_add_f32 v[26:27], v[132:133], 1.0 op_sel_hi:[1,0]
	s_waitcnt vmcnt(2)
	v_pk_add_f32 v[16:17], v[138:139], 1.0 op_sel_hi:[1,0]
	v_pk_mul_f32 v[22:23], v[244:245], v[126:127]
	v_pk_add_f32 v[24:25], v[134:135], 1.0 op_sel_hi:[1,0]
	s_waitcnt vmcnt(1)
	v_pk_fma_f32 v[20:21], v[20:21], v[26:27], v[140:141]
	v_pk_mul_f32 v[2:3], v[242:243], v[128:129]
	v_pk_add_f32 v[18:19], v[136:137], 1.0 op_sel_hi:[1,0]
	s_waitcnt vmcnt(0)
	v_pk_fma_f32 v[16:17], v[6:7], v[16:17], v[146:147]
	v_pk_fma_f32 v[6:7], v[22:23], v[24:25], v[142:143]
	v_pk_fma_f32 v[18:19], v[2:3], v[18:19], v[144:145]
	v_mul_f32_e32 v26, v20, v46
	v_fmac_f32_e32 v26, v18, v34
	v_mul_f32_e32 v27, v21, v47
	v_add_f32_e32 v26, v26, v4
	v_cvt_pk_bf16_f32 v4, v20, v21
	v_mul_f32_e32 v24, v86, v56
	v_mul_f32_e32 v29, v6, v48
	v_fmac_f32_e32 v27, v19, v35
	v_fmac_f32_e32 v24, v80, v52
	v_mul_f32_e32 v31, v7, v49
	v_fmac_f32_e32 v29, v16, v36
	v_cvt_pk_bf16_f32 v2, v18, v19
	v_cvt_pk_bf16_f32 v3, v16, v17
	v_add_f32_e32 v22, v27, v26
	v_add_f32_e32 v32, v24, v148
	v_mul_f32_e32 v24, v118, v56
	v_fmac_f32_e32 v31, v17, v37
	v_add_f32_e32 v22, v29, v22
	v_add_f32_e32 v23, v30, v28
	v_fmac_f32_e32 v24, v116, v52
	v_add_f32_e32 v22, v31, v22
	v_add_f32_e32 v23, v24, v23
	ds_read_b128 v[24:27], v73 offset:12288
	ds_read_b128 v[28:31], v73 offset:13312
	v_fmac_f32_e32 v33, v81, v53
	v_add_f32_e32 v32, v33, v32
	v_mul_f32_e32 v33, v119, v57
	v_fmac_f32_e32 v33, v117, v53
	v_add_f32_e32 v23, v33, v23
	s_waitcnt lgkmcnt(0)
	v_mul_f32_e32 v33, v96, v28
	v_mul_f32_e32 v28, v14, v28
	v_fmac_f32_e32 v28, v12, v24
	v_fmac_f32_e32 v33, v94, v24
	v_add_f32_e32 v23, v28, v23
	v_mul_f32_e32 v24, v97, v29
	v_mul_f32_e32 v28, v15, v29
	v_add_f32_e32 v32, v33, v32
	v_fmac_f32_e32 v24, v95, v25
	v_fmac_f32_e32 v28, v13, v25
	v_mul_f32_e32 v25, v92, v30
	v_add_f32_e32 v24, v24, v32
	v_fmac_f32_e32 v25, v90, v26
	v_add_f32_e32 v24, v25, v24
	v_mul_f32_e32 v25, v10, v30
	v_add_f32_e32 v23, v28, v23
	v_fmac_f32_e32 v25, v8, v26
	ds_read_b128 v[32:35], v73 offset:14336
	ds_read_b128 v[36:39], v73 offset:15360
	v_add_f32_e32 v23, v25, v23
	v_mul_f32_e32 v25, v93, v31
	v_fmac_f32_e32 v25, v91, v27
	v_add_f32_e32 v24, v25, v24
	v_mul_f32_e32 v25, v11, v31
	v_fmac_f32_e32 v25, v9, v27
	v_add_f32_e32 v23, v25, v23
	s_waitcnt lgkmcnt(0)
	v_mul_f32_e32 v25, v106, v36
	v_fmac_f32_e32 v25, v104, v32
	v_add_f32_e32 v24, v25, v24
	v_mul_f32_e32 v25, v20, v36
	v_fmac_f32_e32 v25, v18, v32
	v_add_f32_e32 v23, v25, v23
	v_mul_f32_e32 v25, v107, v37
	v_fmac_f32_e32 v25, v105, v33
	v_add_f32_e32 v24, v25, v24
	v_mul_f32_e32 v25, v21, v37
	v_fmac_f32_e32 v25, v19, v33
	v_add_f32_e32 v23, v25, v23
	v_mul_f32_e32 v25, v102, v38
	v_fmac_f32_e32 v25, v100, v34
	v_add_f32_e32 v24, v25, v24
	v_mul_f32_e32 v25, v6, v38
	v_fmac_f32_e32 v25, v16, v34
	ds_read_b128 v[26:29], v73 offset:16384
	ds_read_b128 v[30:33], v73 offset:17408
	v_add_f32_e32 v23, v25, v23
	v_mul_f32_e32 v25, v103, v39
	v_fmac_f32_e32 v25, v101, v35
	v_add_f32_e32 v24, v25, v24
	v_mul_f32_e32 v25, v7, v39
	v_fmac_f32_e32 v25, v17, v35
	v_add_f32_e32 v23, v25, v23
	s_waitcnt lgkmcnt(0)
	v_mul_f32_e32 v25, v82, v30
	v_mul_f32_e32 v30, v114, v30
	v_fmac_f32_e32 v30, v112, v26
	v_fmac_f32_e32 v25, v78, v26
	v_add_f32_e32 v26, 0, v30
	v_mul_f32_e32 v30, v83, v31
	v_add_f32_e32 v25, 0, v25
	v_fmac_f32_e32 v30, v79, v27
	v_add_f32_e32 v25, v30, v25
	v_mul_f32_e32 v30, v115, v31
	v_fmac_f32_e32 v30, v113, v27
	v_mul_f32_e32 v27, v76, v32
	v_fmac_f32_e32 v27, v74, v28
	v_add_f32_e32 v25, v27, v25
	v_mul_f32_e32 v27, v110, v32
	v_add_f32_e32 v26, v30, v26
	v_fmac_f32_e32 v27, v108, v28
	ds_read_b128 v[34:37], v73 offset:18432
	ds_read_b128 v[38:41], v73 offset:19456
	v_add_f32_e32 v26, v27, v26
	v_mul_f32_e32 v27, v77, v33
	v_fmac_f32_e32 v27, v75, v29
	v_add_f32_e32 v25, v27, v25
	v_mul_f32_e32 v27, v111, v33
	v_fmac_f32_e32 v27, v109, v29
	v_add_f32_e32 v26, v27, v26
	s_waitcnt lgkmcnt(0)
	v_mul_f32_e32 v27, v88, v38
	v_fmac_f32_e32 v27, v84, v34
	v_add_f32_e32 v25, v27, v25
	v_mul_f32_e32 v27, v122, v38
	v_fmac_f32_e32 v27, v120, v34
	v_add_f32_e32 v26, v27, v26
	v_mul_f32_e32 v27, v89, v39
	v_fmac_f32_e32 v27, v85, v35
	v_add_f32_e32 v25, v27, v25
	v_mul_f32_e32 v27, v123, v39
	v_fmac_f32_e32 v27, v121, v35
	v_add_f32_e32 v26, v27, v26
	v_mul_f32_e32 v27, v86, v40
	v_fmac_f32_e32 v27, v80, v36
	v_add_f32_e32 v25, v27, v25
	v_mul_f32_e32 v27, v118, v40
	v_fmac_f32_e32 v27, v116, v36
	v_add_f32_e32 v34, v27, v26
	ds_read_b128 v[26:29], v73 offset:20480
	ds_read_b128 v[30:33], v73 offset:21504
	v_mul_f32_e32 v35, v87, v41
	v_fmac_f32_e32 v35, v81, v37
	v_add_f32_e32 v25, v35, v25
	v_mul_f32_e32 v35, v119, v41
	v_fmac_f32_e32 v35, v117, v37
	v_add_f32_e32 v34, v35, v34
	s_waitcnt lgkmcnt(0)
	v_mul_f32_e32 v35, v96, v30
	v_mul_f32_e32 v30, v14, v30
	v_fmac_f32_e32 v30, v12, v26
	v_fmac_f32_e32 v35, v94, v26
	v_add_f32_e32 v26, v30, v34
	v_mul_f32_e32 v30, v97, v31
	v_add_f32_e32 v25, v35, v25
	v_fmac_f32_e32 v30, v95, v27
	v_add_f32_e32 v25, v30, v25
	v_mul_f32_e32 v30, v15, v31
	v_fmac_f32_e32 v30, v13, v27
	v_mul_f32_e32 v27, v92, v32
	v_fmac_f32_e32 v27, v90, v28
	v_add_f32_e32 v25, v27, v25
	v_mul_f32_e32 v27, v10, v32
	v_add_f32_e32 v26, v30, v26
	v_fmac_f32_e32 v27, v8, v28
	ds_read_b128 v[34:37], v73 offset:22528
	ds_read_b128 v[38:41], v73 offset:23552
	v_add_f32_e32 v26, v27, v26
	v_mul_f32_e32 v27, v93, v33
	v_fmac_f32_e32 v27, v91, v29
	v_add_f32_e32 v25, v27, v25
	v_mul_f32_e32 v27, v11, v33
	v_fmac_f32_e32 v27, v9, v29
	v_add_f32_e32 v26, v27, v26
	s_waitcnt lgkmcnt(0)
; #define LAS __attribute__((address_space(3)))
; template <bool ZP, bool XF32, bool OUT8 = false>
; __device__ __forceinline__ void norm_phase(LAS unsigned char* lds, const void* xin, const float* gain, const float* sh, const float* sc, bf16* hout, const float* wzt, float* zout, int lane, int wave, int vcu, int G) {
;     ...
;             float p0[16], p1[16];
; #pragma unroll
;             for (int rr = 0; rr < 16; ++rr) { p0[rr] = 0.f; p1[rr] = 0.f;
; #pragma unroll
;                 for (int j = 0; j < 4; ++j) { const f32x4 w0 = *(const LAS f32x4*)(wl + (((rr * 4 + j) * 2 + 0) * 64 + lane) * 4), w1 = *(const LAS f32x4*)(wl + (((rr * 4 + j) * 2 + 1) * 64 + lane) * 4);
; #pragma unroll
;                     for (int e = 0; e < 4; ++e) { p0[rr] += v[0][j][0][e] * w0[e] + v[0][j][1][e] * w1[e]; p1[rr] += v[1][j][0][e] * w0[e] + v[1][j][1][e] * w1[e]; } } }
	v_mul_f32_e32 v27, v106, v38
	v_fmac_f32_e32 v27, v104, v34
	v_add_f32_e32 v25, v27, v25
	v_mul_f32_e32 v27, v20, v38
	v_fmac_f32_e32 v27, v18, v34
	v_add_f32_e32 v26, v27, v26
	v_mul_f32_e32 v27, v107, v39
	v_fmac_f32_e32 v27, v105, v35
	v_add_f32_e32 v25, v27, v25
	v_mul_f32_e32 v27, v21, v39
	v_fmac_f32_e32 v27, v19, v35
	v_add_f32_e32 v26, v27, v26
	v_mul_f32_e32 v27, v102, v40
	v_fmac_f32_e32 v27, v100, v36
	v_add_f32_e32 v25, v27, v25
	v_mul_f32_e32 v27, v6, v40
	v_fmac_f32_e32 v27, v16, v36
	ds_read_b128 v[28:31], v73 offset:24576
	ds_read_b128 v[32:35], v73 offset:25600
	v_add_f32_e32 v27, v27, v26
	v_mul_f32_e32 v26, v103, v41
	v_fmac_f32_e32 v26, v101, v37
	v_add_f32_e32 v26, v26, v25
	v_mul_f32_e32 v25, v7, v41
	v_fmac_f32_e32 v25, v17, v37
	v_add_f32_e32 v25, v25, v27
	s_waitcnt lgkmcnt(0)
	v_mul_f32_e32 v27, v82, v32
	v_mul_f32_e32 v32, v114, v32
	v_fmac_f32_e32 v32, v112, v28
	v_fmac_f32_e32 v27, v78, v28
	v_add_f32_e32 v28, 0, v32
	v_mul_f32_e32 v32, v83, v33
	v_add_f32_e32 v27, 0, v27
	v_fmac_f32_e32 v32, v79, v29
	v_add_f32_e32 v27, v32, v27
	v_mul_f32_e32 v32, v115, v33
	v_fmac_f32_e32 v32, v113, v29
	v_mul_f32_e32 v29, v76, v34
	v_fmac_f32_e32 v29, v74, v30
	v_add_f32_e32 v27, v29, v27
	v_mul_f32_e32 v29, v110, v34
	v_add_f32_e32 v28, v32, v28
	v_fmac_f32_e32 v29, v108, v30
	ds_read_b128 v[36:39], v73 offset:26624
	ds_read_b128 v[40:43], v73 offset:27648
	v_add_f32_e32 v28, v29, v28
	v_mul_f32_e32 v29, v77, v35
	v_fmac_f32_e32 v29, v75, v31
	v_add_f32_e32 v27, v29, v27
	v_mul_f32_e32 v29, v111, v35
	v_fmac_f32_e32 v29, v109, v31
	v_add_f32_e32 v28, v29, v28
	s_waitcnt lgkmcnt(0)
	v_mul_f32_e32 v29, v88, v40
	v_fmac_f32_e32 v29, v84, v36
	v_add_f32_e32 v27, v29, v27
	v_mul_f32_e32 v29, v122, v40
	v_fmac_f32_e32 v29, v120, v36
	v_add_f32_e32 v28, v29, v28
	v_mul_f32_e32 v29, v89, v41
	v_fmac_f32_e32 v29, v85, v37
	v_add_f32_e32 v27, v29, v27
	v_mul_f32_e32 v29, v123, v41
	v_fmac_f32_e32 v29, v121, v37
	v_add_f32_e32 v28, v29, v28
	v_mul_f32_e32 v29, v86, v42
	v_fmac_f32_e32 v29, v80, v38
	v_add_f32_e32 v27, v29, v27
	v_mul_f32_e32 v29, v118, v42
	v_fmac_f32_e32 v29, v116, v38
	v_add_f32_e32 v36, v29, v28
	ds_read_b128 v[28:31], v73 offset:28672
	ds_read_b128 v[32:35], v73 offset:29696
	v_mul_f32_e32 v37, v87, v43
	v_fmac_f32_e32 v37, v81, v39
	v_add_f32_e32 v27, v37, v27
	v_mul_f32_e32 v37, v119, v43
	v_fmac_f32_e32 v37, v117, v39
	v_add_f32_e32 v36, v37, v36
	s_waitcnt lgkmcnt(0)
	v_mul_f32_e32 v37, v96, v32
	v_mul_f32_e32 v32, v14, v32
	v_fmac_f32_e32 v32, v12, v28
	v_fmac_f32_e32 v37, v94, v28
	v_add_f32_e32 v28, v32, v36
	v_mul_f32_e32 v32, v97, v33
	v_add_f32_e32 v27, v37, v27
	v_fmac_f32_e32 v32, v95, v29
	v_add_f32_e32 v27, v32, v27
	v_mul_f32_e32 v32, v15, v33
	v_fmac_f32_e32 v32, v13, v29
	v_mul_f32_e32 v29, v92, v34
	v_fmac_f32_e32 v29, v90, v30
	v_add_f32_e32 v27, v29, v27
	v_mul_f32_e32 v29, v10, v34
	v_add_f32_e32 v28, v32, v28
	v_fmac_f32_e32 v29, v8, v30
	ds_read_b128 v[36:39], v73 offset:30720
	ds_read_b128 v[40:43], v73 offset:31744
	v_add_f32_e32 v28, v29, v28
	v_mul_f32_e32 v29, v93, v35
	v_fmac_f32_e32 v29, v91, v31
	v_add_f32_e32 v27, v29, v27
	v_mul_f32_e32 v29, v11, v35
	v_fmac_f32_e32 v29, v9, v31
	v_add_f32_e32 v28, v29, v28
	s_waitcnt lgkmcnt(0)
	v_mul_f32_e32 v29, v106, v40
	v_fmac_f32_e32 v29, v104, v36
	v_add_f32_e32 v27, v29, v27
	v_mul_f32_e32 v29, v20, v40
	v_fmac_f32_e32 v29, v18, v36
	v_add_f32_e32 v28, v29, v28
	v_mul_f32_e32 v29, v107, v41
	v_fmac_f32_e32 v29, v105, v37
	v_add_f32_e32 v27, v29, v27
	v_mul_f32_e32 v29, v21, v41
	v_fmac_f32_e32 v29, v19, v37
	v_add_f32_e32 v28, v29, v28
	v_mul_f32_e32 v29, v102, v42
	v_fmac_f32_e32 v29, v100, v38
	v_add_f32_e32 v27, v29, v27
	v_mul_f32_e32 v29, v6, v42
	v_fmac_f32_e32 v29, v16, v38
	ds_read_b128 v[30:33], v73 offset:32768
	ds_read_b128 v[34:37], v73 offset:33792
	v_add_f32_e32 v29, v29, v28
	v_mul_f32_e32 v28, v103, v43
	v_fmac_f32_e32 v28, v101, v39
	v_add_f32_e32 v28, v28, v27
	v_mul_f32_e32 v27, v7, v43
	v_fmac_f32_e32 v27, v17, v39
	v_add_f32_e32 v27, v27, v29
	s_waitcnt lgkmcnt(0)
	v_mul_f32_e32 v29, v82, v34
	v_mul_f32_e32 v34, v114, v34
	v_fmac_f32_e32 v34, v112, v30
	v_fmac_f32_e32 v29, v78, v30
	v_add_f32_e32 v30, 0, v34
	v_mul_f32_e32 v34, v83, v35
	v_add_f32_e32 v29, 0, v29
	v_fmac_f32_e32 v34, v79, v31
	v_add_f32_e32 v29, v34, v29
	v_mul_f32_e32 v34, v115, v35
	v_fmac_f32_e32 v34, v113, v31
	v_mul_f32_e32 v31, v76, v36
	v_fmac_f32_e32 v31, v74, v32
	v_add_f32_e32 v29, v31, v29
	v_mul_f32_e32 v31, v110, v36
	v_add_f32_e32 v30, v34, v30
	v_fmac_f32_e32 v31, v108, v32
	ds_read_b128 v[38:41], v73 offset:34816
	ds_read_b128 v[42:45], v73 offset:35840
	v_add_f32_e32 v30, v31, v30
	v_mul_f32_e32 v31, v77, v37
	v_fmac_f32_e32 v31, v75, v33
	v_add_f32_e32 v29, v31, v29
	v_mul_f32_e32 v31, v111, v37
	v_fmac_f32_e32 v31, v109, v33
	v_add_f32_e32 v30, v31, v30
	s_waitcnt lgkmcnt(0)
	v_mul_f32_e32 v31, v88, v42
	v_fmac_f32_e32 v31, v84, v38
	v_add_f32_e32 v29, v31, v29
	v_mul_f32_e32 v31, v122, v42
	v_fmac_f32_e32 v31, v120, v38
	v_add_f32_e32 v30, v31, v30
	v_mul_f32_e32 v31, v89, v43
	v_fmac_f32_e32 v31, v85, v39
	v_add_f32_e32 v29, v31, v29
	v_mul_f32_e32 v31, v123, v43
	v_fmac_f32_e32 v31, v121, v39
	v_add_f32_e32 v30, v31, v30
	v_mul_f32_e32 v31, v86, v44
	v_fmac_f32_e32 v31, v80, v40
	v_add_f32_e32 v29, v31, v29
	v_mul_f32_e32 v31, v118, v44
	v_fmac_f32_e32 v31, v116, v40
	v_add_f32_e32 v38, v31, v30
	ds_read_b128 v[30:33], v73 offset:36864
	ds_read_b128 v[34:37], v73 offset:37888
	v_mul_f32_e32 v39, v87, v45
	v_fmac_f32_e32 v39, v81, v41
	v_add_f32_e32 v29, v39, v29
	v_mul_f32_e32 v39, v119, v45
	v_fmac_f32_e32 v39, v117, v41
	v_add_f32_e32 v38, v39, v38
	s_waitcnt lgkmcnt(0)
; #define LAS __attribute__((address_space(3)))
; template <bool ZP, bool XF32, bool OUT8 = false>
; __device__ __forceinline__ void norm_phase(LAS unsigned char* lds, const void* xin, const float* gain, const float* sh, const float* sc, bf16* hout, const float* wzt, float* zout, int lane, int wave, int vcu, int G) {
;     ...
;             float p0[16], p1[16];
; #pragma unroll
;             for (int rr = 0; rr < 16; ++rr) { p0[rr] = 0.f; p1[rr] = 0.f;
; #pragma unroll
;                 for (int j = 0; j < 4; ++j) { const f32x4 w0 = *(const LAS f32x4*)(wl + (((rr * 4 + j) * 2 + 0) * 64 + lane) * 4), w1 = *(const LAS f32x4*)(wl + (((rr * 4 + j) * 2 + 1) * 64 + lane) * 4);
; #pragma unroll
;                     for (int e = 0; e < 4; ++e) { p0[rr] += v[0][j][0][e] * w0[e] + v[0][j][1][e] * w1[e]; p1[rr] += v[1][j][0][e] * w0[e] + v[1][j][1][e] * w1[e]; } } }
	v_mul_f32_e32 v39, v96, v34
	v_mul_f32_e32 v34, v14, v34
	v_fmac_f32_e32 v34, v12, v30
	v_fmac_f32_e32 v39, v94, v30
	v_add_f32_e32 v30, v34, v38
	v_mul_f32_e32 v34, v97, v35
	v_add_f32_e32 v29, v39, v29
	v_fmac_f32_e32 v34, v95, v31
	v_add_f32_e32 v29, v34, v29
	v_mul_f32_e32 v34, v15, v35
	v_fmac_f32_e32 v34, v13, v31
	v_mul_f32_e32 v31, v92, v36
	v_fmac_f32_e32 v31, v90, v32
	v_add_f32_e32 v29, v31, v29
	v_mul_f32_e32 v31, v10, v36
	v_add_f32_e32 v30, v34, v30
	v_fmac_f32_e32 v31, v8, v32
	ds_read_b128 v[38:41], v73 offset:38912
	ds_read_b128 v[42:45], v73 offset:39936
	v_add_f32_e32 v30, v31, v30
	v_mul_f32_e32 v31, v93, v37
	v_fmac_f32_e32 v31, v91, v33
	v_add_f32_e32 v29, v31, v29
	v_mul_f32_e32 v31, v11, v37
	v_fmac_f32_e32 v31, v9, v33
	v_add_f32_e32 v30, v31, v30
	s_waitcnt lgkmcnt(0)
	v_mul_f32_e32 v31, v106, v42
	v_fmac_f32_e32 v31, v104, v38
	v_add_f32_e32 v29, v31, v29
	v_mul_f32_e32 v31, v20, v42
	v_fmac_f32_e32 v31, v18, v38
	v_add_f32_e32 v30, v31, v30
	v_mul_f32_e32 v31, v107, v43
	v_fmac_f32_e32 v31, v105, v39
	v_add_f32_e32 v29, v31, v29
	v_mul_f32_e32 v31, v21, v43
	v_fmac_f32_e32 v31, v19, v39
	v_add_f32_e32 v30, v31, v30
	v_mul_f32_e32 v31, v102, v44
	v_fmac_f32_e32 v31, v100, v40
	v_add_f32_e32 v29, v31, v29
	v_mul_f32_e32 v31, v6, v44
	v_fmac_f32_e32 v31, v16, v40
	ds_read_b128 v[32:35], v73 offset:40960
	ds_read_b128 v[36:39], v73 offset:41984
	v_add_f32_e32 v31, v31, v30
	v_mul_f32_e32 v30, v103, v45
	v_fmac_f32_e32 v30, v101, v41
	v_add_f32_e32 v30, v30, v29
	v_mul_f32_e32 v29, v7, v45
	v_fmac_f32_e32 v29, v17, v41
	v_add_f32_e32 v29, v29, v31
	s_waitcnt lgkmcnt(0)
	v_mul_f32_e32 v31, v82, v36
	v_mul_f32_e32 v36, v114, v36
	v_fmac_f32_e32 v36, v112, v32
	v_fmac_f32_e32 v31, v78, v32
	v_add_f32_e32 v32, 0, v36
	v_mul_f32_e32 v36, v83, v37
	v_add_f32_e32 v31, 0, v31
	v_fmac_f32_e32 v36, v79, v33
	v_add_f32_e32 v31, v36, v31
	v_mul_f32_e32 v36, v115, v37
	v_fmac_f32_e32 v36, v113, v33
	v_mul_f32_e32 v33, v76, v38
	v_fmac_f32_e32 v33, v74, v34
	v_add_f32_e32 v31, v33, v31
	v_mul_f32_e32 v33, v110, v38
	v_add_f32_e32 v32, v36, v32
	v_fmac_f32_e32 v33, v108, v34
	ds_read_b128 v[40:43], v73 offset:43008
	ds_read_b128 v[44:47], v73 offset:44032
	v_add_f32_e32 v32, v33, v32
	v_mul_f32_e32 v33, v77, v39
	v_fmac_f32_e32 v33, v75, v35
	v_add_f32_e32 v31, v33, v31
	v_mul_f32_e32 v33, v111, v39
	v_fmac_f32_e32 v33, v109, v35
	v_add_f32_e32 v32, v33, v32
	s_waitcnt lgkmcnt(0)
	v_mul_f32_e32 v33, v88, v44
	v_fmac_f32_e32 v33, v84, v40
	v_add_f32_e32 v31, v33, v31
	v_mul_f32_e32 v33, v122, v44
	v_fmac_f32_e32 v33, v120, v40
	v_add_f32_e32 v32, v33, v32
	v_mul_f32_e32 v33, v89, v45
	v_fmac_f32_e32 v33, v85, v41
	v_add_f32_e32 v31, v33, v31
	v_mul_f32_e32 v33, v123, v45
	v_fmac_f32_e32 v33, v121, v41
	v_add_f32_e32 v32, v33, v32
	v_mul_f32_e32 v33, v86, v46
	v_fmac_f32_e32 v33, v80, v42
	v_add_f32_e32 v31, v33, v31
	v_mul_f32_e32 v33, v118, v46
	v_fmac_f32_e32 v33, v116, v42
	v_add_f32_e32 v40, v33, v32
	ds_read_b128 v[32:35], v73 offset:45056
	ds_read_b128 v[36:39], v73 offset:46080
	v_mul_f32_e32 v41, v87, v47
	v_fmac_f32_e32 v41, v81, v43
	v_add_f32_e32 v31, v41, v31
	v_mul_f32_e32 v41, v119, v47
	v_fmac_f32_e32 v41, v117, v43
	v_add_f32_e32 v40, v41, v40
	s_waitcnt lgkmcnt(0)
	v_mul_f32_e32 v41, v96, v36
	v_mul_f32_e32 v36, v14, v36
	v_fmac_f32_e32 v36, v12, v32
	v_fmac_f32_e32 v41, v94, v32
	v_add_f32_e32 v32, v36, v40
	v_mul_f32_e32 v36, v97, v37
	v_add_f32_e32 v31, v41, v31
	v_fmac_f32_e32 v36, v95, v33
	v_add_f32_e32 v31, v36, v31
	v_mul_f32_e32 v36, v15, v37
	v_fmac_f32_e32 v36, v13, v33
	v_mul_f32_e32 v33, v92, v38
	v_fmac_f32_e32 v33, v90, v34
	v_add_f32_e32 v31, v33, v31
	v_mul_f32_e32 v33, v10, v38
	v_add_f32_e32 v32, v36, v32
	v_fmac_f32_e32 v33, v8, v34
	ds_read_b128 v[40:43], v73 offset:47104
	ds_read_b128 v[44:47], v73 offset:48128
	v_add_f32_e32 v32, v33, v32
	v_mul_f32_e32 v33, v93, v39
	v_fmac_f32_e32 v33, v91, v35
	v_add_f32_e32 v31, v33, v31
	v_mul_f32_e32 v33, v11, v39
	v_fmac_f32_e32 v33, v9, v35
	v_add_f32_e32 v32, v33, v32
	s_waitcnt lgkmcnt(0)
	v_mul_f32_e32 v33, v106, v44
	v_fmac_f32_e32 v33, v104, v40
	v_add_f32_e32 v31, v33, v31
	v_mul_f32_e32 v33, v20, v44
	v_fmac_f32_e32 v33, v18, v40
	v_add_f32_e32 v32, v33, v32
	v_mul_f32_e32 v33, v107, v45
	v_fmac_f32_e32 v33, v105, v41
	v_add_f32_e32 v31, v33, v31
	v_mul_f32_e32 v33, v21, v45
	v_fmac_f32_e32 v33, v19, v41
	v_add_f32_e32 v32, v33, v32
	v_mul_f32_e32 v33, v102, v46
	v_fmac_f32_e32 v33, v100, v42
	v_add_f32_e32 v31, v33, v31
	v_mul_f32_e32 v33, v6, v46
	v_fmac_f32_e32 v33, v16, v42
	ds_read_b128 v[34:37], v73 offset:49152
	ds_read_b128 v[38:41], v73 offset:50176
	v_add_f32_e32 v33, v33, v32
	v_mul_f32_e32 v32, v103, v47
	v_fmac_f32_e32 v32, v101, v43
	v_add_f32_e32 v32, v32, v31
	v_mul_f32_e32 v31, v7, v47
	v_fmac_f32_e32 v31, v17, v43
	v_add_f32_e32 v31, v31, v33
	s_waitcnt lgkmcnt(0)
	v_mul_f32_e32 v33, v82, v38
	v_mul_f32_e32 v38, v114, v38
	v_fmac_f32_e32 v38, v112, v34
	v_fmac_f32_e32 v33, v78, v34
	v_add_f32_e32 v34, 0, v38
	v_mul_f32_e32 v38, v83, v39
	v_add_f32_e32 v33, 0, v33
	v_fmac_f32_e32 v38, v79, v35
	v_add_f32_e32 v33, v38, v33
	v_mul_f32_e32 v38, v115, v39
	v_fmac_f32_e32 v38, v113, v35
	v_mul_f32_e32 v35, v76, v40
	v_fmac_f32_e32 v35, v74, v36
	v_add_f32_e32 v33, v35, v33
	v_mul_f32_e32 v35, v110, v40
	v_add_f32_e32 v34, v38, v34
	v_fmac_f32_e32 v35, v108, v36
	ds_read_b128 v[42:45], v73 offset:51200
	ds_read_b128 v[46:49], v73 offset:52224
	v_add_f32_e32 v34, v35, v34
	v_mul_f32_e32 v35, v77, v41
	v_fmac_f32_e32 v35, v75, v37
	v_add_f32_e32 v33, v35, v33
	v_mul_f32_e32 v35, v111, v41
	v_fmac_f32_e32 v35, v109, v37
	v_add_f32_e32 v34, v35, v34
	s_waitcnt lgkmcnt(0)
; #define LAS __attribute__((address_space(3)))
; template <bool ZP, bool XF32, bool OUT8 = false>
; __device__ __forceinline__ void norm_phase(LAS unsigned char* lds, const void* xin, const float* gain, const float* sh, const float* sc, bf16* hout, const float* wzt, float* zout, int lane, int wave, int vcu, int G) {
;     ...
;             float p0[16], p1[16];
; #pragma unroll
;             for (int rr = 0; rr < 16; ++rr) { p0[rr] = 0.f; p1[rr] = 0.f;
; #pragma unroll
;                 for (int j = 0; j < 4; ++j) { const f32x4 w0 = *(const LAS f32x4*)(wl + (((rr * 4 + j) * 2 + 0) * 64 + lane) * 4), w1 = *(const LAS f32x4*)(wl + (((rr * 4 + j) * 2 + 1) * 64 + lane) * 4);
; #pragma unroll
;                     for (int e = 0; e < 4; ++e) { p0[rr] += v[0][j][0][e] * w0[e] + v[0][j][1][e] * w1[e]; p1[rr] += v[1][j][0][e] * w0[e] + v[1][j][1][e] * w1[e]; } } }
	v_mul_f32_e32 v35, v88, v46
	v_fmac_f32_e32 v35, v84, v42
	v_add_f32_e32 v33, v35, v33
	v_mul_f32_e32 v35, v122, v46
	v_fmac_f32_e32 v35, v120, v42
	v_add_f32_e32 v34, v35, v34
	v_mul_f32_e32 v35, v89, v47
	v_fmac_f32_e32 v35, v85, v43
	v_add_f32_e32 v33, v35, v33
	v_mul_f32_e32 v35, v123, v47
	v_fmac_f32_e32 v35, v121, v43
	v_add_f32_e32 v34, v35, v34
	v_mul_f32_e32 v35, v86, v48
	v_fmac_f32_e32 v35, v80, v44
	v_add_f32_e32 v33, v35, v33
	v_mul_f32_e32 v35, v118, v48
	v_fmac_f32_e32 v35, v116, v44
	v_add_f32_e32 v42, v35, v34
	ds_read_b128 v[34:37], v73 offset:53248
	ds_read_b128 v[38:41], v73 offset:54272
	v_mul_f32_e32 v43, v87, v49
	v_fmac_f32_e32 v43, v81, v45
	v_add_f32_e32 v33, v43, v33
	v_mul_f32_e32 v43, v119, v49
	v_fmac_f32_e32 v43, v117, v45
	v_add_f32_e32 v42, v43, v42
	s_waitcnt lgkmcnt(0)
	v_mul_f32_e32 v43, v96, v38
	v_mul_f32_e32 v38, v14, v38
	v_fmac_f32_e32 v38, v12, v34
	v_fmac_f32_e32 v43, v94, v34
	v_add_f32_e32 v34, v38, v42
	v_mul_f32_e32 v38, v97, v39
	v_add_f32_e32 v33, v43, v33
	v_fmac_f32_e32 v38, v95, v35
	v_add_f32_e32 v33, v38, v33
	v_mul_f32_e32 v38, v15, v39
	v_fmac_f32_e32 v38, v13, v35
	v_mul_f32_e32 v35, v92, v40
	v_fmac_f32_e32 v35, v90, v36
	v_add_f32_e32 v33, v35, v33
	v_mul_f32_e32 v35, v10, v40
	v_add_f32_e32 v34, v38, v34
	v_fmac_f32_e32 v35, v8, v36
	ds_read_b128 v[42:45], v73 offset:55296
	ds_read_b128 v[46:49], v73 offset:56320
	v_add_f32_e32 v34, v35, v34
	v_mul_f32_e32 v35, v93, v41
	v_fmac_f32_e32 v35, v91, v37
	v_add_f32_e32 v33, v35, v33
	v_mul_f32_e32 v35, v11, v41
	v_fmac_f32_e32 v35, v9, v37
	v_add_f32_e32 v34, v35, v34
	s_waitcnt lgkmcnt(0)
	v_mul_f32_e32 v35, v106, v46
	v_fmac_f32_e32 v35, v104, v42
	v_add_f32_e32 v33, v35, v33
	v_mul_f32_e32 v35, v20, v46
	v_fmac_f32_e32 v35, v18, v42
	v_add_f32_e32 v34, v35, v34
	v_mul_f32_e32 v35, v107, v47
	v_fmac_f32_e32 v35, v105, v43
	v_add_f32_e32 v33, v35, v33
	v_mul_f32_e32 v35, v21, v47
	v_fmac_f32_e32 v35, v19, v43
	v_add_f32_e32 v34, v35, v34
	v_mul_f32_e32 v35, v102, v48
	v_fmac_f32_e32 v35, v100, v44
	v_add_f32_e32 v33, v35, v33
	v_mul_f32_e32 v35, v6, v48
	v_fmac_f32_e32 v35, v16, v44
	ds_read_b128 v[36:39], v73 offset:57344
	ds_read_b128 v[40:43], v73 offset:58368
	v_add_f32_e32 v35, v35, v34
	v_mul_f32_e32 v34, v103, v49
	v_fmac_f32_e32 v34, v101, v45
	v_add_f32_e32 v34, v34, v33
	v_mul_f32_e32 v33, v7, v49
	v_fmac_f32_e32 v33, v17, v45
	v_add_f32_e32 v33, v33, v35
	s_waitcnt lgkmcnt(0)
	v_mul_f32_e32 v35, v82, v40
	v_mul_f32_e32 v40, v114, v40
	v_fmac_f32_e32 v40, v112, v36
	v_fmac_f32_e32 v35, v78, v36
	v_add_f32_e32 v36, 0, v40
	v_mul_f32_e32 v40, v83, v41
	v_add_f32_e32 v35, 0, v35
	v_fmac_f32_e32 v40, v79, v37
	v_add_f32_e32 v35, v40, v35
	v_mul_f32_e32 v40, v115, v41
	v_fmac_f32_e32 v40, v113, v37
	v_mul_f32_e32 v37, v76, v42
	v_fmac_f32_e32 v37, v74, v38
	v_add_f32_e32 v35, v37, v35
	v_mul_f32_e32 v37, v110, v42
	v_add_f32_e32 v36, v40, v36
	v_fmac_f32_e32 v37, v108, v38
	ds_read_b128 v[44:47], v73 offset:59392
	ds_read_b128 v[48:51], v73 offset:60416
	v_add_f32_e32 v36, v37, v36
	v_mul_f32_e32 v37, v77, v43
	v_fmac_f32_e32 v37, v75, v39
	v_add_f32_e32 v35, v37, v35
	v_mul_f32_e32 v37, v111, v43
	v_fmac_f32_e32 v37, v109, v39
	v_add_f32_e32 v36, v37, v36
	s_waitcnt lgkmcnt(0)
	v_mul_f32_e32 v37, v88, v48
	v_fmac_f32_e32 v37, v84, v44
	v_add_f32_e32 v35, v37, v35
	v_mul_f32_e32 v37, v122, v48
	v_fmac_f32_e32 v37, v120, v44
	v_add_f32_e32 v36, v37, v36
	v_mul_f32_e32 v37, v89, v49
	v_fmac_f32_e32 v37, v85, v45
	v_add_f32_e32 v35, v37, v35
	v_mul_f32_e32 v37, v123, v49
	v_fmac_f32_e32 v37, v121, v45
	v_add_f32_e32 v36, v37, v36
	v_mul_f32_e32 v37, v86, v50
	v_fmac_f32_e32 v37, v80, v46
	v_add_f32_e32 v35, v37, v35
	v_mul_f32_e32 v37, v118, v50
	v_fmac_f32_e32 v37, v116, v46
	v_add_f32_e32 v44, v37, v36
	ds_read_b128 v[36:39], v73 offset:61440
	ds_read_b128 v[40:43], v73 offset:62464
	v_mul_f32_e32 v45, v87, v51
	v_fmac_f32_e32 v45, v81, v47
	v_add_f32_e32 v35, v45, v35
	v_mul_f32_e32 v45, v119, v51
	v_fmac_f32_e32 v45, v117, v47
	v_add_f32_e32 v44, v45, v44
	s_waitcnt lgkmcnt(0)
	v_mul_f32_e32 v45, v96, v40
	v_mul_f32_e32 v40, v14, v40
	v_fmac_f32_e32 v40, v12, v36
	v_fmac_f32_e32 v45, v94, v36
	v_add_f32_e32 v36, v40, v44
	v_mul_f32_e32 v40, v97, v41
	v_add_f32_e32 v35, v45, v35
	v_fmac_f32_e32 v40, v95, v37
	v_add_f32_e32 v35, v40, v35
	v_mul_f32_e32 v40, v15, v41
	v_fmac_f32_e32 v40, v13, v37
	v_mul_f32_e32 v37, v92, v42
	v_fmac_f32_e32 v37, v90, v38
	v_add_f32_e32 v35, v37, v35
	v_mul_f32_e32 v37, v10, v42
	v_add_f32_e32 v36, v40, v36
	v_fmac_f32_e32 v37, v8, v38
	ds_read_b128 v[44:47], v73 offset:63488
	ds_read_b128 v[48:51], v73 offset:64512
	v_add_f32_e32 v36, v37, v36
	v_mul_f32_e32 v37, v93, v43
	v_fmac_f32_e32 v37, v91, v39
	v_add_f32_e32 v35, v37, v35
	v_mul_f32_e32 v37, v11, v43
	v_fmac_f32_e32 v37, v9, v39
	v_add_f32_e32 v36, v37, v36
	s_waitcnt lgkmcnt(0)
	v_mul_f32_e32 v37, v106, v48
	v_fmac_f32_e32 v37, v104, v44
	v_add_f32_e32 v35, v37, v35
	v_mul_f32_e32 v37, v20, v48
	v_fmac_f32_e32 v37, v18, v44
	v_add_f32_e32 v36, v37, v36
	v_mul_f32_e32 v37, v107, v49
	v_fmac_f32_e32 v37, v105, v45
	v_add_f32_e32 v35, v37, v35
	v_mul_f32_e32 v37, v21, v49
	v_fmac_f32_e32 v37, v19, v45
	v_add_f32_e32 v36, v37, v36
	v_mul_f32_e32 v37, v102, v50
	v_fmac_f32_e32 v37, v100, v46
	v_add_f32_e32 v35, v37, v35
	v_mul_f32_e32 v37, v6, v50
	v_fmac_f32_e32 v37, v16, v46
	ds_read_b128 v[38:41], v149
	ds_read_b128 v[42:45], v150
	v_add_f32_e32 v37, v37, v36
	v_mul_f32_e32 v36, v103, v51
	v_fmac_f32_e32 v36, v101, v47
	v_add_f32_e32 v36, v36, v35
	v_mul_f32_e32 v35, v7, v51
	v_fmac_f32_e32 v35, v17, v47
	v_add_f32_e32 v35, v35, v37
	s_waitcnt lgkmcnt(0)
; #define LAS __attribute__((address_space(3)))
; template <bool ZP, bool XF32, bool OUT8 = false>
; __device__ __forceinline__ void norm_phase(LAS unsigned char* lds, const void* xin, const float* gain, const float* sh, const float* sc, bf16* hout, const float* wzt, float* zout, int lane, int wave, int vcu, int G) {
;     ...
;             float p0[16], p1[16];
; #pragma unroll
;             for (int rr = 0; rr < 16; ++rr) { p0[rr] = 0.f; p1[rr] = 0.f;
; #pragma unroll
;                 for (int j = 0; j < 4; ++j) { const f32x4 w0 = *(const LAS f32x4*)(wl + (((rr * 4 + j) * 2 + 0) * 64 + lane) * 4), w1 = *(const LAS f32x4*)(wl + (((rr * 4 + j) * 2 + 1) * 64 + lane) * 4);
; #pragma unroll
;                     for (int e = 0; e < 4; ++e) { p0[rr] += v[0][j][0][e] * w0[e] + v[0][j][1][e] * w1[e]; p1[rr] += v[1][j][0][e] * w0[e] + v[1][j][1][e] * w1[e]; } } }
	v_mul_f32_e32 v37, v82, v42
	v_mul_f32_e32 v42, v114, v42
	v_fmac_f32_e32 v42, v112, v38
	v_fmac_f32_e32 v37, v78, v38
	v_add_f32_e32 v38, 0, v42
	v_mul_f32_e32 v42, v83, v43
	v_add_f32_e32 v37, 0, v37
	v_fmac_f32_e32 v42, v79, v39
	v_add_f32_e32 v37, v42, v37
	v_mul_f32_e32 v42, v115, v43
	v_fmac_f32_e32 v42, v113, v39
	v_mul_f32_e32 v39, v76, v44
	v_fmac_f32_e32 v39, v74, v40
	v_add_f32_e32 v37, v39, v37
	v_mul_f32_e32 v39, v110, v44
	v_add_f32_e32 v38, v42, v38
	v_fmac_f32_e32 v39, v108, v40
	ds_read_b128 v[46:49], v151
	ds_read_b128 v[50:53], v152
	v_add_f32_e32 v38, v39, v38
	v_mul_f32_e32 v39, v77, v45
	v_fmac_f32_e32 v39, v75, v41
	v_add_f32_e32 v37, v39, v37
	v_mul_f32_e32 v39, v111, v45
	v_fmac_f32_e32 v39, v109, v41
	v_add_f32_e32 v38, v39, v38
	s_waitcnt lgkmcnt(0)
	v_mul_f32_e32 v39, v88, v50
	v_fmac_f32_e32 v39, v84, v46
	v_add_f32_e32 v37, v39, v37
	v_mul_f32_e32 v39, v122, v50
	v_fmac_f32_e32 v39, v120, v46
	v_add_f32_e32 v38, v39, v38
	v_mul_f32_e32 v39, v89, v51
	v_fmac_f32_e32 v39, v85, v47
	v_add_f32_e32 v37, v39, v37
	v_mul_f32_e32 v39, v123, v51
	v_fmac_f32_e32 v39, v121, v47
	v_add_f32_e32 v38, v39, v38
	v_mul_f32_e32 v39, v86, v52
	v_fmac_f32_e32 v39, v80, v48
	v_add_f32_e32 v37, v39, v37
	v_mul_f32_e32 v39, v118, v52
	v_fmac_f32_e32 v39, v116, v48
	v_add_f32_e32 v46, v39, v38
	ds_read_b128 v[38:41], v153
	ds_read_b128 v[42:45], v154
	v_mul_f32_e32 v47, v87, v53
	v_fmac_f32_e32 v47, v81, v49
	v_add_f32_e32 v37, v47, v37
	v_mul_f32_e32 v47, v119, v53
	v_fmac_f32_e32 v47, v117, v49
	v_add_f32_e32 v46, v47, v46
	s_waitcnt lgkmcnt(0)
	v_mul_f32_e32 v47, v96, v42
	v_mul_f32_e32 v42, v14, v42
	v_fmac_f32_e32 v42, v12, v38
	v_fmac_f32_e32 v47, v94, v38
	v_add_f32_e32 v38, v42, v46
	v_mul_f32_e32 v42, v97, v43
	v_add_f32_e32 v37, v47, v37
	v_fmac_f32_e32 v42, v95, v39
	v_add_f32_e32 v37, v42, v37
	v_mul_f32_e32 v42, v15, v43
	v_fmac_f32_e32 v42, v13, v39
	v_mul_f32_e32 v39, v92, v44
	v_fmac_f32_e32 v39, v90, v40
	v_add_f32_e32 v37, v39, v37
	v_mul_f32_e32 v39, v10, v44
	v_add_f32_e32 v38, v42, v38
	v_fmac_f32_e32 v39, v8, v40
	ds_read_b128 v[46:49], v155
	ds_read_b128 v[50:53], v156
	v_add_f32_e32 v38, v39, v38
	v_mul_f32_e32 v39, v93, v45
	v_fmac_f32_e32 v39, v91, v41
	v_add_f32_e32 v37, v39, v37
	v_mul_f32_e32 v39, v11, v45
	v_fmac_f32_e32 v39, v9, v41
	v_add_f32_e32 v38, v39, v38
	s_waitcnt lgkmcnt(0)
	v_mul_f32_e32 v39, v106, v50
	v_fmac_f32_e32 v39, v104, v46
	v_add_f32_e32 v37, v39, v37
	v_mul_f32_e32 v39, v20, v50
	v_fmac_f32_e32 v39, v18, v46
	v_add_f32_e32 v38, v39, v38
	v_mul_f32_e32 v39, v107, v51
	v_fmac_f32_e32 v39, v105, v47
	v_add_f32_e32 v37, v39, v37
	v_mul_f32_e32 v39, v21, v51
	v_fmac_f32_e32 v39, v19, v47
	v_add_f32_e32 v38, v39, v38
	v_mul_f32_e32 v39, v102, v52
	v_fmac_f32_e32 v39, v100, v48
	v_add_f32_e32 v37, v39, v37
	v_mul_f32_e32 v39, v6, v52
	v_fmac_f32_e32 v39, v16, v48
	ds_read_b128 v[40:43], v157
	ds_read_b128 v[44:47], v158
	v_add_f32_e32 v39, v39, v38
	v_mul_f32_e32 v38, v103, v53
	v_fmac_f32_e32 v38, v101, v49
	v_add_f32_e32 v38, v38, v37
	v_mul_f32_e32 v37, v7, v53
	v_fmac_f32_e32 v37, v17, v49
	v_add_f32_e32 v37, v37, v39
	s_waitcnt lgkmcnt(0)
	v_mul_f32_e32 v39, v82, v44
	v_mul_f32_e32 v44, v114, v44
	v_fmac_f32_e32 v44, v112, v40
	v_fmac_f32_e32 v39, v78, v40
	v_add_f32_e32 v40, 0, v44
	v_mul_f32_e32 v44, v83, v45
	v_add_f32_e32 v39, 0, v39
	v_fmac_f32_e32 v44, v79, v41
	v_add_f32_e32 v39, v44, v39
	v_mul_f32_e32 v44, v115, v45
	v_fmac_f32_e32 v44, v113, v41
	v_mul_f32_e32 v41, v76, v46
	v_fmac_f32_e32 v41, v74, v42
	v_add_f32_e32 v39, v41, v39
	v_mul_f32_e32 v41, v110, v46
	v_add_f32_e32 v40, v44, v40
	v_fmac_f32_e32 v41, v108, v42
	ds_read_b128 v[48:51], v159
	ds_read_b128 v[52:55], v160
	v_add_f32_e32 v40, v41, v40
	v_mul_f32_e32 v41, v77, v47
	v_fmac_f32_e32 v41, v75, v43
	v_add_f32_e32 v39, v41, v39
	v_mul_f32_e32 v41, v111, v47
	v_fmac_f32_e32 v41, v109, v43
	v_add_f32_e32 v40, v41, v40
	s_waitcnt lgkmcnt(0)
	v_mul_f32_e32 v41, v88, v52
	v_fmac_f32_e32 v41, v84, v48
	v_add_f32_e32 v39, v41, v39
	v_mul_f32_e32 v41, v122, v52
	v_fmac_f32_e32 v41, v120, v48
	v_add_f32_e32 v40, v41, v40
	v_mul_f32_e32 v41, v89, v53
	v_fmac_f32_e32 v41, v85, v49
	v_add_f32_e32 v39, v41, v39
	v_mul_f32_e32 v41, v123, v53
	v_fmac_f32_e32 v41, v121, v49
	v_add_f32_e32 v40, v41, v40
	v_mul_f32_e32 v41, v86, v54
	v_fmac_f32_e32 v41, v80, v50
	v_add_f32_e32 v39, v41, v39
	v_mul_f32_e32 v41, v118, v54
	v_fmac_f32_e32 v41, v116, v50
	v_add_f32_e32 v48, v41, v40
	ds_read_b128 v[40:43], v161
	ds_read_b128 v[44:47], v162
	v_mul_f32_e32 v49, v87, v55
	v_fmac_f32_e32 v49, v81, v51
	v_add_f32_e32 v39, v49, v39
	v_mul_f32_e32 v49, v119, v55
	v_fmac_f32_e32 v49, v117, v51
	v_add_f32_e32 v48, v49, v48
	s_waitcnt lgkmcnt(0)
	v_mul_f32_e32 v49, v96, v44
	v_mul_f32_e32 v44, v14, v44
	v_fmac_f32_e32 v44, v12, v40
	v_fmac_f32_e32 v49, v94, v40
	v_add_f32_e32 v40, v44, v48
	v_mul_f32_e32 v44, v97, v45
	v_add_f32_e32 v39, v49, v39
	v_fmac_f32_e32 v44, v95, v41
	v_add_f32_e32 v39, v44, v39
	v_mul_f32_e32 v44, v15, v45
	v_fmac_f32_e32 v44, v13, v41
	v_mul_f32_e32 v41, v92, v46
	v_fmac_f32_e32 v41, v90, v42
	v_add_f32_e32 v39, v41, v39
	v_mul_f32_e32 v41, v10, v46
	v_add_f32_e32 v40, v44, v40
	v_fmac_f32_e32 v41, v8, v42
	ds_read_b128 v[48:51], v163
	ds_read_b128 v[52:55], v164
	v_add_f32_e32 v40, v41, v40
	v_mul_f32_e32 v41, v93, v47
	v_fmac_f32_e32 v41, v91, v43
	v_add_f32_e32 v39, v41, v39
	v_mul_f32_e32 v41, v11, v47
	v_fmac_f32_e32 v41, v9, v43
	v_add_f32_e32 v40, v41, v40
	s_waitcnt lgkmcnt(0)
; #define LAS __attribute__((address_space(3)))
; template <bool ZP, bool XF32, bool OUT8 = false>
; __device__ __forceinline__ void norm_phase(LAS unsigned char* lds, const void* xin, const float* gain, const float* sh, const float* sc, bf16* hout, const float* wzt, float* zout, int lane, int wave, int vcu, int G) {
;     ...
;             float p0[16], p1[16];
; #pragma unroll
;             for (int rr = 0; rr < 16; ++rr) { p0[rr] = 0.f; p1[rr] = 0.f;
; #pragma unroll
;                 for (int j = 0; j < 4; ++j) { const f32x4 w0 = *(const LAS f32x4*)(wl + (((rr * 4 + j) * 2 + 0) * 64 + lane) * 4), w1 = *(const LAS f32x4*)(wl + (((rr * 4 + j) * 2 + 1) * 64 + lane) * 4);
; #pragma unroll
;                     for (int e = 0; e < 4; ++e) { p0[rr] += v[0][j][0][e] * w0[e] + v[0][j][1][e] * w1[e]; p1[rr] += v[1][j][0][e] * w0[e] + v[1][j][1][e] * w1[e]; } } }
	v_mul_f32_e32 v41, v106, v52
	v_fmac_f32_e32 v41, v104, v48
	v_add_f32_e32 v39, v41, v39
	v_mul_f32_e32 v41, v20, v52
	v_fmac_f32_e32 v41, v18, v48
	v_add_f32_e32 v40, v41, v40
	v_mul_f32_e32 v41, v107, v53
	v_fmac_f32_e32 v41, v105, v49
	v_add_f32_e32 v39, v41, v39
	v_mul_f32_e32 v41, v21, v53
	v_fmac_f32_e32 v41, v19, v49
	v_add_f32_e32 v40, v41, v40
	v_mul_f32_e32 v41, v102, v54
	v_fmac_f32_e32 v41, v100, v50
	v_add_f32_e32 v39, v41, v39
	v_mul_f32_e32 v41, v6, v54
	v_fmac_f32_e32 v41, v16, v50
	ds_read_b128 v[42:45], v165
	ds_read_b128 v[46:49], v166
	v_add_f32_e32 v41, v41, v40
	v_mul_f32_e32 v40, v103, v55
	v_fmac_f32_e32 v40, v101, v51
	v_add_f32_e32 v40, v40, v39
	v_mul_f32_e32 v39, v7, v55
	v_fmac_f32_e32 v39, v17, v51
	v_add_f32_e32 v39, v39, v41
	s_waitcnt lgkmcnt(0)
	v_mul_f32_e32 v41, v82, v46
	v_mul_f32_e32 v46, v114, v46
	v_fmac_f32_e32 v46, v112, v42
	v_fmac_f32_e32 v41, v78, v42
	v_add_f32_e32 v42, 0, v46
	v_mul_f32_e32 v46, v83, v47
	v_add_f32_e32 v41, 0, v41
	v_fmac_f32_e32 v46, v79, v43
	v_add_f32_e32 v41, v46, v41
	v_mul_f32_e32 v46, v115, v47
	v_fmac_f32_e32 v46, v113, v43
	v_mul_f32_e32 v43, v76, v48
	v_fmac_f32_e32 v43, v74, v44
	v_add_f32_e32 v41, v43, v41
	v_mul_f32_e32 v43, v110, v48
	v_add_f32_e32 v42, v46, v42
	v_fmac_f32_e32 v43, v108, v44
	ds_read_b128 v[50:53], v167
	ds_read_b128 v[54:57], v168
	v_add_f32_e32 v42, v43, v42
	v_mul_f32_e32 v43, v77, v49
	v_fmac_f32_e32 v43, v75, v45
	v_add_f32_e32 v41, v43, v41
	v_mul_f32_e32 v43, v111, v49
	v_fmac_f32_e32 v43, v109, v45
	v_add_f32_e32 v42, v43, v42
	s_waitcnt lgkmcnt(0)
	v_mul_f32_e32 v43, v88, v54
	v_fmac_f32_e32 v43, v84, v50
	v_add_f32_e32 v41, v43, v41
	v_mul_f32_e32 v43, v122, v54
	v_fmac_f32_e32 v43, v120, v50
	v_add_f32_e32 v42, v43, v42
	v_mul_f32_e32 v43, v89, v55
	v_fmac_f32_e32 v43, v85, v51
	v_add_f32_e32 v41, v43, v41
	v_mul_f32_e32 v43, v123, v55
	v_fmac_f32_e32 v43, v121, v51
	v_add_f32_e32 v42, v43, v42
	v_mul_f32_e32 v43, v86, v56
	v_fmac_f32_e32 v43, v80, v52
	v_add_f32_e32 v41, v43, v41
	v_mul_f32_e32 v43, v118, v56
	v_fmac_f32_e32 v43, v116, v52
	v_add_f32_e32 v50, v43, v42
	ds_read_b128 v[42:45], v169
	ds_read_b128 v[46:49], v170
	v_mul_f32_e32 v51, v87, v57
	v_fmac_f32_e32 v51, v81, v53
	v_add_f32_e32 v41, v51, v41
	v_mul_f32_e32 v51, v119, v57
	v_fmac_f32_e32 v51, v117, v53
	v_add_f32_e32 v50, v51, v50
	s_waitcnt lgkmcnt(0)
	v_mul_f32_e32 v51, v96, v46
	v_mul_f32_e32 v46, v14, v46
	v_fmac_f32_e32 v46, v12, v42
	v_fmac_f32_e32 v51, v94, v42
	v_add_f32_e32 v42, v46, v50
	v_mul_f32_e32 v46, v97, v47
	v_add_f32_e32 v41, v51, v41
	v_fmac_f32_e32 v46, v95, v43
	v_add_f32_e32 v41, v46, v41
	v_mul_f32_e32 v46, v15, v47
	v_fmac_f32_e32 v46, v13, v43
	v_mul_f32_e32 v43, v92, v48
	v_fmac_f32_e32 v43, v90, v44
	v_add_f32_e32 v41, v43, v41
	v_mul_f32_e32 v43, v10, v48
	v_add_f32_e32 v42, v46, v42
	v_fmac_f32_e32 v43, v8, v44
	ds_read_b128 v[50:53], v171
	ds_read_b128 v[54:57], v172
	v_add_f32_e32 v42, v43, v42
	v_mul_f32_e32 v43, v93, v49
	v_fmac_f32_e32 v43, v91, v45
	v_add_f32_e32 v41, v43, v41
	v_mul_f32_e32 v43, v11, v49
	v_fmac_f32_e32 v43, v9, v45
	v_add_f32_e32 v42, v43, v42
	s_waitcnt lgkmcnt(0)
	v_mul_f32_e32 v43, v106, v54
	v_fmac_f32_e32 v43, v104, v50
	v_add_f32_e32 v41, v43, v41
	v_mul_f32_e32 v43, v20, v54
	v_fmac_f32_e32 v43, v18, v50
	v_add_f32_e32 v42, v43, v42
	v_mul_f32_e32 v43, v107, v55
	v_fmac_f32_e32 v43, v105, v51
	v_add_f32_e32 v41, v43, v41
	v_mul_f32_e32 v43, v21, v55
	v_fmac_f32_e32 v43, v19, v51
	v_add_f32_e32 v42, v43, v42
	v_mul_f32_e32 v43, v102, v56
	v_fmac_f32_e32 v43, v100, v52
	v_add_f32_e32 v41, v43, v41
	v_mul_f32_e32 v43, v6, v56
	v_fmac_f32_e32 v43, v16, v52
	ds_read_b128 v[44:47], v173
	ds_read_b128 v[48:51], v174
	v_add_f32_e32 v43, v43, v42
	v_mul_f32_e32 v42, v103, v57
	v_fmac_f32_e32 v42, v101, v53
	v_add_f32_e32 v42, v42, v41
	v_mul_f32_e32 v41, v7, v57
	v_fmac_f32_e32 v41, v17, v53
	v_add_f32_e32 v41, v41, v43
	s_waitcnt lgkmcnt(0)
	v_mul_f32_e32 v43, v82, v48
	v_mul_f32_e32 v48, v114, v48
	v_fmac_f32_e32 v48, v112, v44
	v_fmac_f32_e32 v43, v78, v44
	v_add_f32_e32 v44, 0, v48
	v_mul_f32_e32 v48, v83, v49
	v_add_f32_e32 v43, 0, v43
	v_fmac_f32_e32 v48, v79, v45
	v_add_f32_e32 v43, v48, v43
	v_mul_f32_e32 v48, v115, v49
	v_fmac_f32_e32 v48, v113, v45
	v_mul_f32_e32 v45, v76, v50
	v_fmac_f32_e32 v45, v74, v46
	v_add_f32_e32 v43, v45, v43
	v_mul_f32_e32 v45, v110, v50
	v_add_f32_e32 v44, v48, v44
	v_fmac_f32_e32 v45, v108, v46
	ds_read_b128 v[52:55], v175
	ds_read_b128 v[124:127], v176
	v_add_f32_e32 v44, v45, v44
	v_mul_f32_e32 v45, v77, v51
	v_fmac_f32_e32 v45, v75, v47
	v_add_f32_e32 v43, v45, v43
	v_mul_f32_e32 v45, v111, v51
	v_fmac_f32_e32 v45, v109, v47
	v_add_f32_e32 v44, v45, v44
	s_waitcnt lgkmcnt(0)
	v_mul_f32_e32 v45, v88, v124
	v_fmac_f32_e32 v45, v84, v52
	v_add_f32_e32 v43, v45, v43
	v_mul_f32_e32 v45, v122, v124
	v_fmac_f32_e32 v45, v120, v52
	v_add_f32_e32 v44, v45, v44
	v_mul_f32_e32 v45, v89, v125
	v_fmac_f32_e32 v45, v85, v53
	v_add_f32_e32 v43, v45, v43
	v_mul_f32_e32 v45, v123, v125
	v_fmac_f32_e32 v45, v121, v53
	v_add_f32_e32 v44, v45, v44
	v_mul_f32_e32 v45, v86, v126
	v_fmac_f32_e32 v45, v80, v54
	v_add_f32_e32 v43, v45, v43
	v_mul_f32_e32 v45, v118, v126
	v_fmac_f32_e32 v45, v116, v54
	v_add_f32_e32 v52, v45, v44
	ds_read_b128 v[44:47], v177
	ds_read_b128 v[48:51], v178
	v_mul_f32_e32 v53, v87, v127
	v_fmac_f32_e32 v53, v81, v55
	v_add_f32_e32 v43, v53, v43
	v_mul_f32_e32 v53, v119, v127
	v_fmac_f32_e32 v53, v117, v55
	v_add_f32_e32 v52, v53, v52
	s_waitcnt lgkmcnt(0)
; #define LAS __attribute__((address_space(3)))
; template <bool ZP, bool XF32, bool OUT8 = false>
; __device__ __forceinline__ void norm_phase(LAS unsigned char* lds, const void* xin, const float* gain, const float* sh, const float* sc, bf16* hout, const float* wzt, float* zout, int lane, int wave, int vcu, int G) {
;     ...
;             float p0[16], p1[16];
; #pragma unroll
;             for (int rr = 0; rr < 16; ++rr) { p0[rr] = 0.f; p1[rr] = 0.f;
; #pragma unroll
;                 for (int j = 0; j < 4; ++j) { const f32x4 w0 = *(const LAS f32x4*)(wl + (((rr * 4 + j) * 2 + 0) * 64 + lane) * 4), w1 = *(const LAS f32x4*)(wl + (((rr * 4 + j) * 2 + 1) * 64 + lane) * 4);
; #pragma unroll
;                     for (int e = 0; e < 4; ++e) { p0[rr] += v[0][j][0][e] * w0[e] + v[0][j][1][e] * w1[e]; p1[rr] += v[1][j][0][e] * w0[e] + v[1][j][1][e] * w1[e]; } } }
	v_mul_f32_e32 v53, v96, v48
	v_mul_f32_e32 v48, v14, v48
	v_fmac_f32_e32 v48, v12, v44
	v_fmac_f32_e32 v53, v94, v44
	v_add_f32_e32 v44, v48, v52
	v_mul_f32_e32 v48, v97, v49
	v_add_f32_e32 v43, v53, v43
	v_fmac_f32_e32 v48, v95, v45
	v_add_f32_e32 v43, v48, v43
	v_mul_f32_e32 v48, v15, v49
	v_fmac_f32_e32 v48, v13, v45
	v_mul_f32_e32 v45, v92, v50
	v_fmac_f32_e32 v45, v90, v46
	v_add_f32_e32 v43, v45, v43
	v_mul_f32_e32 v45, v10, v50
	v_add_f32_e32 v44, v48, v44
	v_fmac_f32_e32 v45, v8, v46
	ds_read_b128 v[52:55], v179
	ds_read_b128 v[124:127], v180
	v_add_f32_e32 v44, v45, v44
	v_mul_f32_e32 v45, v93, v51
	v_fmac_f32_e32 v45, v91, v47
	v_add_f32_e32 v43, v45, v43
	v_mul_f32_e32 v45, v11, v51
	v_fmac_f32_e32 v45, v9, v47
	v_add_f32_e32 v44, v45, v44
	s_waitcnt lgkmcnt(0)
	v_mul_f32_e32 v45, v106, v124
	v_fmac_f32_e32 v45, v104, v52
	v_add_f32_e32 v43, v45, v43
	v_mul_f32_e32 v45, v20, v124
	v_fmac_f32_e32 v45, v18, v52
	v_add_f32_e32 v44, v45, v44
	v_mul_f32_e32 v45, v107, v125
	v_fmac_f32_e32 v45, v105, v53
	v_add_f32_e32 v43, v45, v43
	v_mul_f32_e32 v45, v21, v125
	v_fmac_f32_e32 v45, v19, v53
	v_add_f32_e32 v44, v45, v44
	v_mul_f32_e32 v45, v102, v126
	v_fmac_f32_e32 v45, v100, v54
	v_add_f32_e32 v43, v45, v43
	v_mul_f32_e32 v45, v6, v126
	v_fmac_f32_e32 v45, v16, v54
	ds_read_b128 v[46:49], v181
	ds_read_b128 v[50:53], v182
	v_add_f32_e32 v45, v45, v44
	v_mul_f32_e32 v44, v103, v127
	v_fmac_f32_e32 v44, v101, v55
	v_add_f32_e32 v44, v44, v43
	v_mul_f32_e32 v43, v7, v127
	v_fmac_f32_e32 v43, v17, v55
	v_add_f32_e32 v43, v43, v45
	s_waitcnt lgkmcnt(0)
	v_mul_f32_e32 v45, v82, v50
	v_mul_f32_e32 v50, v114, v50
	v_fmac_f32_e32 v50, v112, v46
	v_fmac_f32_e32 v45, v78, v46
	v_add_f32_e32 v46, 0, v50
	v_mul_f32_e32 v50, v83, v51
	v_add_f32_e32 v45, 0, v45
	v_fmac_f32_e32 v50, v79, v47
	v_add_f32_e32 v45, v50, v45
	v_mul_f32_e32 v50, v115, v51
	v_fmac_f32_e32 v50, v113, v47
	v_mul_f32_e32 v47, v76, v52
	v_fmac_f32_e32 v47, v74, v48
	v_add_f32_e32 v45, v47, v45
	v_mul_f32_e32 v47, v110, v52
	v_add_f32_e32 v46, v50, v46
	v_fmac_f32_e32 v47, v108, v48
	ds_read_b128 v[54:57], v183
	ds_read_b128 v[124:127], v184
	v_add_f32_e32 v46, v47, v46
	v_mul_f32_e32 v47, v77, v53
	v_fmac_f32_e32 v47, v75, v49
	v_add_f32_e32 v45, v47, v45
	v_mul_f32_e32 v47, v111, v53
	v_fmac_f32_e32 v47, v109, v49
	v_add_f32_e32 v46, v47, v46
	s_waitcnt lgkmcnt(0)
	v_mul_f32_e32 v47, v88, v124
	v_fmac_f32_e32 v47, v84, v54
	v_add_f32_e32 v45, v47, v45
	v_mul_f32_e32 v47, v122, v124
	v_fmac_f32_e32 v47, v120, v54
	v_add_f32_e32 v46, v47, v46
	v_mul_f32_e32 v47, v89, v125
	v_fmac_f32_e32 v47, v85, v55
	v_add_f32_e32 v45, v47, v45
	v_mul_f32_e32 v47, v123, v125
	v_fmac_f32_e32 v47, v121, v55
	v_add_f32_e32 v46, v47, v46
	v_mul_f32_e32 v47, v86, v126
	v_fmac_f32_e32 v47, v80, v56
	v_add_f32_e32 v45, v47, v45
	v_mul_f32_e32 v47, v118, v126
	v_fmac_f32_e32 v47, v116, v56
	v_add_f32_e32 v54, v47, v46
	ds_read_b128 v[46:49], v185
	ds_read_b128 v[50:53], v186
	v_mul_f32_e32 v55, v87, v127
	v_fmac_f32_e32 v55, v81, v57
	v_add_f32_e32 v45, v55, v45
	v_mul_f32_e32 v55, v119, v127
	v_fmac_f32_e32 v55, v117, v57
	v_add_f32_e32 v54, v55, v54
	s_waitcnt lgkmcnt(0)
	v_mul_f32_e32 v55, v96, v50
	v_mul_f32_e32 v50, v14, v50
	v_fmac_f32_e32 v50, v12, v46
	v_fmac_f32_e32 v55, v94, v46
	v_add_f32_e32 v46, v50, v54
	v_mul_f32_e32 v50, v97, v51
	v_add_f32_e32 v45, v55, v45
	v_fmac_f32_e32 v50, v95, v47
	v_add_f32_e32 v45, v50, v45
	v_mul_f32_e32 v50, v15, v51
	v_fmac_f32_e32 v50, v13, v47
	v_mul_f32_e32 v47, v92, v52
	v_fmac_f32_e32 v47, v90, v48
	v_add_f32_e32 v45, v47, v45
	v_mul_f32_e32 v47, v10, v52
	v_add_f32_e32 v46, v50, v46
	v_fmac_f32_e32 v47, v8, v48
	ds_read_b128 v[54:57], v187
	ds_read_b128 v[124:127], v188
	v_add_f32_e32 v46, v47, v46
	v_mul_f32_e32 v47, v93, v53
	v_fmac_f32_e32 v47, v91, v49
	v_add_f32_e32 v45, v47, v45
	v_mul_f32_e32 v47, v11, v53
	v_fmac_f32_e32 v47, v9, v49
	v_add_f32_e32 v46, v47, v46
	s_waitcnt lgkmcnt(0)
	v_mul_f32_e32 v47, v106, v124
	v_fmac_f32_e32 v47, v104, v54
	v_add_f32_e32 v45, v47, v45
	v_mul_f32_e32 v47, v20, v124
	v_fmac_f32_e32 v47, v18, v54
	v_add_f32_e32 v46, v47, v46
	v_mul_f32_e32 v47, v107, v125
	v_fmac_f32_e32 v47, v105, v55
	v_add_f32_e32 v45, v47, v45
	v_mul_f32_e32 v47, v21, v125
	v_fmac_f32_e32 v47, v19, v55
	v_add_f32_e32 v46, v47, v46
	v_mul_f32_e32 v47, v102, v126
	v_fmac_f32_e32 v47, v100, v56
	v_add_f32_e32 v45, v47, v45
	v_mul_f32_e32 v47, v6, v126
	v_fmac_f32_e32 v47, v16, v56
	v_add_f32_e32 v54, v47, v46
	ds_read_b128 v[46:49], v189
	ds_read_b128 v[50:53], v190
	v_mul_f32_e32 v55, v103, v127
	v_fmac_f32_e32 v55, v101, v57
	v_add_f32_e32 v128, v55, v45
	v_mul_f32_e32 v45, v7, v127
	v_fmac_f32_e32 v45, v17, v57
	v_add_f32_e32 v45, v45, v54
	s_waitcnt lgkmcnt(0)
	v_mul_f32_e32 v54, v82, v50
	v_mul_f32_e32 v50, v114, v50
	v_fmac_f32_e32 v50, v112, v46
	v_fmac_f32_e32 v54, v78, v46
	v_add_f32_e32 v46, 0, v50
	v_mul_f32_e32 v50, v83, v51
	v_mul_f32_e32 v51, v115, v51
	v_add_f32_e32 v54, 0, v54
	v_fmac_f32_e32 v50, v79, v47
	v_fmac_f32_e32 v51, v113, v47
	v_mul_f32_e32 v47, v76, v52
	v_add_f32_e32 v50, v50, v54
	v_fmac_f32_e32 v47, v74, v48
	v_add_f32_e32 v47, v47, v50
	v_mul_f32_e32 v50, v110, v52
	ds_read_b128 v[54:57], v191
	ds_read_b128 v[124:127], v192
	v_fmac_f32_e32 v50, v108, v48
	v_mul_f32_e32 v48, v77, v53
	v_fmac_f32_e32 v48, v75, v49
	v_add_f32_e32 v46, v51, v46
	v_add_f32_e32 v47, v48, v47
	v_mul_f32_e32 v48, v111, v53
	v_add_f32_e32 v46, v50, v46
	v_fmac_f32_e32 v48, v109, v49
	v_add_f32_e32 v46, v48, v46
	s_waitcnt lgkmcnt(0)
; #define LAS __attribute__((address_space(3)))
; template <bool ZP, bool XF32, bool OUT8 = false>
; __device__ __forceinline__ void norm_phase(LAS unsigned char* lds, const void* xin, const float* gain, const float* sh, const float* sc, bf16* hout, const float* wzt, float* zout, int lane, int wave, int vcu, int G) {
;     ...
;             float p0[16], p1[16];
; #pragma unroll
;             for (int rr = 0; rr < 16; ++rr) { p0[rr] = 0.f; p1[rr] = 0.f;
; #pragma unroll
;                 for (int j = 0; j < 4; ++j) { const f32x4 w0 = *(const LAS f32x4*)(wl + (((rr * 4 + j) * 2 + 0) * 64 + lane) * 4), w1 = *(const LAS f32x4*)(wl + (((rr * 4 + j) * 2 + 1) * 64 + lane) * 4);
; #pragma unroll
;                     for (int e = 0; e < 4; ++e) { p0[rr] += v[0][j][0][e] * w0[e] + v[0][j][1][e] * w1[e]; p1[rr] += v[1][j][0][e] * w0[e] + v[1][j][1][e] * w1[e]; } } }
	v_mul_f32_e32 v48, v88, v124
	v_fmac_f32_e32 v48, v84, v54
	v_add_f32_e32 v47, v48, v47
	v_mul_f32_e32 v48, v122, v124
	v_fmac_f32_e32 v48, v120, v54
	v_add_f32_e32 v46, v48, v46
	v_mul_f32_e32 v48, v89, v125
	v_fmac_f32_e32 v48, v85, v55
	v_add_f32_e32 v47, v48, v47
	v_mul_f32_e32 v48, v123, v125
	v_fmac_f32_e32 v48, v121, v55
	v_add_f32_e32 v46, v48, v46
	v_mul_f32_e32 v48, v86, v126
	v_fmac_f32_e32 v48, v80, v56
	v_add_f32_e32 v54, v48, v47
	v_mul_f32_e32 v47, v118, v126
	v_fmac_f32_e32 v47, v116, v56
	v_add_f32_e32 v55, v47, v46
	ds_read_b128 v[46:49], v193
	ds_read_b128 v[50:53], v194
	v_mul_f32_e32 v56, v87, v127
	v_fmac_f32_e32 v56, v81, v57
	v_add_f32_e32 v54, v56, v54
	v_mul_f32_e32 v56, v119, v127
	v_fmac_f32_e32 v56, v117, v57
	v_add_f32_e32 v55, v56, v55
	s_waitcnt lgkmcnt(0)
	v_mul_f32_e32 v56, v96, v50
	v_mul_f32_e32 v50, v14, v50
	v_fmac_f32_e32 v50, v12, v46
	v_fmac_f32_e32 v56, v94, v46
	v_add_f32_e32 v46, v50, v55
	v_mul_f32_e32 v50, v97, v51
	v_mul_f32_e32 v51, v15, v51
	v_add_f32_e32 v54, v56, v54
	v_fmac_f32_e32 v50, v95, v47
	v_fmac_f32_e32 v51, v13, v47
	v_mul_f32_e32 v47, v92, v52
	v_add_f32_e32 v50, v50, v54
	v_fmac_f32_e32 v47, v90, v48
	v_add_f32_e32 v47, v47, v50
	v_mul_f32_e32 v50, v10, v52
	ds_read_b128 v[54:57], v195
	ds_read_b128 v[124:127], v196
	v_fmac_f32_e32 v50, v8, v48
	v_mul_f32_e32 v48, v93, v53
	v_fmac_f32_e32 v48, v91, v49
	v_add_f32_e32 v46, v51, v46
	v_add_f32_e32 v47, v48, v47
	v_mul_f32_e32 v48, v11, v53
	v_add_f32_e32 v46, v50, v46
	v_fmac_f32_e32 v48, v9, v49
	v_add_f32_e32 v46, v48, v46
	s_waitcnt lgkmcnt(0)
	v_mul_f32_e32 v48, v106, v124
	v_fmac_f32_e32 v48, v104, v54
	v_add_f32_e32 v47, v48, v47
	v_mul_f32_e32 v48, v20, v124
	v_fmac_f32_e32 v48, v18, v54
	v_add_f32_e32 v46, v48, v46
	v_mul_f32_e32 v48, v107, v125
	v_fmac_f32_e32 v48, v105, v55
	v_add_f32_e32 v47, v48, v47
	v_mul_f32_e32 v48, v21, v125
	v_fmac_f32_e32 v48, v19, v55
	v_add_f32_e32 v46, v48, v46
	v_mul_f32_e32 v48, v102, v126
	v_fmac_f32_e32 v48, v100, v56
	v_add_f32_e32 v54, v48, v47
	v_mul_f32_e32 v47, v6, v126
	v_fmac_f32_e32 v47, v16, v56
	v_add_f32_e32 v55, v47, v46
	ds_read_b128 v[46:49], v197
	ds_read_b128 v[50:53], v198
	v_mul_f32_e32 v56, v103, v127
	v_fmac_f32_e32 v56, v101, v57
	v_add_f32_e32 v129, v56, v54
	v_mul_f32_e32 v54, v7, v127
	v_fmac_f32_e32 v54, v17, v57
	v_add_f32_e32 v130, v54, v55
	s_waitcnt lgkmcnt(0)
	v_mul_f32_e32 v54, v82, v50
	v_mul_f32_e32 v50, v114, v50
	v_fmac_f32_e32 v50, v112, v46
	v_fmac_f32_e32 v54, v78, v46
	v_add_f32_e32 v46, 0, v50
	v_mul_f32_e32 v50, v83, v51
	v_mul_f32_e32 v51, v115, v51
	v_add_f32_e32 v54, 0, v54
	v_fmac_f32_e32 v50, v79, v47
	v_fmac_f32_e32 v51, v113, v47
	v_mul_f32_e32 v47, v76, v52
	v_add_f32_e32 v50, v50, v54
	v_fmac_f32_e32 v47, v74, v48
	v_add_f32_e32 v47, v47, v50
	v_mul_f32_e32 v50, v110, v52
	ds_read_b128 v[54:57], v199
	ds_read_b128 v[124:127], v200
	v_fmac_f32_e32 v50, v108, v48
	v_mul_f32_e32 v48, v77, v53
	v_fmac_f32_e32 v48, v75, v49
	v_add_f32_e32 v46, v51, v46
	v_add_f32_e32 v47, v48, v47
	v_mul_f32_e32 v48, v111, v53
	v_add_f32_e32 v46, v50, v46
	v_fmac_f32_e32 v48, v109, v49
	v_add_f32_e32 v46, v48, v46
	s_waitcnt lgkmcnt(0)
	v_mul_f32_e32 v48, v88, v124
	v_fmac_f32_e32 v48, v84, v54
	v_add_f32_e32 v47, v48, v47
	v_mul_f32_e32 v48, v122, v124
	v_fmac_f32_e32 v48, v120, v54
	v_add_f32_e32 v46, v48, v46
	v_mul_f32_e32 v48, v89, v125
	v_fmac_f32_e32 v48, v85, v55
	v_add_f32_e32 v47, v48, v47
	v_mul_f32_e32 v48, v123, v125
	v_fmac_f32_e32 v48, v121, v55
	v_add_f32_e32 v46, v48, v46
	v_mul_f32_e32 v48, v86, v126
	v_fmac_f32_e32 v48, v80, v56
	v_add_f32_e32 v54, v48, v47
	v_mul_f32_e32 v47, v118, v126
	v_fmac_f32_e32 v47, v116, v56
	v_add_f32_e32 v55, v47, v46
	ds_read_b128 v[46:49], v201
	ds_read_b128 v[50:53], v202
	v_mul_f32_e32 v56, v87, v127
	v_fmac_f32_e32 v56, v81, v57
	v_add_f32_e32 v54, v56, v54
	v_mul_f32_e32 v56, v119, v127
	v_fmac_f32_e32 v56, v117, v57
	v_add_f32_e32 v55, v56, v55
	s_waitcnt lgkmcnt(0)
	v_mul_f32_e32 v56, v96, v50
	v_mul_f32_e32 v50, v14, v50
	v_fmac_f32_e32 v50, v12, v46
	v_fmac_f32_e32 v56, v94, v46
	v_add_f32_e32 v46, v50, v55
	v_mul_f32_e32 v50, v97, v51
	v_mul_f32_e32 v51, v15, v51
	v_add_f32_e32 v54, v56, v54
	v_fmac_f32_e32 v50, v95, v47
	v_fmac_f32_e32 v51, v13, v47
	v_mul_f32_e32 v47, v92, v52
	v_add_f32_e32 v50, v50, v54
	v_fmac_f32_e32 v47, v90, v48
	v_add_f32_e32 v47, v47, v50
	v_mul_f32_e32 v50, v10, v52
	ds_read_b128 v[54:57], v203
	ds_read_b128 v[124:127], v204
	v_fmac_f32_e32 v50, v8, v48
	v_mul_f32_e32 v48, v93, v53
	v_fmac_f32_e32 v48, v91, v49
	v_add_f32_e32 v46, v51, v46
	v_add_f32_e32 v47, v48, v47
	v_mul_f32_e32 v48, v11, v53
	v_add_f32_e32 v46, v50, v46
	v_fmac_f32_e32 v48, v9, v49
	v_add_f32_e32 v46, v48, v46
	s_waitcnt lgkmcnt(0)
	v_mul_f32_e32 v48, v106, v124
	v_fmac_f32_e32 v48, v104, v54
	v_add_f32_e32 v47, v48, v47
	v_mul_f32_e32 v48, v20, v124
	v_fmac_f32_e32 v48, v18, v54
	v_add_f32_e32 v46, v48, v46
	v_mul_f32_e32 v48, v107, v125
	v_fmac_f32_e32 v48, v105, v55
	v_add_f32_e32 v47, v48, v47
	v_mul_f32_e32 v48, v21, v125
	v_fmac_f32_e32 v48, v19, v55
	v_add_f32_e32 v46, v48, v46
	v_mul_f32_e32 v48, v102, v126
	v_fmac_f32_e32 v48, v100, v56
	v_add_f32_e32 v54, v48, v47
	v_mul_f32_e32 v47, v6, v126
	v_fmac_f32_e32 v47, v16, v56
	v_add_f32_e32 v55, v47, v46
	ds_read_b128 v[46:49], v205
	ds_read_b128 v[50:53], v206
	v_mul_f32_e32 v56, v103, v127
	v_fmac_f32_e32 v56, v101, v57
	v_add_f32_e32 v124, v56, v54
	v_mul_f32_e32 v54, v7, v127
	v_fmac_f32_e32 v54, v17, v57
	v_add_f32_e32 v125, v54, v55
	s_waitcnt lgkmcnt(0)
; #define LAS __attribute__((address_space(3)))
; __device__ __forceinline__ float reduce16(const float (&p)[16], int lane) {
;     float a[8], b[4], c[2];
;     { const bool hi = (lane & 32) != 0;
; #pragma unroll
;       for (int k = 0; k < 8; ++k) { const float send = hi ? p[k] : p[k + 8], keep = hi ? p[k + 8] : p[k]; a[k] = keep + __shfl_xor(send, 32); } }
;     { const bool hi = (lane & 16) != 0;
; #pragma unroll
;       for (int k = 0; k < 4; ++k) { const float send = hi ? a[k] : a[k + 4], keep = hi ? a[k + 4] : a[k]; b[k] = keep + __shfl_xor(send, 16); } }
;     { const bool hi = (lane & 8) != 0;
; #pragma unroll
;       for (int k = 0; k < 2; ++k) { const float send = hi ? b[k] : b[k + 2], keep = hi ? b[k + 2] : b[k]; c[k] = keep + __shfl_xor(send, 8); } }
;     const bool hi4 = (lane & 4) != 0; const float send = hi4 ? c[0] : c[1], keep = hi4 ? c[1] : c[0];
; template <bool ZP, bool XF32, bool OUT8 = false>
; __device__ __forceinline__ void norm_phase(LAS unsigned char* lds, const void* xin, const float* gain, const float* sh, const float* sc, bf16* hout, const float* wzt, float* zout, int lane, int wave, int vcu, int G) {
;     ...
;             for (int rr = 0; rr < 16; ++rr) { p0[rr] = 0.f; p1[rr] = 0.f;
; #pragma unroll
;                 for (int j = 0; j < 4; ++j) { const f32x4 w0 = *(const LAS f32x4*)(wl + (((rr * 4 + j) * 2 + 0) * 64 + lane) * 4), w1 = *(const LAS f32x4*)(wl + (((rr * 4 + j) * 2 + 1) * 64 + lane) * 4);
; #pragma unroll
;                     for (int e = 0; e < 4; ++e) { p0[rr] += v[0][j][0][e] * w0[e] + v[0][j][1][e] * w1[e]; p1[rr] += v[1][j][0][e] * w0[e] + v[1][j][1][e] * w1[e]; } } }
;             const float z0 = reduce16(p0, lane), z1 = reduce16(p1, lane);
;             if ((lane & 3) == 0) { const int rr = ((lane >> 5) & 1) * 8 + ((lane >> 4) & 1) * 4 + ((lane >> 3) & 1) * 2 + ((lane >> 2) & 1);
	v_mul_f32_e32 v54, v82, v50
	v_mul_f32_e32 v50, v114, v50
	v_fmac_f32_e32 v50, v112, v46
	v_fmac_f32_e32 v54, v78, v46
	v_add_f32_e32 v46, 0, v50
	v_mul_f32_e32 v50, v83, v51
	v_mul_f32_e32 v51, v115, v51
	v_add_f32_e32 v54, 0, v54
	v_fmac_f32_e32 v50, v79, v47
	v_fmac_f32_e32 v51, v113, v47
	v_mul_f32_e32 v47, v76, v52
	v_add_f32_e32 v50, v50, v54
	v_fmac_f32_e32 v47, v74, v48
	v_add_f32_e32 v47, v47, v50
	v_mul_f32_e32 v50, v110, v52
	v_fmac_f32_e32 v50, v108, v48
	v_mul_f32_e32 v48, v77, v53
	v_fmac_f32_e32 v48, v75, v49
	ds_read_b128 v[54:57], v207
	ds_read_b128 v[74:77], v208
	v_add_f32_e32 v46, v51, v46
	v_add_f32_e32 v47, v48, v47
	v_mul_f32_e32 v48, v111, v53
	v_add_f32_e32 v46, v50, v46
	v_fmac_f32_e32 v48, v109, v49
	v_add_f32_e32 v46, v48, v46
	s_waitcnt lgkmcnt(0)
	v_mul_f32_e32 v48, v88, v74
	v_fmac_f32_e32 v48, v84, v54
	v_add_f32_e32 v47, v48, v47
	v_mul_f32_e32 v48, v122, v74
	v_fmac_f32_e32 v48, v120, v54
	v_add_f32_e32 v46, v48, v46
	v_mul_f32_e32 v48, v89, v75
	v_fmac_f32_e32 v48, v85, v55
	v_add_f32_e32 v47, v48, v47
	v_mul_f32_e32 v48, v123, v75
	v_fmac_f32_e32 v48, v121, v55
	v_add_f32_e32 v46, v48, v46
	v_mul_f32_e32 v48, v86, v76
	v_fmac_f32_e32 v48, v80, v56
	v_add_f32_e32 v54, v48, v47
	v_mul_f32_e32 v47, v118, v76
	v_fmac_f32_e32 v47, v116, v56
	v_add_f32_e32 v55, v47, v46
	ds_read_b128 v[46:49], v209
	ds_read_b128 v[50:53], v210
	v_mul_f32_e32 v56, v87, v77
	v_fmac_f32_e32 v56, v81, v57
	v_add_f32_e32 v54, v56, v54
	v_mul_f32_e32 v56, v119, v77
	v_fmac_f32_e32 v56, v117, v57
	s_waitcnt lgkmcnt(0)
	v_mul_f32_e32 v14, v14, v50
	v_add_f32_e32 v55, v56, v55
	v_mul_f32_e32 v56, v96, v50
	v_fmac_f32_e32 v14, v12, v46
	v_fmac_f32_e32 v56, v94, v46
	v_add_f32_e32 v12, v14, v55
	v_mul_f32_e32 v14, v97, v51
	v_mul_f32_e32 v15, v15, v51
	v_add_f32_e32 v54, v56, v54
	v_fmac_f32_e32 v14, v95, v47
	v_fmac_f32_e32 v15, v13, v47
	v_mul_f32_e32 v13, v92, v52
	v_mul_f32_e32 v10, v10, v52
	v_add_f32_e32 v14, v14, v54
	v_add_f32_e32 v12, v15, v12
	v_fmac_f32_e32 v13, v90, v48
	v_fmac_f32_e32 v10, v8, v48
	v_add_f32_e32 v46, v13, v14
	v_add_f32_e32 v8, v10, v12
	ds_read_b128 v[12:15], v211
	ds_read_b128 v[54:57], v212
	v_mul_f32_e32 v10, v93, v53
	v_mul_f32_e32 v11, v11, v53
	v_fmac_f32_e32 v10, v91, v49
	v_fmac_f32_e32 v11, v9, v49
	s_waitcnt lgkmcnt(0)
	v_mul_f32_e32 v9, v106, v54
	v_add_f32_e32 v10, v10, v46
	v_fmac_f32_e32 v9, v104, v12
	v_add_f32_e32 v9, v9, v10
	v_mul_f32_e32 v10, v20, v54
	v_add_f32_e32 v8, v11, v8
	v_fmac_f32_e32 v10, v18, v12
	v_add_f32_e32 v8, v10, v8
	v_mul_f32_e32 v10, v107, v55
	v_fmac_f32_e32 v10, v105, v13
	v_add_f32_e32 v9, v10, v9
	v_mul_f32_e32 v10, v21, v55
	v_cndmask_b32_e64 v11, v5, v38, s[6:7]
	v_fmac_f32_e32 v10, v19, v13
	ds_bpermute_b32 v11, v222, v11
	v_cndmask_b32_e64 v12, v24, v40, s[6:7]
	v_add_f32_e32 v8, v10, v8
	v_mul_f32_e32 v10, v102, v56
	ds_bpermute_b32 v12, v222, v12
	v_cndmask_b32_e64 v13, v26, v42, s[6:7]
	v_fmac_f32_e32 v10, v100, v14
	ds_bpermute_b32 v13, v222, v13
	v_add_f32_e32 v9, v10, v9
	v_mul_f32_e32 v10, v6, v56
	v_fmac_f32_e32 v10, v16, v14
	v_cndmask_b32_e64 v5, v38, v5, s[6:7]
	v_add_f32_e32 v8, v10, v8
	v_mul_f32_e32 v10, v103, v57
	s_waitcnt lgkmcnt(2)
	v_add_f32_e32 v5, v5, v11
	v_cndmask_b32_e64 v11, v40, v24, s[6:7]
	v_fmac_f32_e32 v10, v101, v15
	s_waitcnt lgkmcnt(1)
	v_add_f32_e32 v11, v11, v12
	v_cndmask_b32_e64 v12, v42, v26, s[6:7]
	v_add_f32_e32 v9, v10, v9
	v_mul_f32_e32 v10, v7, v57
	s_waitcnt lgkmcnt(0)
	v_add_f32_e32 v12, v12, v13
	v_cndmask_b32_e64 v13, v28, v44, s[6:7]
	v_fmac_f32_e32 v10, v17, v15
	ds_bpermute_b32 v13, v222, v13
	v_cndmask_b32_e64 v15, v30, v128, s[6:7]
	ds_bpermute_b32 v15, v222, v15
	v_cndmask_b32_e64 v16, v32, v129, s[6:7]
	ds_bpermute_b32 v16, v222, v16
	v_cndmask_b32_e64 v14, v44, v28, s[6:7]
	s_waitcnt lgkmcnt(2)
	v_add_f32_e32 v13, v14, v13
	v_cndmask_b32_e64 v14, v128, v30, s[6:7]
	s_waitcnt lgkmcnt(1)
	v_add_f32_e32 v14, v14, v15
	v_cndmask_b32_e64 v15, v129, v32, s[6:7]
	s_waitcnt lgkmcnt(0)
	v_add_f32_e32 v15, v15, v16
	v_cndmask_b32_e64 v16, v34, v124, s[6:7]
	ds_bpermute_b32 v16, v222, v16
	v_cndmask_b32_e64 v18, v36, v9, s[6:7]
	ds_bpermute_b32 v18, v222, v18
	v_cndmask_b32_e64 v17, v124, v34, s[6:7]
	v_cndmask_b32_e64 v9, v9, v36, s[6:7]
	s_waitcnt lgkmcnt(1)
	v_add_f32_e32 v16, v17, v16
	v_cndmask_b32_e64 v19, v5, v14, s[8:9]
	s_waitcnt lgkmcnt(0)
; __device__ __forceinline__ float reduce16(const float (&p)[16], int lane) {
;     float a[8], b[4], c[2];
;     { const bool hi = (lane & 32) != 0;
; #pragma unroll
;       for (int k = 0; k < 8; ++k) { const float send = hi ? p[k] : p[k + 8], keep = hi ? p[k + 8] : p[k]; a[k] = keep + __shfl_xor(send, 32); } }
;     { const bool hi = (lane & 16) != 0;
; #pragma unroll
;       for (int k = 0; k < 4; ++k) { const float send = hi ? a[k] : a[k + 4], keep = hi ? a[k + 4] : a[k]; b[k] = keep + __shfl_xor(send, 16); } }
;     { const bool hi = (lane & 8) != 0;
; #pragma unroll
;       for (int k = 0; k < 2; ++k) { const float send = hi ? b[k] : b[k + 2], keep = hi ? b[k + 2] : b[k]; c[k] = keep + __shfl_xor(send, 8); } }
;     const bool hi4 = (lane & 4) != 0; const float send = hi4 ? c[0] : c[1], keep = hi4 ? c[1] : c[0];
;     float d = keep + __shfl_xor(send, 4);
;     d += __shfl_xor(d, 2); d += __shfl_xor(d, 1);
;     return d;
; }
; template <bool ZP, bool XF32, bool OUT8 = false>
; __device__ __forceinline__ void norm_phase(LAS unsigned char* lds, const void* xin, const float* gain, const float* sh, const float* sc, bf16* hout, const float* wzt, float* zout, int lane, int wave, int vcu, int G) {
;     ...
;             const float z0 = reduce16(p0, lane), z1 = reduce16(p1, lane);
;             if ((lane & 3) == 0) { const int rr = ((lane >> 5) & 1) * 8 + ((lane >> 4) & 1) * 4 + ((lane >> 3) & 1) * 2 + ((lane >> 2) & 1);
;                 zout[(size_t)m0 * 16 + rr] = z0; zout[(size_t)(m0 + 1) * 16 + rr] = z1; }
	v_add_f32_e32 v9, v9, v18
	v_cndmask_b32_e64 v5, v14, v5, s[8:9]
	v_cndmask_b32_e64 v14, v11, v15, s[8:9]
	v_cndmask_b32_e64 v11, v15, v11, s[8:9]
	v_cndmask_b32_e64 v15, v12, v16, s[8:9]
	ds_bpermute_b32 v19, v221, v19
	ds_bpermute_b32 v15, v221, v15
	v_cndmask_b32_e64 v17, v13, v9, s[8:9]
	ds_bpermute_b32 v14, v221, v14
	ds_bpermute_b32 v17, v221, v17
	v_cndmask_b32_e64 v12, v16, v12, s[8:9]
	s_waitcnt lgkmcnt(3)
	v_add_f32_e32 v5, v5, v19
	s_waitcnt lgkmcnt(2)
	v_add_f32_e32 v12, v12, v15
	v_cndmask_b32_e64 v9, v9, v13, s[8:9]
	s_waitcnt lgkmcnt(1)
	v_add_f32_e32 v11, v11, v14
	s_waitcnt lgkmcnt(0)
	v_add_f32_e32 v9, v9, v17
	v_cndmask_b32_e64 v13, v5, v12, s[10:11]
	ds_bpermute_b32 v13, v220, v13
	v_cndmask_b32_e64 v14, v11, v9, s[10:11]
	ds_bpermute_b32 v14, v220, v14
	v_cndmask_b32_e64 v5, v12, v5, s[10:11]
	v_cndmask_b32_e64 v9, v9, v11, s[10:11]
	v_cndmask_b32_e64 v11, v22, v37, s[6:7]
	s_waitcnt lgkmcnt(1)
	v_add_f32_e32 v5, v5, v13
	ds_bpermute_b32 v11, v222, v11
	v_cndmask_b32_e64 v13, v23, v39, s[6:7]
	s_waitcnt lgkmcnt(1)
	v_add_f32_e32 v9, v9, v14
	ds_bpermute_b32 v13, v222, v13
	v_cndmask_b32_e64 v14, v25, v41, s[6:7]
	ds_bpermute_b32 v14, v222, v14
	v_cndmask_b32_e64 v12, v37, v22, s[6:7]
	s_waitcnt lgkmcnt(2)
	v_add_f32_e32 v11, v12, v11
	v_cndmask_b32_e64 v12, v39, v23, s[6:7]
	s_waitcnt lgkmcnt(1)
	v_add_f32_e32 v12, v12, v13
	v_cndmask_b32_e64 v13, v41, v25, s[6:7]
	s_waitcnt lgkmcnt(0)
	v_add_f32_e32 v13, v13, v14
	v_cndmask_b32_e64 v14, v27, v43, s[6:7]
	ds_bpermute_b32 v14, v222, v14
	v_cndmask_b32_e64 v16, v29, v45, s[6:7]
	ds_bpermute_b32 v16, v222, v16
	v_cndmask_b32_e64 v17, v31, v130, s[6:7]
	ds_bpermute_b32 v17, v222, v17
	v_cndmask_b32_e64 v15, v43, v27, s[6:7]
	s_waitcnt lgkmcnt(2)
	v_add_f32_e32 v14, v15, v14
	v_cndmask_b32_e64 v15, v45, v29, s[6:7]
	v_add_f32_e32 v8, v10, v8
	s_waitcnt lgkmcnt(1)
	v_add_f32_e32 v15, v15, v16
	v_cndmask_b32_e64 v16, v130, v31, s[6:7]
	s_waitcnt lgkmcnt(0)
	v_add_f32_e32 v16, v16, v17
	v_cndmask_b32_e64 v17, v33, v125, s[6:7]
	v_cndmask_b32_e64 v19, v35, v8, s[6:7]
	ds_bpermute_b32 v17, v222, v17
	ds_bpermute_b32 v19, v222, v19
	v_cndmask_b32_e64 v18, v125, v33, s[6:7]
	v_cndmask_b32_e64 v8, v8, v35, s[6:7]
	v_cndmask_b32_e64 v20, v11, v15, s[8:9]
	s_waitcnt lgkmcnt(1)
	v_add_f32_e32 v17, v18, v17
	s_waitcnt lgkmcnt(0)
	v_add_f32_e32 v8, v8, v19
	v_cndmask_b32_e64 v11, v15, v11, s[8:9]
	v_cndmask_b32_e64 v15, v12, v16, s[8:9]
	v_cndmask_b32_e64 v12, v16, v12, s[8:9]
	v_cndmask_b32_e64 v16, v13, v17, s[8:9]
	v_cndmask_b32_e64 v18, v14, v8, s[8:9]
	ds_bpermute_b32 v20, v221, v20
	ds_bpermute_b32 v15, v221, v15
	ds_bpermute_b32 v16, v221, v16
	ds_bpermute_b32 v18, v221, v18
	v_cndmask_b32_e64 v13, v17, v13, s[8:9]
	v_cndmask_b32_e64 v8, v8, v14, s[8:9]
	s_waitcnt lgkmcnt(3)
	v_add_f32_e32 v11, v11, v20
	s_waitcnt lgkmcnt(2)
	v_add_f32_e32 v12, v12, v15
	s_waitcnt lgkmcnt(1)
	v_add_f32_e32 v13, v13, v16
	s_waitcnt lgkmcnt(0)
	v_add_f32_e32 v8, v8, v18
	v_cndmask_b32_e64 v14, v11, v13, s[10:11]
	v_cndmask_b32_e64 v15, v12, v8, s[10:11]
	ds_bpermute_b32 v14, v220, v14
	ds_bpermute_b32 v15, v220, v15
	v_cndmask_b32_e64 v11, v13, v11, s[10:11]
	v_cndmask_b32_e64 v8, v8, v12, s[10:11]
	v_cndmask_b32_e64 v10, v5, v9, s[12:13]
	s_waitcnt lgkmcnt(1)
	v_add_f32_e32 v11, v11, v14
	s_waitcnt lgkmcnt(0)
	v_add_f32_e32 v8, v8, v15
	v_cndmask_b32_e64 v12, v11, v8, s[12:13]
	ds_bpermute_b32 v10, v219, v10
	ds_bpermute_b32 v12, v219, v12
	v_cndmask_b32_e64 v5, v9, v5, s[12:13]
	v_cndmask_b32_e64 v8, v8, v11, s[12:13]
	v_bfe_u32 v1, v6, 16, 1
	s_waitcnt lgkmcnt(1)
	v_add_f32_e32 v5, v5, v10
	s_waitcnt lgkmcnt(0)
	v_add_f32_e32 v8, v8, v12
	ds_bpermute_b32 v9, v218, v5
	ds_bpermute_b32 v10, v218, v8
	v_add3_u32 v1, v6, v1, s41
	v_lshrrev_b32_e32 v11, 16, v1
	s_waitcnt lgkmcnt(1)
	v_add_f32_e32 v1, v5, v9
	s_waitcnt lgkmcnt(0)
	v_add_f32_e32 v8, v8, v10
	ds_bpermute_b32 v6, v217, v1
	ds_bpermute_b32 v9, v217, v8
	v_bfe_u32 v5, v7, 16, 1
	v_add3_u32 v5, v7, v5, s41
	v_and_or_b32 v5, v5, s39, v11
	global_store_dwordx4 v[98:99], v[2:5], off offset:3072
	s_and_saveexec_b64 s[22:23], s[14:15]
	s_cbranch_execz .LBB0_1552
	s_lshl_b64 s[0:1], s[18:19], 6
	s_waitcnt lgkmcnt(1)
	v_add_f32_e32 v1, v1, v6
	v_lshl_add_u64 v[2:3], v[60:61], 0, s[0:1]
	s_lshl_b64 s[0:1], s[20:21], 6
	s_waitcnt lgkmcnt(0)
	v_add_f32_e32 v4, v8, v9
	global_store_dword v[2:3], v1, off
	v_lshl_add_u64 v[2:3], v[60:61], 0, s[0:1]
	global_store_dword v[2:3], v4, off
	s_branch .LBB0_1552

; template <bool F8>
; __device__ __forceinline__ void transpose_item(const float* W, int ldw, int k0, int srccol0, bf16* WT, int ldt, int dstrow0, LAS float* scr, int lane) {
;     float wv[32];
; #pragma unroll
;     for (int i = 0; i < 32; ++i) wv[i] = W[(size_t)(k0 + 2 * i + (lane >> 5)) * ldw + srccol0 + (lane & 31)];
.LBB0_1883:
	s_lshl_b32 s22, s25, 6
	v_or_b32_e32 v7, s22, v3
	s_ashr_i32 s25, s24, 31
	s_ashr_i32 s23, s22, 31
	v_lshl_add_u64 v[12:13], s[24:25], 2, v[8:9]
	s_mul_i32 s24, s20, s23
	v_mul_lo_u32 v27, s21, v7
	v_mad_u64_u32 v[28:29], s[0:1], s20, v7, 0
	v_add3_u32 v29, v29, s24, v27
	v_or_b32_e32 v27, 2, v7
	v_mul_lo_u32 v32, s21, v27
	v_mad_u64_u32 v[30:31], s[0:1], s20, v27, 0
	v_or_b32_e32 v27, 4, v7
	v_add3_u32 v31, v31, s24, v32
	v_mul_lo_u32 v34, s21, v27
	v_mad_u64_u32 v[32:33], s[0:1], s20, v27, 0
	v_or_b32_e32 v27, 6, v7
	v_add3_u32 v33, v33, s24, v34
	v_mul_lo_u32 v36, s21, v27
	v_mad_u64_u32 v[34:35], s[0:1], s20, v27, 0
	v_or_b32_e32 v27, 8, v7
	v_add3_u32 v35, v35, s24, v36
	v_mul_lo_u32 v38, s21, v27
	v_mad_u64_u32 v[36:37], s[0:1], s20, v27, 0
	v_or_b32_e32 v27, 10, v7
	v_add3_u32 v37, v37, s24, v38
	v_mul_lo_u32 v40, s21, v27
	v_mad_u64_u32 v[38:39], s[0:1], s20, v27, 0
	v_or_b32_e32 v27, 12, v7
	v_add3_u32 v39, v39, s24, v40
	v_mul_lo_u32 v42, s21, v27
	v_mad_u64_u32 v[40:41], s[0:1], s20, v27, 0
	v_or_b32_e32 v27, 14, v7
	v_add3_u32 v41, v41, s24, v42
	v_mul_lo_u32 v44, s21, v27
	v_mad_u64_u32 v[42:43], s[0:1], s20, v27, 0
	v_lshl_add_u64 v[28:29], v[28:29], 2, v[12:13]
	v_add3_u32 v43, v43, s24, v44
	v_lshl_add_u64 v[30:31], v[30:31], 2, v[12:13]
	v_lshl_add_u64 v[32:33], v[32:33], 2, v[12:13]
	v_lshl_add_u64 v[34:35], v[34:35], 2, v[12:13]
	v_lshl_add_u64 v[36:37], v[36:37], 2, v[12:13]
	v_lshl_add_u64 v[38:39], v[38:39], 2, v[12:13]
	v_lshl_add_u64 v[40:41], v[40:41], 2, v[12:13]
	v_lshl_add_u64 v[42:43], v[42:43], 2, v[12:13]
	global_load_dword v27, v[28:29], off
	global_load_dword v44, v[30:31], off
	global_load_dword v45, v[32:33], off
	global_load_dword v46, v[34:35], off
	global_load_dword v47, v[36:37], off
	global_load_dword v48, v[38:39], off
	global_load_dword v49, v[40:41], off
	global_load_dword v50, v[42:43], off
	v_or_b32_e32 v28, 16, v7
	v_mul_lo_u32 v30, s21, v28
	v_mad_u64_u32 v[28:29], s[0:1], s20, v28, 0
	v_add3_u32 v29, v29, s24, v30
	v_or_b32_e32 v30, 18, v7
	v_mul_lo_u32 v32, s21, v30
	v_mad_u64_u32 v[30:31], s[0:1], s20, v30, 0
	v_add3_u32 v31, v31, s24, v32
	v_or_b32_e32 v32, 20, v7
	v_mul_lo_u32 v34, s21, v32
	v_mad_u64_u32 v[32:33], s[0:1], s20, v32, 0
	v_add3_u32 v33, v33, s24, v34
	v_or_b32_e32 v34, 22, v7
	v_mul_lo_u32 v36, s21, v34
	v_mad_u64_u32 v[34:35], s[0:1], s20, v34, 0
	v_add3_u32 v35, v35, s24, v36
	v_or_b32_e32 v36, 24, v7
	v_mul_lo_u32 v38, s21, v36
	v_mad_u64_u32 v[36:37], s[0:1], s20, v36, 0
	v_add3_u32 v37, v37, s24, v38
	v_or_b32_e32 v38, 26, v7
	v_mul_lo_u32 v40, s21, v38
	v_mad_u64_u32 v[38:39], s[0:1], s20, v38, 0
	v_add3_u32 v39, v39, s24, v40
	v_or_b32_e32 v40, 28, v7
	v_mul_lo_u32 v42, s21, v40
	v_mad_u64_u32 v[40:41], s[0:1], s20, v40, 0
	v_add3_u32 v41, v41, s24, v42
	v_or_b32_e32 v42, 30, v7
	v_mul_lo_u32 v51, s21, v42
	v_mad_u64_u32 v[42:43], s[0:1], s20, v42, 0
	v_lshl_add_u64 v[28:29], v[28:29], 2, v[12:13]
	v_add3_u32 v43, v43, s24, v51
	v_lshl_add_u64 v[30:31], v[30:31], 2, v[12:13]
	v_lshl_add_u64 v[32:33], v[32:33], 2, v[12:13]
	v_lshl_add_u64 v[34:35], v[34:35], 2, v[12:13]
	v_lshl_add_u64 v[36:37], v[36:37], 2, v[12:13]
	v_lshl_add_u64 v[38:39], v[38:39], 2, v[12:13]
	v_lshl_add_u64 v[40:41], v[40:41], 2, v[12:13]
	v_lshl_add_u64 v[42:43], v[42:43], 2, v[12:13]
	global_load_dword v51, v[28:29], off
	global_load_dword v52, v[30:31], off
	global_load_dword v53, v[32:33], off
	global_load_dword v54, v[34:35], off
	global_load_dword v55, v[36:37], off
	global_load_dword v56, v[38:39], off
	global_load_dword v57, v[40:41], off
	global_load_dword v58, v[42:43], off
	v_or_b32_e32 v28, 32, v7
	v_mul_lo_u32 v30, s21, v28
	v_mad_u64_u32 v[28:29], s[0:1], s20, v28, 0
	v_add3_u32 v29, v29, s24, v30
	v_or_b32_e32 v30, 34, v7
	v_mul_lo_u32 v32, s21, v30
	v_mad_u64_u32 v[30:31], s[0:1], s20, v30, 0
	v_add3_u32 v31, v31, s24, v32
	v_or_b32_e32 v32, 36, v7
	v_mul_lo_u32 v34, s21, v32
	v_mad_u64_u32 v[32:33], s[0:1], s20, v32, 0
	v_add3_u32 v33, v33, s24, v34
	v_or_b32_e32 v34, 38, v7
	v_mul_lo_u32 v36, s21, v34
	v_mad_u64_u32 v[34:35], s[0:1], s20, v34, 0
	v_add3_u32 v35, v35, s24, v36
	v_or_b32_e32 v36, 40, v7
	v_mul_lo_u32 v38, s21, v36
	v_mad_u64_u32 v[36:37], s[0:1], s20, v36, 0
	v_add3_u32 v37, v37, s24, v38
	v_or_b32_e32 v38, 42, v7
	v_mul_lo_u32 v40, s21, v38
	v_mad_u64_u32 v[38:39], s[0:1], s20, v38, 0
	v_add3_u32 v39, v39, s24, v40
	v_or_b32_e32 v40, 44, v7
	v_mul_lo_u32 v42, s21, v40
	v_mad_u64_u32 v[40:41], s[0:1], s20, v40, 0
	v_add3_u32 v41, v41, s24, v42
	v_or_b32_e32 v42, 46, v7
	v_mul_lo_u32 v59, s21, v42
	v_mad_u64_u32 v[42:43], s[0:1], s20, v42, 0
	v_lshl_add_u64 v[28:29], v[28:29], 2, v[12:13]
	v_add3_u32 v43, v43, s24, v59
	v_lshl_add_u64 v[30:31], v[30:31], 2, v[12:13]
	v_lshl_add_u64 v[32:33], v[32:33], 2, v[12:13]
	v_lshl_add_u64 v[34:35], v[34:35], 2, v[12:13]
	v_lshl_add_u64 v[36:37], v[36:37], 2, v[12:13]
	v_lshl_add_u64 v[38:39], v[38:39], 2, v[12:13]
	v_lshl_add_u64 v[40:41], v[40:41], 2, v[12:13]
	v_lshl_add_u64 v[42:43], v[42:43], 2, v[12:13]
	global_load_dword v59, v[28:29], off
	global_load_dword v60, v[30:31], off
	global_load_dword v61, v[32:33], off
	global_load_dword v62, v[34:35], off
	global_load_dword v63, v[36:37], off
	global_load_dword v64, v[38:39], off
	global_load_dword v65, v[40:41], off
	global_load_dword v66, v[42:43], off
	v_or_b32_e32 v28, 48, v7
	v_mul_lo_u32 v30, s21, v28
	v_mad_u64_u32 v[28:29], s[0:1], s20, v28, 0
	v_add3_u32 v29, v29, s24, v30
	v_or_b32_e32 v30, 50, v7
	v_mul_lo_u32 v32, s21, v30
; #define LAS __attribute__((address_space(3)))
; #define LDS_WAIT() asm volatile("s_waitcnt lgkmcnt(0)" ::: "memory")
; __device__ __forceinline__ unsigned pk2(float lo, float hi) { return f2bf(lo) | (f2bf(hi) << 16); }
; template <bool F8>
; __device__ __forceinline__ void transpose_item(const float* W, int ldw, int k0, int srccol0, bf16* WT, int ldt, int dstrow0, LAS float* scr, int lane) {
;     ...
; #pragma unroll
;     for (int i = 0; i < 32; ++i) scr[(2 * i + (lane >> 5)) * 33 + (lane & 31)] = wv[i];
;     LDS_WAIT(); asm volatile("" ::: "memory");
;     const int c = lane & 7;
; #pragma unroll
;     for (int j = 0; j < 4; ++j) { const int n = (lane >> 3) + 8 * j; const LAS float* s = scr + (8 * c) * 33 + n;
;         if constexpr (F8) { *(v2u*)((unsigned char*)WT + (size_t)(dstrow0 + n) * ldt + k0 + 8 * c) = pack8_fp8(s[0 * 33], s[1 * 33], s[2 * 33], s[3 * 33], s[4 * 33], s[5 * 33], s[6 * 33], s[7 * 33], FP8_WSCALE); }
;         else { v4u o; o.x = pk2(s[0 * 33], s[1 * 33]); o.y = pk2(s[2 * 33], s[3 * 33]); o.z = pk2(s[4 * 33], s[5 * 33]); o.w = pk2(s[6 * 33], s[7 * 33]);
;             *(v4u*)(WT + (size_t)(dstrow0 + n) * ldt + k0 + 8 * c) = o; } }
;     LDS_WAIT(); asm volatile("" ::: "memory");
	v_mad_u64_u32 v[30:31], s[0:1], s20, v30, 0
	v_add3_u32 v31, v31, s24, v32
	v_or_b32_e32 v32, 52, v7
	v_mul_lo_u32 v34, s21, v32
	v_mad_u64_u32 v[32:33], s[0:1], s20, v32, 0
	v_add3_u32 v33, v33, s24, v34
	v_or_b32_e32 v34, 54, v7
	v_mul_lo_u32 v36, s21, v34
	v_mad_u64_u32 v[34:35], s[0:1], s20, v34, 0
	v_add3_u32 v35, v35, s24, v36
	v_or_b32_e32 v36, 56, v7
	v_mul_lo_u32 v38, s21, v36
	v_mad_u64_u32 v[36:37], s[0:1], s20, v36, 0
	v_add3_u32 v37, v37, s24, v38
	v_or_b32_e32 v38, 58, v7
	v_mul_lo_u32 v40, s21, v38
	v_mad_u64_u32 v[38:39], s[0:1], s20, v38, 0
	v_add3_u32 v39, v39, s24, v40
	v_or_b32_e32 v40, 60, v7
	v_mul_lo_u32 v42, s21, v40
	v_mad_u64_u32 v[40:41], s[0:1], s20, v40, 0
	v_or_b32_e32 v7, 62, v7
	v_add3_u32 v41, v41, s24, v42
	v_mul_lo_u32 v67, s21, v7
	v_mad_u64_u32 v[42:43], s[0:1], s20, v7, 0
	v_add3_u32 v43, v43, s24, v67
	v_lshl_add_u64 v[28:29], v[28:29], 2, v[12:13]
	v_lshl_add_u64 v[30:31], v[30:31], 2, v[12:13]
	v_lshl_add_u64 v[32:33], v[32:33], 2, v[12:13]
	v_lshl_add_u64 v[34:35], v[34:35], 2, v[12:13]
	v_lshl_add_u64 v[36:37], v[36:37], 2, v[12:13]
	v_lshl_add_u64 v[38:39], v[38:39], 2, v[12:13]
	v_lshl_add_u64 v[40:41], v[40:41], 2, v[12:13]
	v_lshl_add_u64 v[12:13], v[42:43], 2, v[12:13]
	global_load_dword v7, v[28:29], off
	s_nop 0
	global_load_dword v28, v[30:31], off
	global_load_dword v29, v[32:33], off
	s_nop 0
	global_load_dword v30, v[34:35], off
	global_load_dword v31, v[36:37], off
	global_load_dword v32, v[38:39], off
	global_load_dword v33, v[40:41], off
	s_nop 0
	global_load_dword v12, v[12:13], off
	s_waitcnt vmcnt(0)
	ds_write2_b32 v19, v27, v44 offset1:66
	ds_write2_b32 v19, v45, v46 offset0:132 offset1:198
	ds_write2_b32 v20, v47, v48 offset0:8 offset1:74
	ds_write2_b32 v20, v49, v50 offset0:140 offset1:206
	ds_write2_b32 v21, v51, v52 offset0:16 offset1:82
	ds_write2_b32 v21, v53, v54 offset0:148 offset1:214
	ds_write2_b32 v22, v55, v56 offset0:24 offset1:90
	ds_write2_b32 v22, v57, v58 offset0:156 offset1:222
	ds_write2_b32 v23, v59, v60 offset0:32 offset1:98
	ds_write2_b32 v23, v61, v62 offset0:164 offset1:230
	ds_write2_b32 v24, v63, v64 offset0:40 offset1:106
	ds_write2_b32 v24, v65, v66 offset0:172 offset1:238
	ds_write2_b32 v25, v7, v28 offset0:48 offset1:114
	ds_write2_b32 v25, v29, v30 offset0:180 offset1:246
	ds_write2_b32 v26, v31, v32 offset0:56 offset1:122
	ds_write2_b32 v26, v33, v12 offset0:188 offset1:254
	s_waitcnt lgkmcnt(0)
	ds_read2_b32 v[12:13], v15 offset1:8
	ds_read2_b32 v[34:35], v15 offset0:33 offset1:41
	ds_read2_b32 v[36:37], v15 offset0:66 offset1:74
	ds_read2_b32 v[38:39], v15 offset0:99 offset1:107
	ds_read2_b32 v[40:41], v15 offset0:132 offset1:140
	s_waitcnt lgkmcnt(4)
	v_bfe_u32 v7, v12, 16, 1
	v_add3_u32 v7, v12, v7, s36
	s_waitcnt lgkmcnt(3)
	v_bfe_u32 v12, v34, 16, 1
	v_lshrrev_b32_e32 v7, 16, v7
	v_add3_u32 v12, v34, v12, s36
	ds_read2_b32 v[42:43], v15 offset0:165 offset1:173
	v_and_or_b32 v28, v12, s37, v7
	s_waitcnt lgkmcnt(3)
	s_waitcnt lgkmcnt(2)
	ds_read2_b32 v[44:45], v15 offset0:198 offset1:206
	ds_read2_b32 v[46:47], v15 offset0:231 offset1:239
	v_cvt_pk_bf16_f32 v29, v36, v38
	s_waitcnt lgkmcnt(3)
	s_waitcnt lgkmcnt(2)
	v_cvt_pk_bf16_f32 v30, v40, v42
	s_waitcnt lgkmcnt(1)
	s_waitcnt lgkmcnt(0)
	v_cvt_pk_bf16_f32 v31, v44, v46
	v_or_b32_e32 v7, s43, v14
	s_ashr_i32 s0, s43, 31
	v_lshl_add_u64 v[32:33], s[22:23], 1, v[10:11]
	s_mul_i32 s22, s0, s6
	v_mad_u64_u32 v[48:49], s[0:1], v7, s6, 0
	v_bfe_u32 v7, v13, 16, 1
	v_add_u32_e32 v49, s22, v49
	v_add3_u32 v7, v13, v7, s36
	v_bfe_u32 v12, v35, 16, 1
	v_lshl_add_u64 v[48:49], v[48:49], 1, v[32:33]
	v_lshrrev_b32_e32 v7, 16, v7
	v_add3_u32 v12, v35, v12, s36
	global_store_dwordx4 v[48:49], v[28:31], off
	ds_read2_b32 v[34:35], v15 offset0:16 offset1:24
	s_addk_i32 s27, 0x400
	v_and_or_b32 v28, v12, s37, v7
	v_cvt_pk_bf16_f32 v29, v37, v39
	v_cvt_pk_bf16_f32 v30, v41, v43
	v_cvt_pk_bf16_f32 v31, v45, v47
	v_or_b32_e32 v7, s43, v16
	v_mad_u64_u32 v[12:13], s[0:1], v7, s6, 0
	v_add_u32_e32 v13, s22, v13
	v_lshl_add_u64 v[12:13], v[12:13], 1, v[32:33]
	global_store_dwordx4 v[12:13], v[28:31], off
	ds_read2_b32 v[12:13], v15 offset0:49 offset1:57
	ds_read2_b32 v[36:37], v15 offset0:82 offset1:90
	ds_read2_b32 v[38:39], v15 offset0:115 offset1:123
	s_waitcnt lgkmcnt(3)
	v_bfe_u32 v7, v34, 16, 1
	v_add3_u32 v7, v34, v7, s36
	s_waitcnt lgkmcnt(2)
	v_bfe_u32 v27, v12, 16, 1
	ds_read2_b32 v[40:41], v15 offset0:148 offset1:156
	v_lshrrev_b32_e32 v7, 16, v7
	v_add3_u32 v12, v12, v27, s36
	ds_read2_b32 v[42:43], v15 offset0:181 offset1:189
	v_and_or_b32 v28, v12, s37, v7
	s_waitcnt lgkmcnt(3)
	s_waitcnt lgkmcnt(2)
	ds_read2_b32 v[44:45], v15 offset0:214 offset1:222
	ds_read2_b32 v[46:47], v15 offset0:247 offset1:255
	v_cvt_pk_bf16_f32 v29, v36, v38
	s_waitcnt lgkmcnt(3)
	s_waitcnt lgkmcnt(2)
	v_cvt_pk_bf16_f32 v30, v40, v42
	s_waitcnt lgkmcnt(1)
	s_waitcnt lgkmcnt(0)
	v_cvt_pk_bf16_f32 v31, v44, v46
	v_or_b32_e32 v7, s43, v17
	v_mad_u64_u32 v[48:49], s[0:1], v7, s6, 0
	v_add_u32_e32 v49, s22, v49
	v_lshl_add_u64 v[48:49], v[48:49], 1, v[32:33]
	global_store_dwordx4 v[48:49], v[28:31], off
	s_nop 1
	v_cvt_pk_bf16_f32 v28, v35, v13
	v_cvt_pk_bf16_f32 v29, v37, v39
	v_cvt_pk_bf16_f32 v30, v41, v43
	v_cvt_pk_bf16_f32 v31, v45, v47
	v_or_b32_e32 v7, s43, v18
	v_mad_u64_u32 v[12:13], s[0:1], v7, s6, 0
	v_add_u32_e32 v13, s22, v13
	v_lshl_add_u64 v[12:13], v[12:13], 1, v[32:33]
	global_store_dwordx4 v[12:13], v[28:31], off
	s_waitcnt lgkmcnt(0)
	s_add_i32 s0, s39, s27
	s_cmp_lt_i32 s0, s26
	s_cbranch_scc0 .LBB0_1849

; __device__ __forceinline__ void unpack8(const v4u& w, float (&f)[8]) { f[0] = bflo(w.x); f[1] = bfhi(w.x); f[2] = bflo(w.y); f[3] = bfhi(w.y); f[4] = bflo(w.z); f[5] = bfhi(w.z); f[6] = bflo(w.w); f[7] = bfhi(w.w); }
; __device__ __forceinline__ void pool_phase(const bf16* H, bf16* MX, int tid, int vcu, int G) {
;     ...
;         for (int r0 = 0; r0 < 32; r0 += 8) {
;             v4u cw[8], ow[8];
; #pragma unroll
;             for (int u = 0; u < 8; ++u) { const int r = r0 + u; cw[u] = *(const v4u*)(hp + (size_t)r * D);
;                 ow[u] = (t0 + r - win >= 0) ? *(const v4u*)(hp + (ptrdiff_t)(r - win) * D) : (v4u){0u, 0u, 0u, 0u}; }
; #pragma unroll
;             for (int u = 0; u < 8; ++u) { const int r = r0 + u, t = t0 + r; const int cnt = (t + 1 < win) ? t + 1 : win;
;                 float cur[8], old[8], y[8]; unpack8(cw[u], cur); unpack8(ow[u], old);
;                 const float inv = 1.0f / (float)cnt;
; #pragma unroll
;                 for (int e = 0; e < 8; ++e) { sum[e] += cur[e] - old[e]; y[e] = sum[e] * inv - cur[e]; }
.LBB0_2568:
	s_or_b64 exec, exec, s[18:19]
	v_min_u32_e32 v84, v86, v87
	v_cvt_f32_ubyte0_e32 v84, v84
	v_div_scale_f32 v85, s[0:1], v84, v84, 1.0
	v_rcp_f32_e32 v86, v85
	v_div_scale_f32 v95, vcc, 1.0, v84, 1.0
	v_min_u32_e32 v88, v88, v87
	v_fma_f32 v96, -v85, v86, 1.0
	v_fmac_f32_e32 v86, v96, v86
	v_mul_f32_e32 v96, v95, v86
	v_fma_f32 v97, -v85, v96, v95
	v_fmac_f32_e32 v96, v97, v86
	v_cvt_f32_ubyte0_e32 v88, v88
	v_fma_f32 v85, -v85, v96, v95
	v_div_scale_f32 v95, s[0:1], v88, v88, 1.0
	v_rcp_f32_e32 v97, v95
	v_div_fmas_f32 v85, v85, v86, v96
	v_div_fixup_f32 v98, v85, v84, 1.0
	s_waitcnt vmcnt(0)
	v_lshlrev_b32_e32 v101, 16, v65
	v_fma_f32 v84, -v95, v97, 1.0
	v_fmac_f32_e32 v97, v84, v97
	v_div_scale_f32 v84, vcc, 1.0, v88, 1.0
	v_mul_f32_e32 v85, v84, v97
	v_fma_f32 v86, -v95, v85, v84
	v_fmac_f32_e32 v85, v86, v97
	v_min_u32_e32 v86, v90, v87
	v_cvt_f32_ubyte0_e32 v86, v86
	v_div_scale_f32 v90, s[0:1], v86, v86, 1.0
	v_fma_f32 v84, -v95, v85, v84
	v_rcp_f32_e32 v95, v90
	v_div_fmas_f32 v84, v84, v97, v85
	v_div_fixup_f32 v84, v84, v88, 1.0
	v_lshlrev_b32_e32 v97, 16, v61
	v_fma_f32 v85, -v90, v95, 1.0
	v_fmac_f32_e32 v95, v85, v95
	v_div_scale_f32 v85, vcc, 1.0, v86, 1.0
	v_mul_f32_e32 v88, v85, v95
	v_fma_f32 v96, -v90, v88, v85
	v_fmac_f32_e32 v88, v96, v95
	v_fma_f32 v85, -v90, v88, v85
	v_min_u32_e32 v90, v91, v87
	v_cvt_f32_ubyte0_e32 v90, v90
	v_div_scale_f32 v91, s[0:1], v90, v90, 1.0
	v_rcp_f32_e32 v96, v91
	v_div_fmas_f32 v85, v85, v95, v88
	v_div_fixup_f32 v86, v85, v86, 1.0
	v_lshlrev_b32_e32 v100, 16, v64
	v_fma_f32 v85, -v91, v96, 1.0
	v_fmac_f32_e32 v96, v85, v96
	v_div_scale_f32 v85, vcc, 1.0, v90, 1.0
	v_mul_f32_e32 v88, v85, v96
	v_fma_f32 v95, -v91, v88, v85
	v_fmac_f32_e32 v88, v95, v96
	v_fma_f32 v85, -v91, v88, v85
	v_min_u32_e32 v91, v92, v87
	v_cvt_f32_ubyte0_e32 v91, v91
	v_div_scale_f32 v92, s[0:1], v91, v91, 1.0
	v_rcp_f32_e32 v95, v92
	v_div_fmas_f32 v85, v85, v96, v88
	v_div_fixup_f32 v88, v85, v90, 1.0
	v_lshlrev_b32_e32 v109, 16, v55
	v_fma_f32 v85, -v92, v95, 1.0
	v_fmac_f32_e32 v95, v85, v95
	v_div_scale_f32 v85, vcc, 1.0, v91, 1.0
	v_mul_f32_e32 v90, v85, v95
	v_fma_f32 v96, -v92, v90, v85
	v_fmac_f32_e32 v90, v96, v95
	v_fma_f32 v85, -v92, v90, v85
	v_min_u32_e32 v92, v93, v87
	v_cvt_f32_ubyte0_e32 v92, v92
	v_div_scale_f32 v93, s[0:1], v92, v92, 1.0
	v_rcp_f32_e32 v96, v93
	v_div_fmas_f32 v85, v85, v95, v90
	v_div_fixup_f32 v90, v85, v91, 1.0
	v_lshlrev_b32_e32 v108, 16, v54
	v_fma_f32 v85, -v93, v96, 1.0
	v_fmac_f32_e32 v96, v85, v96
	v_div_scale_f32 v85, vcc, 1.0, v92, 1.0
	v_mul_f32_e32 v91, v85, v96
	v_fma_f32 v95, -v93, v91, v85
	v_fmac_f32_e32 v91, v95, v96
	v_fma_f32 v85, -v93, v91, v85
	v_min_u32_e32 v93, v94, v87
	v_cvt_f32_ubyte0_e32 v93, v93
	v_div_scale_f32 v94, s[0:1], v93, v93, 1.0
	v_rcp_f32_e32 v95, v94
	v_div_fmas_f32 v85, v85, v96, v91
	v_div_fixup_f32 v92, v85, v92, 1.0
	v_and_b32_e32 v111, 0xffff0000, v55
	v_fma_f32 v85, -v94, v95, 1.0
	v_fmac_f32_e32 v95, v85, v95
	v_div_scale_f32 v85, vcc, 1.0, v93, 1.0
	v_mul_f32_e32 v91, v85, v95
	v_fma_f32 v96, -v94, v91, v85
	v_fmac_f32_e32 v91, v96, v95
	v_lshlrev_b32_e32 v96, 16, v60
	v_and_b32_e32 v110, 0xffff0000, v54
	v_lshlrev_b32_e32 v55, 16, v15
	v_lshlrev_b32_e32 v54, 16, v14
	v_and_b32_e32 v15, 0xffff0000, v15
	v_and_b32_e32 v14, 0xffff0000, v14
	v_lshlrev_b32_e32 v107, 16, v27
	v_lshlrev_b32_e32 v106, 16, v26
	v_and_b32_e32 v27, 0xffff0000, v27
	v_and_b32_e32 v26, 0xffff0000, v26
	v_pk_add_f32 v[102:103], v[96:97], v[100:101] neg_lo:[0,1] neg_hi:[0,1]
	v_and_b32_e32 v100, 0xffff0000, v60
	v_add_u32_e32 v60, 16, v67
	v_pk_add_f32 v[26:27], v[14:15], v[26:27] neg_lo:[0,1] neg_hi:[0,1]
	v_fma_f32 v85, -v94, v91, v85
	v_min_u32_e32 v60, v60, v87
	v_pk_add_f32 v[106:107], v[54:55], v[106:107] neg_lo:[0,1] neg_hi:[0,1]
	v_pk_add_f32 v[26:27], v[78:79], v[26:27]
	v_div_fmas_f32 v85, v85, v95, v91
	v_cvt_f32_ubyte0_e32 v67, v60
	v_pk_add_f32 v[76:77], v[76:77], v[106:107]
	v_pk_fma_f32 v[106:107], v[98:99], v[26:27], v[14:15] op_sel_hi:[0,1,1] neg_lo:[0,0,1] neg_hi:[0,0,1]
	v_lshlrev_b32_e32 v15, 16, v11
	v_lshlrev_b32_e32 v14, 16, v10
	v_lshlrev_b32_e32 v79, 16, v7
	v_lshlrev_b32_e32 v78, 16, v6
	v_div_fixup_f32 v94, v85, v93, 1.0
	v_div_scale_f32 v85, s[0:1], v67, v67, 1.0
	v_pk_add_f32 v[78:79], v[14:15], v[78:79] neg_lo:[0,1] neg_hi:[0,1]
	v_lshlrev_b32_e32 v113, 16, v23
	v_lshlrev_b32_e32 v112, 16, v22
	v_lshlrev_b32_e32 v115, 16, v31
	v_lshlrev_b32_e32 v114, 16, v30
	v_rcp_f32_e32 v91, v85
	v_pk_fma_f32 v[54:55], v[98:99], v[76:77], v[54:55] op_sel_hi:[0,1,1] neg_lo:[0,0,1] neg_hi:[0,0,1]
	v_pk_add_f32 v[114:115], v[112:113], v[114:115] neg_lo:[0,1] neg_hi:[0,1]
	v_lshlrev_b32_e32 v117, 16, v35
	v_lshlrev_b32_e32 v116, 16, v34
	v_lshlrev_b32_e32 v119, 16, v19
	v_lshlrev_b32_e32 v118, 16, v18
	v_pk_add_f32 v[76:77], v[76:77], v[78:79]
	v_pk_add_f32 v[118:119], v[116:117], v[118:119] neg_lo:[0,1] neg_hi:[0,1]
	v_lshlrev_b32_e32 v121, 16, v43
	v_lshlrev_b32_e32 v120, 16, v42
	v_lshlrev_b32_e32 v123, 16, v47
	v_lshlrev_b32_e32 v122, 16, v46
	v_pk_add_f32 v[78:79], v[76:77], v[114:115]
	v_and_b32_e32 v11, 0xffff0000, v11
	v_and_b32_e32 v10, 0xffff0000, v10
	v_and_b32_e32 v7, 0xffff0000, v7
	v_and_b32_e32 v6, 0xffff0000, v6
	v_pk_add_f32 v[122:123], v[120:121], v[122:123] neg_lo:[0,1] neg_hi:[0,1]
	v_lshlrev_b32_e32 v125, 16, v51
	v_lshlrev_b32_e32 v124, 16, v50
	v_lshlrev_b32_e32 v127, 16, v39
	v_lshlrev_b32_e32 v126, 16, v38
	v_pk_add_f32 v[114:115], v[78:79], v[118:119]
	v_pk_add_f32 v[6:7], v[10:11], v[6:7] neg_lo:[0,1] neg_hi:[0,1]
	v_and_b32_e32 v23, 0xffff0000, v23
	v_and_b32_e32 v22, 0xffff0000, v22
	v_and_b32_e32 v31, 0xffff0000, v31
; __device__ __forceinline__ void unpack8(const v4u& w, float (&f)[8]) { f[0] = bflo(w.x); f[1] = bfhi(w.x); f[2] = bflo(w.y); f[3] = bfhi(w.y); f[4] = bflo(w.z); f[5] = bfhi(w.z); f[6] = bflo(w.w); f[7] = bfhi(w.w); }
; __device__ __forceinline__ void pool_phase(const bf16* H, bf16* MX, int tid, int vcu, int G) {
;     ...
;             for (int u = 0; u < 8; ++u) { const int r = r0 + u, t = t0 + r; const int cnt = (t + 1 < win) ? t + 1 : win;
;                 float cur[8], old[8], y[8]; unpack8(cw[u], cur); unpack8(ow[u], old);
;                 const float inv = 1.0f / (float)cnt;
; #pragma unroll
;                 for (int e = 0; e < 8; ++e) { sum[e] += cur[e] - old[e]; y[e] = sum[e] * inv - cur[e]; }
	v_and_b32_e32 v30, 0xffff0000, v30
	v_and_b32_e32 v101, 0xffff0000, v61
	v_and_b32_e32 v61, 0xffff0000, v65
	v_and_b32_e32 v60, 0xffff0000, v64
	v_pk_add_f32 v[126:127], v[124:125], v[126:127] neg_lo:[0,1] neg_hi:[0,1]
	v_pk_add_f32 v[118:119], v[114:115], v[122:123]
	v_pk_add_f32 v[30:31], v[22:23], v[30:31] neg_lo:[0,1] neg_hi:[0,1]
	v_and_b32_e32 v35, 0xffff0000, v35
	v_and_b32_e32 v34, 0xffff0000, v34
	v_and_b32_e32 v19, 0xffff0000, v19
	v_and_b32_e32 v18, 0xffff0000, v18
	v_pk_add_f32 v[6:7], v[26:27], v[6:7]
	v_pk_add_f32 v[104:105], v[100:101], v[60:61] neg_lo:[0,1] neg_hi:[0,1]
	v_fma_f32 v60, -v85, v91, 1.0
	v_pk_add_f32 v[122:123], v[118:119], v[126:127]
	v_pk_add_f32 v[18:19], v[34:35], v[18:19] neg_lo:[0,1] neg_hi:[0,1]
	v_and_b32_e32 v127, 0xffff0000, v43
	v_and_b32_e32 v126, 0xffff0000, v42
	v_and_b32_e32 v43, 0xffff0000, v47
	v_and_b32_e32 v42, 0xffff0000, v46
	v_pk_fma_f32 v[134:135], v[84:85], v[6:7], v[10:11] op_sel_hi:[0,1,1] neg_lo:[0,0,1] neg_hi:[0,0,1]
	v_pk_add_f32 v[6:7], v[6:7], v[30:31]
	v_fmac_f32_e32 v91, v60, v91
	v_div_scale_f32 v60, vcc, 1.0, v67, 1.0
	v_pk_add_f32 v[128:129], v[126:127], v[42:43] neg_lo:[0,1] neg_hi:[0,1]
	v_and_b32_e32 v51, 0xffff0000, v51
	v_and_b32_e32 v50, 0xffff0000, v50
	v_and_b32_e32 v39, 0xffff0000, v39
	v_and_b32_e32 v38, 0xffff0000, v38
	v_pk_fma_f32 v[46:47], v[86:87], v[78:79], v[112:113] op_sel_hi:[0,1,1] neg_lo:[0,0,1] neg_hi:[0,0,1]
	v_pk_fma_f32 v[112:113], v[86:87], v[6:7], v[22:23] op_sel_hi:[0,1,1] neg_lo:[0,0,1] neg_hi:[0,0,1]
	v_pk_add_f32 v[6:7], v[6:7], v[18:19]
	v_mul_f32_e32 v61, v60, v91
	v_pk_add_f32 v[130:131], v[50:51], v[38:39] neg_lo:[0,1] neg_hi:[0,1]
	v_pk_fma_f32 v[132:133], v[84:85], v[76:77], v[14:15] op_sel_hi:[0,1,1] neg_lo:[0,0,1] neg_hi:[0,0,1]
	v_pk_fma_f32 v[42:43], v[88:89], v[6:7], v[34:35] op_sel_hi:[0,1,1] neg_lo:[0,0,1] neg_hi:[0,0,1]
	v_pk_add_f32 v[6:7], v[6:7], v[128:129]
	v_lshlrev_b32_e32 v11, 16, v59
	v_lshlrev_b32_e32 v10, 16, v58
	v_lshlrev_b32_e32 v15, 16, v63
	v_lshlrev_b32_e32 v14, 16, v62
	v_fma_f32 v64, -v85, v61, v60
	v_pk_fma_f32 v[34:35], v[90:91], v[6:7], v[126:127] op_sel_hi:[0,1,1] neg_lo:[0,0,1] neg_hi:[0,0,1]
	v_pk_add_f32 v[6:7], v[6:7], v[130:131]
	v_pk_add_f32 v[14:15], v[10:11], v[14:15] neg_lo:[0,1] neg_hi:[0,1]
	v_fmac_f32_e32 v61, v64, v91
	v_lshlrev_b32_e32 v65, 16, v3
	v_lshlrev_b32_e32 v64, 16, v2
	v_pk_fma_f32 v[26:27], v[92:93], v[6:7], v[50:51] op_sel_hi:[0,1,1] neg_lo:[0,0,1] neg_hi:[0,0,1]
	v_and_b32_e32 v23, 0xffff0000, v59
	v_and_b32_e32 v22, 0xffff0000, v58
	v_and_b32_e32 v51, 0xffff0000, v63
	v_and_b32_e32 v50, 0xffff0000, v62
	v_pk_add_f32 v[58:59], v[122:123], v[14:15]
	v_and_b32_e32 v3, 0xffff0000, v3
	v_and_b32_e32 v2, 0xffff0000, v2
	v_pk_add_f32 v[50:51], v[22:23], v[50:51] neg_lo:[0,1] neg_hi:[0,1]
	v_pk_fma_f32 v[14:15], v[94:95], v[58:59], v[10:11] op_sel_hi:[0,1,1] neg_lo:[0,0,1] neg_hi:[0,0,1]
	v_pk_add_f32 v[10:11], v[64:65], v[108:109] neg_lo:[0,1] neg_hi:[0,1]
	v_pk_add_f32 v[6:7], v[6:7], v[50:51]
	v_pk_add_f32 v[76:77], v[58:59], v[10:11]
	v_pk_add_f32 v[10:11], v[2:3], v[110:111] neg_lo:[0,1] neg_hi:[0,1]
	v_pk_fma_f32 v[22:23], v[94:95], v[6:7], v[22:23] op_sel_hi:[0,1,1] neg_lo:[0,0,1] neg_hi:[0,0,1]
	v_pk_add_f32 v[78:79], v[6:7], v[10:11]
	v_lshlrev_b32_e32 v7, 16, v57
	v_lshlrev_b32_e32 v6, 16, v56
	v_and_b32_e32 v11, 0xffff0000, v57
	v_and_b32_e32 v10, 0xffff0000, v56
	v_lshlrev_b32_e32 v51, 16, v17
	v_lshlrev_b32_e32 v50, 16, v16
	v_and_b32_e32 v17, 0xffff0000, v17
	v_and_b32_e32 v16, 0xffff0000, v16
	v_lshlrev_b32_e32 v57, 16, v29
	v_lshlrev_b32_e32 v56, 16, v28
	v_and_b32_e32 v29, 0xffff0000, v29
	v_and_b32_e32 v28, 0xffff0000, v28
	v_pk_add_f32 v[56:57], v[50:51], v[56:57] neg_lo:[0,1] neg_hi:[0,1]
	v_pk_add_f32 v[28:29], v[16:17], v[28:29] neg_lo:[0,1] neg_hi:[0,1]
	v_lshlrev_b32_e32 v59, 16, v13
	v_lshlrev_b32_e32 v58, 16, v12
	v_lshlrev_b32_e32 v63, 16, v9
	v_lshlrev_b32_e32 v62, 16, v8
	v_and_b32_e32 v13, 0xffff0000, v13
	v_and_b32_e32 v12, 0xffff0000, v12
	v_and_b32_e32 v9, 0xffff0000, v9
	v_and_b32_e32 v8, 0xffff0000, v8
	v_pk_add_f32 v[56:57], v[80:81], v[56:57]
	v_pk_add_f32 v[28:29], v[82:83], v[28:29]
	v_lshlrev_b32_e32 v81, 16, v25
	v_lshlrev_b32_e32 v80, 16, v24
	v_lshlrev_b32_e32 v83, 16, v33
	v_lshlrev_b32_e32 v82, 16, v32
	v_pk_add_f32 v[8:9], v[12:13], v[8:9] neg_lo:[0,1] neg_hi:[0,1]
	v_and_b32_e32 v25, 0xffff0000, v25
	v_and_b32_e32 v24, 0xffff0000, v24
	v_and_b32_e32 v33, 0xffff0000, v33
	v_and_b32_e32 v32, 0xffff0000, v32
	v_pk_fma_f32 v[50:51], v[98:99], v[56:57], v[50:51] op_sel_hi:[0,1,1] neg_lo:[0,0,1] neg_hi:[0,0,1]
	v_pk_fma_f32 v[16:17], v[98:99], v[28:29], v[16:17] op_sel_hi:[0,1,1] neg_lo:[0,0,1] neg_hi:[0,0,1]
	v_lshlrev_b32_e32 v99, 16, v37
	v_lshlrev_b32_e32 v98, 16, v36
	v_lshlrev_b32_e32 v109, 16, v21
	v_lshlrev_b32_e32 v108, 16, v20
	v_pk_add_f32 v[32:33], v[24:25], v[32:33] neg_lo:[0,1] neg_hi:[0,1]
	v_and_b32_e32 v37, 0xffff0000, v37
	v_and_b32_e32 v36, 0xffff0000, v36
	v_and_b32_e32 v21, 0xffff0000, v21
	v_and_b32_e32 v20, 0xffff0000, v20
	v_pk_add_f32 v[8:9], v[28:29], v[8:9]
	v_pk_fma_f32 v[38:39], v[88:89], v[114:115], v[116:117] op_sel_hi:[0,1,1] neg_lo:[0,0,1] neg_hi:[0,0,1]
	v_lshlrev_b32_e32 v111, 16, v45
	v_lshlrev_b32_e32 v110, 16, v44
	v_lshlrev_b32_e32 v115, 16, v49
	v_lshlrev_b32_e32 v114, 16, v48
	v_pk_add_f32 v[20:21], v[36:37], v[20:21] neg_lo:[0,1] neg_hi:[0,1]
	v_and_b32_e32 v45, 0xffff0000, v45
	v_and_b32_e32 v44, 0xffff0000, v44
	v_and_b32_e32 v49, 0xffff0000, v49
	v_and_b32_e32 v48, 0xffff0000, v48
	v_pk_fma_f32 v[12:13], v[84:85], v[8:9], v[12:13] op_sel_hi:[0,1,1] neg_lo:[0,0,1] neg_hi:[0,0,1]
	v_pk_add_f32 v[8:9], v[8:9], v[32:33]
; __device__ __forceinline__ unsigned pk2(float lo, float hi) { return f2bf(lo) | (f2bf(hi) << 16); }
; __device__ __forceinline__ void unpack8(const v4u& w, float (&f)[8]) { f[0] = bflo(w.x); f[1] = bfhi(w.x); f[2] = bflo(w.y); f[3] = bfhi(w.y); f[4] = bflo(w.z); f[5] = bfhi(w.z); f[6] = bflo(w.w); f[7] = bfhi(w.w); }
; __device__ __forceinline__ void pool_phase(const bf16* H, bf16* MX, int tid, int vcu, int G) {
;     ...
;             for (int u = 0; u < 8; ++u) { const int r = r0 + u, t = t0 + r; const int cnt = (t + 1 < win) ? t + 1 : win;
;                 float cur[8], old[8], y[8]; unpack8(cw[u], cur); unpack8(ow[u], old);
;                 const float inv = 1.0f / (float)cnt;
; #pragma unroll
;                 for (int e = 0; e < 8; ++e) { sum[e] += cur[e] - old[e]; y[e] = sum[e] * inv - cur[e]; }
;                 v4u w; w.x = pk2(y[0], y[1]); w.y = pk2(y[2], y[3]); w.z = pk2(y[4], y[5]); w.w = pk2(y[6], y[7]);
;                 *(v4u*)(MX + (size_t)(m0 + r) * D + col) = w; }
	v_fma_f32 v60, -v85, v61, v60
	v_pk_add_f32 v[62:63], v[58:59], v[62:63] neg_lo:[0,1] neg_hi:[0,1]
	v_pk_add_f32 v[48:49], v[44:45], v[48:49] neg_lo:[0,1] neg_hi:[0,1]
	v_pk_fma_f32 v[24:25], v[86:87], v[8:9], v[24:25] op_sel_hi:[0,1,1] neg_lo:[0,0,1] neg_hi:[0,0,1]
	v_pk_add_f32 v[8:9], v[8:9], v[20:21]
	v_div_fmas_f32 v60, v60, v91, v61
	v_pk_add_f32 v[56:57], v[56:57], v[62:63]
	v_pk_fma_f32 v[36:37], v[88:89], v[8:9], v[36:37] op_sel_hi:[0,1,1] neg_lo:[0,0,1] neg_hi:[0,0,1]
	v_pk_add_f32 v[8:9], v[8:9], v[48:49]
	v_bfe_u32 v49, v106, 16, 1
	v_div_fixup_f32 v60, v60, v67, 1.0
	v_pk_fma_f32 v[28:29], v[84:85], v[56:57], v[58:59] op_sel_hi:[0,1,1] neg_lo:[0,0,1] neg_hi:[0,0,1]
	v_pk_fma_f32 v[58:59], v[90:91], v[8:9], v[44:45] op_sel_hi:[0,1,1] neg_lo:[0,0,1] neg_hi:[0,0,1]
	v_bfe_u32 v44, v17, 16, 1
	v_bfe_u32 v45, v16, 16, 1
	v_add3_u32 v61, v106, v49, s26
	v_bfe_u32 v49, v50, 16, 1
	v_bfe_u32 v67, v51, 16, 1
	v_add3_u32 v16, v16, v45, s26
	v_add3_u32 v17, v17, v44, s26
	v_bfe_u32 v44, v54, 16, 1
	v_add3_u32 v51, v51, v67, s26
	v_add3_u32 v49, v50, v49, s26
	v_add3_u32 v44, v54, v44, s26
	v_lshrrev_b32_e32 v49, 16, v49
	v_lshrrev_b32_e32 v50, 16, v51
	v_lshrrev_b32_e32 v44, 16, v44
	v_and_or_b32 v51, v17, s25, v50
	v_and_or_b32 v50, v16, s25, v49
	v_add_co_u32_e32 v16, vcc, s24, v74
	v_cvt_pk_bf16_f32 v49, v55, v107
	v_and_or_b32 v48, v61, s25, v44
	v_addc_co_u32_e32 v17, vcc, -1, v75, vcc
	global_store_dwordx4 v[16:17], v[48:51], off offset:-4096
	v_bfe_u32 v44, v13, 16, 1
	v_bfe_u32 v45, v12, 16, 1
	v_bfe_u32 v49, v134, 16, 1
	v_add3_u32 v54, v134, v49, s26
	v_bfe_u32 v49, v28, 16, 1
	v_bfe_u32 v50, v29, 16, 1
	v_pk_add_f32 v[82:83], v[80:81], v[82:83] neg_lo:[0,1] neg_hi:[0,1]
	v_add3_u32 v12, v12, v45, s26
	v_add3_u32 v13, v13, v44, s26
	v_bfe_u32 v44, v132, 16, 1
	v_add3_u32 v29, v29, v50, s26
	v_add3_u32 v28, v28, v49, s26
	v_pk_add_f32 v[62:63], v[56:57], v[82:83]
	v_add3_u32 v44, v132, v44, s26
	v_lshrrev_b32_e32 v28, 16, v28
	v_lshrrev_b32_e32 v29, 16, v29
	v_pk_add_f32 v[108:109], v[98:99], v[108:109] neg_lo:[0,1] neg_hi:[0,1]
	v_pk_fma_f32 v[32:33], v[86:87], v[62:63], v[80:81] op_sel_hi:[0,1,1] neg_lo:[0,0,1] neg_hi:[0,0,1]
	v_lshrrev_b32_e32 v44, 16, v44
	v_and_or_b32 v51, v13, s25, v29
	v_and_or_b32 v50, v12, s25, v28
	v_bfe_u32 v12, v25, 16, 1
	v_bfe_u32 v13, v24, 16, 1
	v_pk_add_f32 v[82:83], v[62:63], v[108:109]
	v_cvt_pk_bf16_f32 v49, v133, v135
	v_and_or_b32 v48, v54, s25, v44
	v_add3_u32 v13, v24, v13, s26
	v_add3_u32 v12, v25, v12, s26
	v_bfe_u32 v24, v46, 16, 1
	v_bfe_u32 v25, v47, 16, 1
	v_bfe_u32 v28, v32, 16, 1
	v_bfe_u32 v29, v33, 16, 1
	v_pk_fma_f32 v[20:21], v[88:89], v[82:83], v[98:99] op_sel_hi:[0,1,1] neg_lo:[0,0,1] neg_hi:[0,0,1]
	global_store_dwordx4 v[16:17], v[48:51], off
	v_bfe_u32 v16, v113, 16, 1
	v_bfe_u32 v17, v112, 16, 1
	v_add3_u32 v29, v33, v29, s26
	v_add3_u32 v28, v32, v28, s26
	v_add3_u32 v25, v47, v25, s26
	v_add3_u32 v24, v46, v24, s26
	v_add3_u32 v17, v112, v17, s26
	v_add3_u32 v16, v113, v16, s26
	v_lshrrev_b32_e32 v24, 16, v24
	v_lshrrev_b32_e32 v25, 16, v25
	v_lshrrev_b32_e32 v28, 16, v28
	v_lshrrev_b32_e32 v29, 16, v29
	v_bfe_u32 v32, v20, 16, 1
	v_bfe_u32 v33, v21, 16, 1
	v_pk_add_f32 v[114:115], v[110:111], v[114:115] neg_lo:[0,1] neg_hi:[0,1]
	v_and_or_b32 v47, v12, s25, v29
	v_and_or_b32 v46, v13, s25, v28
	v_and_or_b32 v45, v16, s25, v25
	v_and_or_b32 v44, v17, s25, v24
	v_bfe_u32 v16, v37, 16, 1
	v_bfe_u32 v17, v36, 16, 1
	v_bfe_u32 v28, v38, 16, 1
	v_bfe_u32 v29, v39, 16, 1
	v_add3_u32 v21, v21, v33, s26
	v_add3_u32 v20, v20, v32, s26
	v_pk_fma_f32 v[30:31], v[90:91], v[118:119], v[120:121] op_sel_hi:[0,1,1] neg_lo:[0,0,1] neg_hi:[0,0,1]
	v_pk_add_f32 v[108:109], v[82:83], v[114:115]
	v_bfe_u32 v24, v43, 16, 1
	v_bfe_u32 v25, v42, 16, 1
	v_add3_u32 v17, v36, v17, s26
	v_add3_u32 v16, v37, v16, s26
	v_add3_u32 v29, v39, v29, s26
	v_add3_u32 v28, v38, v28, s26
	v_lshrrev_b32_e32 v20, 16, v20
	v_lshrrev_b32_e32 v21, 16, v21
	v_lshlrev_b32_e32 v117, 16, v53
	v_lshlrev_b32_e32 v116, 16, v52
	v_lshlrev_b32_e32 v119, 16, v41
	v_lshlrev_b32_e32 v118, 16, v40
	v_pk_fma_f32 v[56:57], v[90:91], v[108:109], v[110:111] op_sel_hi:[0,1,1] neg_lo:[0,0,1] neg_hi:[0,0,1]
	v_add_co_u32_e32 v12, vcc, s23, v74
	v_add3_u32 v25, v42, v25, s26
	v_add3_u32 v24, v43, v24, s26
	v_lshrrev_b32_e32 v28, 16, v28
	v_lshrrev_b32_e32 v29, 16, v29
	v_and_or_b32 v39, v16, s25, v21
	v_and_or_b32 v38, v17, s25, v20
	v_pk_add_f32 v[118:119], v[116:117], v[118:119] neg_lo:[0,1] neg_hi:[0,1]
; __device__ __forceinline__ unsigned pk2(float lo, float hi) { return f2bf(lo) | (f2bf(hi) << 16); }
; __device__ __forceinline__ void unpack8(const v4u& w, float (&f)[8]) { f[0] = bflo(w.x); f[1] = bfhi(w.x); f[2] = bflo(w.y); f[3] = bfhi(w.y); f[4] = bflo(w.z); f[5] = bfhi(w.z); f[6] = bflo(w.w); f[7] = bfhi(w.w); }
; __device__ __forceinline__ void pool_phase(const bf16* H, bf16* MX, int tid, int vcu, int G) {
;     ...
;         for (int r0 = 0; r0 < 32; r0 += 8) {
;     ...
;             for (int u = 0; u < 8; ++u) { const int r = r0 + u, t = t0 + r; const int cnt = (t + 1 < win) ? t + 1 : win;
;                 float cur[8], old[8], y[8]; unpack8(cw[u], cur); unpack8(ow[u], old);
;                 const float inv = 1.0f / (float)cnt;
; #pragma unroll
;                 for (int e = 0; e < 8; ++e) { sum[e] += cur[e] - old[e]; y[e] = sum[e] * inv - cur[e]; }
;                 v4u w; w.x = pk2(y[0], y[1]); w.y = pk2(y[2], y[3]); w.z = pk2(y[4], y[5]); w.w = pk2(y[6], y[7]);
;                 *(v4u*)(MX + (size_t)(m0 + r) * D + col) = w; }
	v_and_b32_e32 v53, 0xffff0000, v53
	v_and_b32_e32 v52, 0xffff0000, v52
	v_and_b32_e32 v41, 0xffff0000, v41
	v_and_b32_e32 v40, 0xffff0000, v40
	v_addc_co_u32_e32 v13, vcc, -1, v75, vcc
	v_and_or_b32 v37, v24, s25, v29
	v_and_or_b32 v36, v25, s25, v28
	v_pk_add_f32 v[114:115], v[108:109], v[118:119]
	v_pk_add_f32 v[40:41], v[52:53], v[40:41] neg_lo:[0,1] neg_hi:[0,1]
	global_store_dwordx4 v[12:13], v[44:47], off offset:-4096
	global_store_dwordx4 v[12:13], v[36:39], off
	v_pk_fma_f32 v[18:19], v[92:93], v[122:123], v[124:125] op_sel_hi:[0,1,1] neg_lo:[0,0,1] neg_hi:[0,0,1]
	v_pk_add_f32 v[8:9], v[8:9], v[40:41]
	v_pk_fma_f32 v[40:41], v[92:93], v[114:115], v[116:117] op_sel_hi:[0,1,1] neg_lo:[0,0,1] neg_hi:[0,0,1]
	v_cvt_pk_bf16_f32 v29, v31, v35
	v_cvt_pk_bf16_f32 v28, v30, v34
	v_bfe_u32 v20, v27, 16, 1
	v_bfe_u32 v21, v26, 16, 1
	v_pk_fma_f32 v[52:53], v[92:93], v[8:9], v[52:53] op_sel_hi:[0,1,1] neg_lo:[0,0,1] neg_hi:[0,0,1]
	v_cvt_pk_bf16_f32 v31, v57, v59
	v_cvt_pk_bf16_f32 v30, v56, v58
	v_add3_u32 v21, v26, v21, s26
	v_add3_u32 v20, v27, v20, s26
	v_bfe_u32 v24, v18, 16, 1
	v_bfe_u32 v25, v19, 16, 1
	v_bfe_u32 v26, v40, 16, 1
	v_bfe_u32 v27, v41, 16, 1
	v_bfe_u32 v16, v53, 16, 1
	v_bfe_u32 v17, v52, 16, 1
	v_add3_u32 v27, v41, v27, s26
	v_add3_u32 v26, v40, v26, s26
	v_add3_u32 v19, v19, v25, s26
	v_add3_u32 v18, v18, v24, s26
	v_pk_add_f32 v[62:63], v[114:115], v[102:103]
	v_add_co_u32_e32 v12, vcc, s22, v74
	v_add3_u32 v17, v52, v17, s26
	v_add3_u32 v16, v53, v16, s26
	v_lshrrev_b32_e32 v24, 16, v18
	v_lshrrev_b32_e32 v25, 16, v19
	v_lshrrev_b32_e32 v18, 16, v26
	v_lshrrev_b32_e32 v19, 16, v27
	v_pk_add_f32 v[8:9], v[8:9], v[104:105]
	v_pk_fma_f32 v[80:81], v[94:95], v[62:63], v[96:97] op_sel_hi:[0,1,1] neg_lo:[0,0,1] neg_hi:[0,0,1]
	v_addc_co_u32_e32 v13, vcc, -1, v75, vcc
	v_and_or_b32 v19, v16, s25, v19
	v_and_or_b32 v18, v17, s25, v18
	v_and_or_b32 v17, v20, s25, v25
	v_and_or_b32 v16, v21, s25, v24
	v_pk_fma_f32 v[82:83], v[94:95], v[8:9], v[100:101] op_sel_hi:[0,1,1] neg_lo:[0,0,1] neg_hi:[0,0,1]
	global_store_dwordx4 v[12:13], v[16:19], off
	v_bfe_u32 v20, v80, 16, 1
	v_bfe_u32 v21, v81, 16, 1
	v_bfe_u32 v18, v14, 16, 1
	v_bfe_u32 v19, v15, 16, 1
	global_store_dwordx4 v[12:13], v[28:31], off offset:-4096
	v_bfe_u32 v12, v83, 16, 1
	v_bfe_u32 v13, v82, 16, 1
	v_bfe_u32 v16, v23, 16, 1
	v_bfe_u32 v17, v22, 16, 1
	v_add3_u32 v21, v81, v21, s26
	v_add3_u32 v20, v80, v20, s26
	v_add3_u32 v15, v15, v19, s26
	v_add3_u32 v14, v14, v18, s26
	v_add3_u32 v17, v22, v17, s26
	v_add3_u32 v16, v23, v16, s26
	v_add3_u32 v13, v82, v13, s26
	v_add3_u32 v12, v83, v12, s26
	v_lshrrev_b32_e32 v18, 16, v14
	v_lshrrev_b32_e32 v19, 16, v15
	v_lshrrev_b32_e32 v14, 16, v20
	v_lshrrev_b32_e32 v15, 16, v21
	v_and_or_b32 v15, v12, s25, v15
	v_and_or_b32 v14, v13, s25, v14
	v_and_or_b32 v13, v16, s25, v19
	v_and_or_b32 v12, v17, s25, v18
	global_store_dwordx4 v[74:75], v[12:15], off offset:-4096
	v_pk_fma_f32 v[2:3], v[60:61], v[78:79], v[2:3] op_sel_hi:[0,1,1] neg_lo:[0,0,1] neg_hi:[0,0,1]
	s_add_i32 s20, s20, 8
	v_lshlrev_b32_e32 v15, 16, v5
	v_lshlrev_b32_e32 v14, 16, v4
	v_and_b32_e32 v5, 0xffff0000, v5
	v_and_b32_e32 v4, 0xffff0000, v4
	v_pk_add_f32 v[6:7], v[14:15], v[6:7] neg_lo:[0,1] neg_hi:[0,1]
	v_pk_fma_f32 v[12:13], v[60:61], v[76:77], v[64:65] op_sel_hi:[0,1,1] neg_lo:[0,0,1] neg_hi:[0,0,1]
	v_pk_add_f32 v[80:81], v[62:63], v[6:7]
	v_pk_add_f32 v[6:7], v[4:5], v[10:11] neg_lo:[0,1] neg_hi:[0,1]
	v_bfe_u32 v10, v3, 16, 1
	v_pk_add_f32 v[82:83], v[8:9], v[6:7]
	v_pk_fma_f32 v[6:7], v[60:61], v[80:81], v[14:15] op_sel_hi:[0,1,1] neg_lo:[0,0,1] neg_hi:[0,0,1]
	v_pk_fma_f32 v[4:5], v[60:61], v[82:83], v[4:5] op_sel_hi:[0,1,1] neg_lo:[0,0,1] neg_hi:[0,0,1]
	v_bfe_u32 v8, v5, 16, 1
	v_bfe_u32 v9, v4, 16, 1
	v_bfe_u32 v11, v2, 16, 1
	v_add3_u32 v2, v2, v11, s26
	v_add3_u32 v3, v3, v10, s26
	v_add3_u32 v4, v4, v9, s26
	v_add3_u32 v5, v5, v8, s26
	v_bfe_u32 v8, v12, 16, 1
	v_bfe_u32 v9, v13, 16, 1
	v_bfe_u32 v10, v6, 16, 1
	v_bfe_u32 v11, v7, 16, 1
	v_add3_u32 v7, v7, v11, s26
	v_add3_u32 v6, v6, v10, s26
	v_add3_u32 v9, v13, v9, s26
	v_add3_u32 v8, v12, v8, s26
	v_lshrrev_b32_e32 v8, 16, v8
	v_lshrrev_b32_e32 v9, 16, v9
	v_lshrrev_b32_e32 v6, 16, v6
	v_lshrrev_b32_e32 v7, 16, v7
	v_and_or_b32 v5, v5, s25, v7
	v_and_or_b32 v4, v4, s25, v6
	v_and_or_b32 v3, v3, s25, v9
	v_and_or_b32 v2, v2, s25, v8
	global_store_dwordx4 v[74:75], v[2:5], off
	s_cmp_gt_u32 s20, 23
	v_lshl_add_u64 v[74:75], v[74:75], 0, s[16:17]
	s_cbranch_scc1 .LBB0_2536
